# v_stg_zero64 + all s_setprio flips removed from the 8 GEMM K-loops (probe showed 6a K-loop 1-5 pct faster without them)
# speedup vs baseline: 1.0130x; 1.0096x over previous
; #define PG8_STAGE(bufoff, gbase, voff) do { _Pragma("unroll") for (int _i = 0; _i < 2; ++_i) \
;         __builtin_amdgcn_global_load_lds((const unsigned*)((const char*)(gbase) + (voff)[_i]), (LAS unsigned*)(lds + (bufoff) + ldsw + _i * 8192), 16, 0, 0); } while (0)
; #define PG8_LDA(dst, b, h) do { _Pragma("unroll") for (int m = 0; m < 4; ++m) _Pragma("unroll") for (int k = 0; k < 2; ++k) dst[m][k] = *(const LAS bf16x8*)(lds + PG8_SA(b, h) + aoff + m * 2048 + k * 1024); } while (0)
; #define PG8_LDB(dst, b, h) do { _Pragma("unroll") for (int n = 0; n < 2; ++n) _Pragma("unroll") for (int k = 0; k < 2; ++k) dst[n][k] = *(const LAS bf16x8*)(lds + PG8_SB(b, h) + boff + n * 2048 + k * 1024); } while (0)
; #define PG8_MMA(ai, bj, At, Bt) do { __builtin_amdgcn_s_setprio(1); _Pragma("unroll") for (int m = 0; m < 4; ++m) _Pragma("unroll") for (int n = 0; n < 2; ++n) _Pragma("unroll") for (int k = 0; k < 2; ++k) \
;         acc[ai][bj][m][n] = __builtin_amdgcn_mfma_f32_16x16x32_bf16(Bt[n][k], At[m][k], acc[ai][bj][m][n], 0, 0, 0); __builtin_amdgcn_s_setprio(0); } while (0)
; #define PG8_WAIT_V(n) asm volatile("s_waitcnt vmcnt(" #n ")" ::: "memory")
; #define PG8_WAIT_L(n) asm volatile("s_waitcnt lgkmcnt(" #n ")" ::: "memory")
; #define PG8_BAR __builtin_amdgcn_s_barrier()
; #define PG8_SCHED __builtin_amdgcn_sched_barrier(0)
; template <class Epi, class Sched, bool ALIGN_EPI = true>
; __device__ __forceinline__ void gemm_phase(LAS unsigned char* lds, const Gemm g, const Sched& S, const Epi& E) {
;     ...
;         for (int t = 0; t < nt; t += 2) {
;             const bool last = (t == nt - 2);
;             const char* a1 = cA + (size_t)(t + 1) * kstep;
;             const char* a2 = last ? nA : cA + (size_t)(t + 2) * kstep; const char* b2 = last ? nB : cB + (size_t)(t + 2) * kstep;
;             const char* a3 = a2 + kstep; const char* b3 = b2 + kstep;
;             PG8_LDB(B0, 0, 0); PG8_LDB(B1, 0, 1); PG8_SCHED; PG8_LDA(At, 0, 0); PG8_STAGE(PG8_SA(1, 1), a1 + hstep, voffA);
;             PG8_WAIT_V(8); PG8_WAIT_L(0); PG8_BAR; PG8_MMA(0, 0, At, B0); PG8_MMA(0, 1, At, B1); PG8_BAR; PG8_SCHED;
;             PG8_LDA(At, 0, 1); PG8_STAGE(PG8_SB(0, 0), b2, voffB); PG8_STAGE(PG8_SB(0, 1), b2 + hstep, voffB); PG8_STAGE(PG8_SA(0, 0), a2, voffA);
.LBB0_195:
	v_add_u32_e32 v136, s78, v169
	ds_read_b128 v[172:175], v136
	ds_read_b128 v[180:183], v136 offset:1024
	ds_read_b128 v[184:187], v136 offset:2048
	ds_read_b128 v[188:191], v136 offset:3072
	v_add_u32_e32 v136, s79, v169
	ds_read_b128 v[192:195], v136
	ds_read_b128 v[196:199], v136 offset:1024
	ds_read_b128 v[204:207], v136 offset:2048
	ds_read_b128 v[208:211], v136 offset:3072
	s_add_u32 s36, s34, 0xfff80080
	s_addc_u32 s37, s35, -1
	s_cmp_eq_u32 s89, 28
	s_cselect_b32 s39, s84, s37
	s_cselect_b32 s38, s85, s36
	s_cselect_b32 s37, s9, s88
	s_cselect_b32 s36, s86, s87
	v_lshl_add_u64 v[164:165], s[34:35], 0, v[160:161]
	s_add_i32 m0, s44, 0xc000
	ds_read_b128 v[212:215], v171
	ds_read_b128 v[216:219], v171 offset:1024
	ds_read_b128 v[220:223], v171 offset:2048
	ds_read_b128 v[224:227], v171 offset:3072
	ds_read_b128 v[228:231], v171 offset:4096
	ds_read_b128 v[232:235], v171 offset:5120
	ds_read_b128 v[236:239], v171 offset:6144
	ds_read_b128 v[240:243], v171 offset:7168
	global_load_lds_dwordx4 v[164:165], off
	v_lshl_add_u64 v[164:165], s[34:35], 0, v[162:163]
	s_add_i32 m0, s44, 0xe000
	s_nop 0
	global_load_lds_dwordx4 v[164:165], off
	s_waitcnt vmcnt(8)
	s_waitcnt lgkmcnt(0)
	s_barrier
	s_waitcnt lgkmcnt(0)
	v_mfma_f32_16x16x32_bf16 v[124:127], v[172:175], v[212:215], v[124:127]
	v_mfma_f32_16x16x32_bf16 v[120:123], v[184:187], v[212:215], v[120:123]
	v_mfma_f32_16x16x32_bf16 v[108:111], v[172:175], v[220:223], v[108:111]
	v_mfma_f32_16x16x32_bf16 v[104:107], v[184:187], v[220:223], v[104:107]
	v_mfma_f32_16x16x32_bf16 v[92:95], v[172:175], v[228:231], v[92:95]
	v_mfma_f32_16x16x32_bf16 v[88:91], v[184:187], v[228:231], v[88:91]
	v_mfma_f32_16x16x32_bf16 v[76:79], v[172:175], v[236:239], v[76:79]
	v_mfma_f32_16x16x32_bf16 v[72:75], v[184:187], v[236:239], v[72:75]
	v_mfma_f32_16x16x32_bf16 v[124:127], v[180:183], v[216:219], v[124:127]
	v_mfma_f32_16x16x32_bf16 v[120:123], v[188:191], v[216:219], v[120:123]
	v_mfma_f32_16x16x32_bf16 v[108:111], v[180:183], v[224:227], v[108:111]
	v_mfma_f32_16x16x32_bf16 v[104:107], v[188:191], v[224:227], v[104:107]
	v_mfma_f32_16x16x32_bf16 v[92:95], v[180:183], v[232:235], v[92:95]
	v_mfma_f32_16x16x32_bf16 v[88:91], v[188:191], v[232:235], v[88:91]
	v_mfma_f32_16x16x32_bf16 v[76:79], v[180:183], v[240:243], v[76:79]
	v_mfma_f32_16x16x32_bf16 v[72:75], v[188:191], v[240:243], v[72:75]
	v_mfma_f32_16x16x32_bf16 v[116:119], v[192:195], v[212:215], v[116:119]
	v_mfma_f32_16x16x32_bf16 v[112:115], v[204:207], v[212:215], v[112:115]
	v_mfma_f32_16x16x32_bf16 v[100:103], v[192:195], v[220:223], v[100:103]
	v_mfma_f32_16x16x32_bf16 v[96:99], v[204:207], v[220:223], v[96:99]
	v_mfma_f32_16x16x32_bf16 v[84:87], v[192:195], v[228:231], v[84:87]
	v_mfma_f32_16x16x32_bf16 v[80:83], v[204:207], v[228:231], v[80:83]
	v_mfma_f32_16x16x32_bf16 v[68:71], v[192:195], v[236:239], v[68:71]
	v_mfma_f32_16x16x32_bf16 v[64:67], v[204:207], v[236:239], v[64:67]
	v_mfma_f32_16x16x32_bf16 v[116:119], v[196:199], v[216:219], v[116:119]
	v_mfma_f32_16x16x32_bf16 v[112:115], v[208:211], v[216:219], v[112:115]
	v_mfma_f32_16x16x32_bf16 v[100:103], v[196:199], v[224:227], v[100:103]
	v_mfma_f32_16x16x32_bf16 v[96:99], v[208:211], v[224:227], v[96:99]
	v_mfma_f32_16x16x32_bf16 v[84:87], v[196:199], v[232:235], v[84:87]
	v_mfma_f32_16x16x32_bf16 v[80:83], v[208:211], v[232:235], v[80:83]
	v_mfma_f32_16x16x32_bf16 v[68:71], v[196:199], v[240:243], v[68:71]
	v_mfma_f32_16x16x32_bf16 v[64:67], v[208:211], v[240:243], v[64:67]
	s_barrier
	s_add_i32 s46, s78, s42
	v_lshl_add_u64 v[164:165], s[36:37], 0, v[130:131]
	s_mov_b32 m0, s46
	ds_read_b128 v[212:215], v171 offset:16384
	ds_read_b128 v[216:219], v171 offset:17408
	ds_read_b128 v[220:223], v171 offset:18432
	ds_read_b128 v[224:227], v171 offset:19456
	ds_read_b128 v[228:231], v171 offset:20480
	ds_read_b128 v[232:235], v171 offset:21504
	ds_read_b128 v[236:239], v171 offset:22528
	ds_read_b128 v[240:243], v171 offset:23552
	global_load_lds_dwordx4 v[164:165], off
	s_add_i32 m0, s46, 0x2000
	s_add_u32 s90, s36, 0x80000
	v_lshl_add_u64 v[176:177], s[36:37], 0, v[134:135]
	s_addc_u32 s91, s37, 0
	s_add_i32 s46, s79, s42
	global_load_lds_dwordx4 v[176:177], off
	v_lshl_add_u64 v[200:201], s[90:91], 0, v[130:131]
	s_mov_b32 m0, s46
	v_lshl_add_u64 v[244:245], s[38:39], 0, v[132:133]
	global_load_lds_dwordx4 v[200:201], off
	v_lshl_add_u64 v[200:201], s[90:91], 0, v[134:135]
	s_add_i32 m0, s46, 0x2000
	s_nop 0
	global_load_lds_dwordx4 v[200:201], off
	v_lshl_add_u64 v[200:201], s[38:39], 0, v[128:129]
	s_mov_b32 m0, s44
	s_nop 0
	global_load_lds_dwordx4 v[200:201], off
	s_mov_b32 m0, s50
	s_nop 0
	global_load_lds_dwordx4 v[244:245], off
	s_waitcnt vmcnt(8)
	s_waitcnt lgkmcnt(0)
	s_barrier
; #define PG8_STAGE(bufoff, gbase, voff) do { _Pragma("unroll") for (int _i = 0; _i < 2; ++_i) \
;         __builtin_amdgcn_global_load_lds((const unsigned*)((const char*)(gbase) + (voff)[_i]), (LAS unsigned*)(lds + (bufoff) + ldsw + _i * 8192), 16, 0, 0); } while (0)
; #define PG8_LDA(dst, b, h) do { _Pragma("unroll") for (int m = 0; m < 4; ++m) _Pragma("unroll") for (int k = 0; k < 2; ++k) dst[m][k] = *(const LAS bf16x8*)(lds + PG8_SA(b, h) + aoff + m * 2048 + k * 1024); } while (0)
; #define PG8_LDB(dst, b, h) do { _Pragma("unroll") for (int n = 0; n < 2; ++n) _Pragma("unroll") for (int k = 0; k < 2; ++k) dst[n][k] = *(const LAS bf16x8*)(lds + PG8_SB(b, h) + boff + n * 2048 + k * 1024); } while (0)
; #define PG8_MMA(ai, bj, At, Bt) do { __builtin_amdgcn_s_setprio(1); _Pragma("unroll") for (int m = 0; m < 4; ++m) _Pragma("unroll") for (int n = 0; n < 2; ++n) _Pragma("unroll") for (int k = 0; k < 2; ++k) \
;         acc[ai][bj][m][n] = __builtin_amdgcn_mfma_f32_16x16x32_bf16(Bt[n][k], At[m][k], acc[ai][bj][m][n], 0, 0, 0); __builtin_amdgcn_s_setprio(0); } while (0)
; #define PG8_WAIT_V(n) asm volatile("s_waitcnt vmcnt(" #n ")" ::: "memory")
; #define PG8_WAIT_L(n) asm volatile("s_waitcnt lgkmcnt(" #n ")" ::: "memory")
; #define PG8_BAR __builtin_amdgcn_s_barrier()
; #define PG8_SCHED __builtin_amdgcn_sched_barrier(0)
; template <class Epi, class Sched, bool ALIGN_EPI = true>
; __device__ __forceinline__ void gemm_phase(LAS unsigned char* lds, const Gemm g, const Sched& S, const Epi& E) {
;     ...
;             PG8_WAIT_V(8); PG8_WAIT_L(0); PG8_BAR; PG8_MMA(1, 0, At, B0); PG8_MMA(1, 1, At, B1); PG8_BAR; PG8_SCHED;
;             PG8_LDB(B0, 1, 0); PG8_LDB(B1, 1, 1); PG8_SCHED; PG8_LDA(At, 1, 0); PG8_STAGE(PG8_SA(0, 1), a2 + hstep, voffA);
;             PG8_WAIT_V(8); PG8_WAIT_L(0); PG8_BAR; PG8_MMA(0, 0, At, B0); PG8_MMA(0, 1, At, B1); PG8_BAR; PG8_SCHED;
;             PG8_LDA(At, 1, 1); PG8_STAGE(PG8_SB(1, 0), b3, voffB); PG8_STAGE(PG8_SB(1, 1), b3 + hstep, voffB); PG8_STAGE(PG8_SA(1, 0), a3, voffA);
	s_waitcnt lgkmcnt(0)
	v_mfma_f32_16x16x32_bf16 v[60:63], v[172:175], v[212:215], v[60:63]
	v_mfma_f32_16x16x32_bf16 v[56:59], v[184:187], v[212:215], v[56:59]
	v_mfma_f32_16x16x32_bf16 v[44:47], v[172:175], v[220:223], v[44:47]
	v_mfma_f32_16x16x32_bf16 v[40:43], v[184:187], v[220:223], v[40:43]
	v_mfma_f32_16x16x32_bf16 v[28:31], v[172:175], v[228:231], v[28:31]
	v_mfma_f32_16x16x32_bf16 v[24:27], v[184:187], v[228:231], v[24:27]
	v_mfma_f32_16x16x32_bf16 v[12:15], v[172:175], v[236:239], v[12:15]
	v_mfma_f32_16x16x32_bf16 v[8:11], v[184:187], v[236:239], v[8:11]
	v_mfma_f32_16x16x32_bf16 v[60:63], v[180:183], v[216:219], v[60:63]
	v_mfma_f32_16x16x32_bf16 v[56:59], v[188:191], v[216:219], v[56:59]
	v_mfma_f32_16x16x32_bf16 v[44:47], v[180:183], v[224:227], v[44:47]
	v_mfma_f32_16x16x32_bf16 v[40:43], v[188:191], v[224:227], v[40:43]
	v_mfma_f32_16x16x32_bf16 v[28:31], v[180:183], v[232:235], v[28:31]
	v_mfma_f32_16x16x32_bf16 v[24:27], v[188:191], v[232:235], v[24:27]
	v_mfma_f32_16x16x32_bf16 v[12:15], v[180:183], v[240:243], v[12:15]
	v_mfma_f32_16x16x32_bf16 v[8:11], v[188:191], v[240:243], v[8:11]
	v_mfma_f32_16x16x32_bf16 v[52:55], v[192:195], v[212:215], v[52:55]
	v_mfma_f32_16x16x32_bf16 v[48:51], v[204:207], v[212:215], v[48:51]
	v_mfma_f32_16x16x32_bf16 v[36:39], v[192:195], v[220:223], v[36:39]
	v_mfma_f32_16x16x32_bf16 v[32:35], v[204:207], v[220:223], v[32:35]
	v_mfma_f32_16x16x32_bf16 v[20:23], v[192:195], v[228:231], v[20:23]
	v_mfma_f32_16x16x32_bf16 v[16:19], v[204:207], v[228:231], v[16:19]
	v_mfma_f32_16x16x32_bf16 v[4:7], v[192:195], v[236:239], v[4:7]
	v_mfma_f32_16x16x32_bf16 v[0:3], v[204:207], v[236:239], v[0:3]
	v_mfma_f32_16x16x32_bf16 v[52:55], v[196:199], v[216:219], v[52:55]
	v_mfma_f32_16x16x32_bf16 v[48:51], v[208:211], v[216:219], v[48:51]
	v_mfma_f32_16x16x32_bf16 v[36:39], v[196:199], v[224:227], v[36:39]
	v_mfma_f32_16x16x32_bf16 v[32:35], v[208:211], v[224:227], v[32:35]
	v_mfma_f32_16x16x32_bf16 v[20:23], v[196:199], v[232:235], v[20:23]
	v_mfma_f32_16x16x32_bf16 v[16:19], v[208:211], v[232:235], v[16:19]
	v_mfma_f32_16x16x32_bf16 v[4:7], v[196:199], v[240:243], v[4:7]
	v_mfma_f32_16x16x32_bf16 v[0:3], v[208:211], v[240:243], v[0:3]
	s_barrier
	s_add_i32 s46, 0, 0x18000
	v_add_u32_e32 v136, s46, v169
	s_add_i32 s47, 0, 0x1c000
	ds_read_b128 v[172:175], v136
	ds_read_b128 v[180:183], v136 offset:1024
	ds_read_b128 v[184:187], v136 offset:2048
	ds_read_b128 v[188:191], v136 offset:3072
	v_add_u32_e32 v136, s47, v169
	ds_read_b128 v[192:195], v136
	ds_read_b128 v[196:199], v136 offset:1024
	ds_read_b128 v[204:207], v136 offset:2048
	ds_read_b128 v[208:211], v136 offset:3072
	s_add_u32 s38, s38, 0x80000
	s_addc_u32 s39, s39, 0
	s_mov_b32 m0, s52
	v_lshl_add_u64 v[246:247], s[38:39], 0, v[128:129]
	ds_read_b128 v[212:215], v171 offset:32768
	ds_read_b128 v[216:219], v171 offset:33792
	ds_read_b128 v[220:223], v171 offset:34816
	ds_read_b128 v[224:227], v171 offset:35840
	ds_read_b128 v[228:231], v171 offset:36864
	ds_read_b128 v[232:235], v171 offset:37888
	ds_read_b128 v[236:239], v171 offset:38912
	ds_read_b128 v[240:243], v171 offset:39936
	global_load_lds_dwordx4 v[246:247], off
	v_lshl_add_u64 v[246:247], s[38:39], 0, v[132:133]
	s_mov_b32 m0, s53
	s_nop 0
	global_load_lds_dwordx4 v[246:247], off
	s_waitcnt vmcnt(8)
	s_waitcnt lgkmcnt(0)
	s_barrier
	s_waitcnt lgkmcnt(0)
	v_mfma_f32_16x16x32_bf16 v[124:127], v[172:175], v[212:215], v[124:127]
	v_mfma_f32_16x16x32_bf16 v[120:123], v[184:187], v[212:215], v[120:123]
	v_mfma_f32_16x16x32_bf16 v[108:111], v[172:175], v[220:223], v[108:111]
	v_mfma_f32_16x16x32_bf16 v[104:107], v[184:187], v[220:223], v[104:107]
	v_mfma_f32_16x16x32_bf16 v[92:95], v[172:175], v[228:231], v[92:95]
	v_mfma_f32_16x16x32_bf16 v[88:91], v[184:187], v[228:231], v[88:91]
	v_mfma_f32_16x16x32_bf16 v[76:79], v[172:175], v[236:239], v[76:79]
	v_mfma_f32_16x16x32_bf16 v[72:75], v[184:187], v[236:239], v[72:75]
	v_mfma_f32_16x16x32_bf16 v[124:127], v[180:183], v[216:219], v[124:127]
	v_mfma_f32_16x16x32_bf16 v[120:123], v[188:191], v[216:219], v[120:123]
	v_mfma_f32_16x16x32_bf16 v[108:111], v[180:183], v[224:227], v[108:111]
	v_mfma_f32_16x16x32_bf16 v[104:107], v[188:191], v[224:227], v[104:107]
	v_mfma_f32_16x16x32_bf16 v[92:95], v[180:183], v[232:235], v[92:95]
	v_mfma_f32_16x16x32_bf16 v[88:91], v[188:191], v[232:235], v[88:91]
	v_mfma_f32_16x16x32_bf16 v[76:79], v[180:183], v[240:243], v[76:79]
	v_mfma_f32_16x16x32_bf16 v[72:75], v[188:191], v[240:243], v[72:75]
	v_mfma_f32_16x16x32_bf16 v[116:119], v[192:195], v[212:215], v[116:119]
	v_mfma_f32_16x16x32_bf16 v[112:115], v[204:207], v[212:215], v[112:115]
	v_mfma_f32_16x16x32_bf16 v[100:103], v[192:195], v[220:223], v[100:103]
	v_mfma_f32_16x16x32_bf16 v[96:99], v[204:207], v[220:223], v[96:99]
	v_mfma_f32_16x16x32_bf16 v[84:87], v[192:195], v[228:231], v[84:87]
	v_mfma_f32_16x16x32_bf16 v[80:83], v[204:207], v[228:231], v[80:83]
	v_mfma_f32_16x16x32_bf16 v[68:71], v[192:195], v[236:239], v[68:71]
	v_mfma_f32_16x16x32_bf16 v[64:67], v[204:207], v[236:239], v[64:67]
	v_mfma_f32_16x16x32_bf16 v[116:119], v[196:199], v[216:219], v[116:119]
	v_mfma_f32_16x16x32_bf16 v[112:115], v[208:211], v[216:219], v[112:115]
	v_mfma_f32_16x16x32_bf16 v[100:103], v[196:199], v[224:227], v[100:103]
	v_mfma_f32_16x16x32_bf16 v[96:99], v[208:211], v[224:227], v[96:99]
	v_mfma_f32_16x16x32_bf16 v[84:87], v[196:199], v[232:235], v[84:87]
	v_mfma_f32_16x16x32_bf16 v[80:83], v[208:211], v[232:235], v[80:83]
	v_mfma_f32_16x16x32_bf16 v[68:71], v[196:199], v[240:243], v[68:71]
	v_mfma_f32_16x16x32_bf16 v[64:67], v[208:211], v[240:243], v[64:67]
	s_barrier
; #define PG8_STAGE(bufoff, gbase, voff) do { _Pragma("unroll") for (int _i = 0; _i < 2; ++_i) \
;         __builtin_amdgcn_global_load_lds((const unsigned*)((const char*)(gbase) + (voff)[_i]), (LAS unsigned*)(lds + (bufoff) + ldsw + _i * 8192), 16, 0, 0); } while (0)
; #define PG8_LDA(dst, b, h) do { _Pragma("unroll") for (int m = 0; m < 4; ++m) _Pragma("unroll") for (int k = 0; k < 2; ++k) dst[m][k] = *(const LAS bf16x8*)(lds + PG8_SA(b, h) + aoff + m * 2048 + k * 1024); } while (0)
; #define PG8_MMA(ai, bj, At, Bt) do { __builtin_amdgcn_s_setprio(1); _Pragma("unroll") for (int m = 0; m < 4; ++m) _Pragma("unroll") for (int n = 0; n < 2; ++n) _Pragma("unroll") for (int k = 0; k < 2; ++k) \
;         acc[ai][bj][m][n] = __builtin_amdgcn_mfma_f32_16x16x32_bf16(Bt[n][k], At[m][k], acc[ai][bj][m][n], 0, 0, 0); __builtin_amdgcn_s_setprio(0); } while (0)
; #define PG8_WAIT_V(n) asm volatile("s_waitcnt vmcnt(" #n ")" ::: "memory")
; #define PG8_WAIT_L(n) asm volatile("s_waitcnt lgkmcnt(" #n ")" ::: "memory")
; #define PG8_BAR __builtin_amdgcn_s_barrier()
; #define PG8_SCHED __builtin_amdgcn_sched_barrier(0)
; template <class Epi, class Sched, bool ALIGN_EPI = true>
; __device__ __forceinline__ void gemm_phase(LAS unsigned char* lds, const Gemm g, const Sched& S, const Epi& E) {
;     ...
;             PG8_LDA(At, 1, 1); PG8_STAGE(PG8_SB(1, 0), b3, voffB); PG8_STAGE(PG8_SB(1, 1), b3 + hstep, voffB); PG8_STAGE(PG8_SA(1, 0), a3, voffA);
;             PG8_WAIT_V(8); PG8_WAIT_L(0); PG8_BAR; PG8_MMA(1, 0, At, B0); PG8_MMA(1, 1, At, B1); PG8_BAR; PG8_SCHED;
;         }
	s_add_i32 s38, s46, s42
	v_lshl_add_u64 v[164:165], v[164:165], 0, s[22:23]
	s_mov_b32 m0, s38
	ds_read_b128 v[212:215], v171 offset:49152
	ds_read_b128 v[216:219], v171 offset:50176
	ds_read_b128 v[220:223], v171 offset:51200
	ds_read_b128 v[224:227], v171 offset:52224
	ds_read_b128 v[228:231], v171 offset:53248
	ds_read_b128 v[232:235], v171 offset:54272
	ds_read_b128 v[236:239], v171 offset:55296
	ds_read_b128 v[240:243], v171 offset:56320
	global_load_lds_dwordx4 v[164:165], off
	s_add_i32 m0, s38, 0x2000
	s_add_u32 s36, s36, 0x80080
	v_lshl_add_u64 v[164:165], v[176:177], 0, s[22:23]
	s_addc_u32 s37, s37, 0
	s_add_i32 s38, s47, s42
	global_load_lds_dwordx4 v[164:165], off
	v_lshl_add_u64 v[164:165], s[36:37], 0, v[130:131]
	s_mov_b32 m0, s38
	s_nop 0
	global_load_lds_dwordx4 v[164:165], off
	v_lshl_add_u64 v[164:165], s[36:37], 0, v[134:135]
	s_add_i32 m0, s38, 0x2000
	s_nop 0
	global_load_lds_dwordx4 v[164:165], off
	v_lshl_add_u64 v[164:165], v[200:201], 0, s[22:23]
	s_mov_b32 m0, s54
	s_nop 0
	global_load_lds_dwordx4 v[164:165], off
	v_lshl_add_u64 v[164:165], v[244:245], 0, s[22:23]
	s_mov_b32 m0, s55
	s_nop 0
	global_load_lds_dwordx4 v[164:165], off
	s_waitcnt vmcnt(8)
	s_waitcnt lgkmcnt(0)
	s_barrier
	s_waitcnt lgkmcnt(0)
	v_mfma_f32_16x16x32_bf16 v[60:63], v[172:175], v[212:215], v[60:63]
	v_mfma_f32_16x16x32_bf16 v[56:59], v[184:187], v[212:215], v[56:59]
	v_mfma_f32_16x16x32_bf16 v[44:47], v[172:175], v[220:223], v[44:47]
	v_mfma_f32_16x16x32_bf16 v[40:43], v[184:187], v[220:223], v[40:43]
	v_mfma_f32_16x16x32_bf16 v[28:31], v[172:175], v[228:231], v[28:31]
	v_mfma_f32_16x16x32_bf16 v[24:27], v[184:187], v[228:231], v[24:27]
	v_mfma_f32_16x16x32_bf16 v[12:15], v[172:175], v[236:239], v[12:15]
	v_mfma_f32_16x16x32_bf16 v[8:11], v[184:187], v[236:239], v[8:11]
	v_mfma_f32_16x16x32_bf16 v[60:63], v[180:183], v[216:219], v[60:63]
	v_mfma_f32_16x16x32_bf16 v[56:59], v[188:191], v[216:219], v[56:59]
	v_mfma_f32_16x16x32_bf16 v[44:47], v[180:183], v[224:227], v[44:47]
	v_mfma_f32_16x16x32_bf16 v[40:43], v[188:191], v[224:227], v[40:43]
	v_mfma_f32_16x16x32_bf16 v[28:31], v[180:183], v[232:235], v[28:31]
	v_mfma_f32_16x16x32_bf16 v[24:27], v[188:191], v[232:235], v[24:27]
	v_mfma_f32_16x16x32_bf16 v[12:15], v[180:183], v[240:243], v[12:15]
	v_mfma_f32_16x16x32_bf16 v[8:11], v[188:191], v[240:243], v[8:11]
	v_mfma_f32_16x16x32_bf16 v[52:55], v[192:195], v[212:215], v[52:55]
	v_mfma_f32_16x16x32_bf16 v[48:51], v[204:207], v[212:215], v[48:51]
	v_mfma_f32_16x16x32_bf16 v[36:39], v[192:195], v[220:223], v[36:39]
	v_mfma_f32_16x16x32_bf16 v[32:35], v[204:207], v[220:223], v[32:35]
	v_mfma_f32_16x16x32_bf16 v[20:23], v[192:195], v[228:231], v[20:23]
	v_mfma_f32_16x16x32_bf16 v[16:19], v[204:207], v[228:231], v[16:19]
	v_mfma_f32_16x16x32_bf16 v[4:7], v[192:195], v[236:239], v[4:7]
	v_mfma_f32_16x16x32_bf16 v[0:3], v[204:207], v[236:239], v[0:3]
	v_mfma_f32_16x16x32_bf16 v[52:55], v[196:199], v[216:219], v[52:55]
	v_mfma_f32_16x16x32_bf16 v[48:51], v[208:211], v[216:219], v[48:51]
	v_mfma_f32_16x16x32_bf16 v[36:39], v[196:199], v[224:227], v[36:39]
	v_mfma_f32_16x16x32_bf16 v[32:35], v[208:211], v[224:227], v[32:35]
	v_mfma_f32_16x16x32_bf16 v[20:23], v[196:199], v[232:235], v[20:23]
	v_mfma_f32_16x16x32_bf16 v[16:19], v[208:211], v[232:235], v[16:19]
	v_mfma_f32_16x16x32_bf16 v[4:7], v[196:199], v[240:243], v[4:7]
	v_mfma_f32_16x16x32_bf16 v[0:3], v[208:211], v[240:243], v[0:3]
	s_barrier
	s_add_i32 s89, s89, 2
	s_add_u32 s34, s34, 0x100
	s_addc_u32 s35, s35, 0
	s_add_u32 s87, s87, 0x100
	s_addc_u32 s88, s88, 0
	s_cmp_gt_u32 s89, 29
	s_cbranch_scc0 .LBB0_195
	s_and_b64 vcc, exec, s[24:25]
	s_cbranch_vccnz .LBB0_202
	s_lshr_b32 s9, s81, 2
	s_cmp_lt_i32 s9, 1
	s_mov_b64 s[34:35], -1
	s_cbranch_scc0 .LBB0_203

; #define PG8_STAGE(bufoff, gbase, voff) do { _Pragma("unroll") for (int _i = 0; _i < 2; ++_i) \
;         __builtin_amdgcn_global_load_lds((const unsigned*)((const char*)(gbase) + (voff)[_i]), (LAS unsigned*)(lds + (bufoff) + ldsw + _i * 8192), 16, 0, 0); } while (0)
; #define PG8_LDA(dst, b, h) do { _Pragma("unroll") for (int m = 0; m < 4; ++m) _Pragma("unroll") for (int k = 0; k < 2; ++k) dst[m][k] = *(const LAS bf16x8*)(lds + PG8_SA(b, h) + aoff + m * 2048 + k * 1024); } while (0)
; #define PG8_LDB(dst, b, h) do { _Pragma("unroll") for (int n = 0; n < 2; ++n) _Pragma("unroll") for (int k = 0; k < 2; ++k) dst[n][k] = *(const LAS bf16x8*)(lds + PG8_SB(b, h) + boff + n * 2048 + k * 1024); } while (0)
; #define PG8_MMA(ai, bj, At, Bt) do { __builtin_amdgcn_s_setprio(1); _Pragma("unroll") for (int m = 0; m < 4; ++m) _Pragma("unroll") for (int n = 0; n < 2; ++n) _Pragma("unroll") for (int k = 0; k < 2; ++k) \
;         acc[ai][bj][m][n] = __builtin_amdgcn_mfma_f32_16x16x32_bf16(Bt[n][k], At[m][k], acc[ai][bj][m][n], 0, 0, 0); __builtin_amdgcn_s_setprio(0); } while (0)
; #define PG8_WAIT_V(n) asm volatile("s_waitcnt vmcnt(" #n ")" ::: "memory")
; #define PG8_WAIT_L(n) asm volatile("s_waitcnt lgkmcnt(" #n ")" ::: "memory")
; #define PG8_BAR __builtin_amdgcn_s_barrier()
; #define PG8_SCHED __builtin_amdgcn_sched_barrier(0)
; template <class Epi, class Sched, bool ALIGN_EPI = true>
; __device__ __forceinline__ void gemm_phase(LAS unsigned char* lds, const Gemm g, const Sched& S, const Epi& E) {
;     ...
;         for (int t = 0; t < nt; t += 2) {
;             const bool last = (t == nt - 2);
;             const char* a1 = cA + (size_t)(t + 1) * kstep;
;             const char* a2 = last ? nA : cA + (size_t)(t + 2) * kstep; const char* b2 = last ? nB : cB + (size_t)(t + 2) * kstep;
;             const char* a3 = a2 + kstep; const char* b3 = b2 + kstep;
;             PG8_LDB(B0, 0, 0); PG8_LDB(B1, 0, 1); PG8_SCHED; PG8_LDA(At, 0, 0); PG8_STAGE(PG8_SA(1, 1), a1 + hstep, voffA);
;             PG8_WAIT_V(8); PG8_WAIT_L(0); PG8_BAR; PG8_MMA(0, 0, At, B0); PG8_MMA(0, 1, At, B1); PG8_BAR; PG8_SCHED;
;             PG8_LDA(At, 0, 1); PG8_STAGE(PG8_SB(0, 0), b2, voffB); PG8_STAGE(PG8_SB(0, 1), b2 + hstep, voffB); PG8_STAGE(PG8_SA(0, 0), a2, voffA);
.LBB0_223:
	ds_read_b128 v[128:131], v203
	s_waitcnt lgkmcnt(0)
	ds_read_b128 v[132:135], v203 offset:1024
	ds_read_b128 v[136:139], v203 offset:2048
	ds_read_b128 v[140:143], v203 offset:3072
	ds_read_b128 v[176:179], v204
	ds_read_b128 v[180:183], v204 offset:1024
	ds_read_b128 v[184:187], v204 offset:2048
	ds_read_b128 v[188:191], v204 offset:3072
	s_add_u32 s46, s76, 0xfff80080
	s_addc_u32 s47, s77, -1
	s_cmp_eq_u32 vcc_hi, 28
	s_cselect_b32 s81, s9, s47
	s_cselect_b32 s80, s30, s46
	s_cselect_b32 s79, s11, vcc_lo
	s_cselect_b32 s78, s96, s97
	v_lshl_add_u64 v[200:201], s[76:77], 0, v[164:165]
	s_add_i32 m0, s55, 0xc000
	ds_read_b128 v[192:195], v205
	ds_read_b128 v[196:199], v205 offset:1024
	ds_read_b128 v[208:211], v205 offset:2048
	ds_read_b128 v[212:215], v205 offset:3072
	ds_read_b128 v[216:219], v205 offset:4096
	ds_read_b128 v[220:223], v205 offset:5120
	ds_read_b128 v[224:227], v205 offset:6144
	ds_read_b128 v[228:231], v205 offset:7168
	global_load_lds_dwordx4 v[200:201], off
	v_lshl_add_u64 v[200:201], s[76:77], 0, v[166:167]
	s_add_i32 m0, s55, 0xe000
	s_nop 0
	global_load_lds_dwordx4 v[200:201], off
	s_waitcnt vmcnt(8)
	s_waitcnt lgkmcnt(0)
	s_barrier
	s_waitcnt lgkmcnt(0)
	v_mfma_f32_16x16x32_bf16 v[124:127], v[128:131], v[192:195], v[124:127]
	v_mfma_f32_16x16x32_bf16 v[120:123], v[136:139], v[192:195], v[120:123]
	v_mfma_f32_16x16x32_bf16 v[108:111], v[128:131], v[208:211], v[108:111]
	v_mfma_f32_16x16x32_bf16 v[104:107], v[136:139], v[208:211], v[104:107]
	v_mfma_f32_16x16x32_bf16 v[92:95], v[128:131], v[216:219], v[92:95]
	v_mfma_f32_16x16x32_bf16 v[88:91], v[136:139], v[216:219], v[88:91]
	v_mfma_f32_16x16x32_bf16 v[76:79], v[128:131], v[224:227], v[76:79]
	v_mfma_f32_16x16x32_bf16 v[72:75], v[136:139], v[224:227], v[72:75]
	v_mfma_f32_16x16x32_bf16 v[124:127], v[132:135], v[196:199], v[124:127]
	v_mfma_f32_16x16x32_bf16 v[120:123], v[140:143], v[196:199], v[120:123]
	v_mfma_f32_16x16x32_bf16 v[108:111], v[132:135], v[212:215], v[108:111]
	v_mfma_f32_16x16x32_bf16 v[104:107], v[140:143], v[212:215], v[104:107]
	v_mfma_f32_16x16x32_bf16 v[92:95], v[132:135], v[220:223], v[92:95]
	v_mfma_f32_16x16x32_bf16 v[88:91], v[140:143], v[220:223], v[88:91]
	v_mfma_f32_16x16x32_bf16 v[76:79], v[132:135], v[228:231], v[76:79]
	v_mfma_f32_16x16x32_bf16 v[72:75], v[140:143], v[228:231], v[72:75]
	v_mfma_f32_16x16x32_bf16 v[116:119], v[176:179], v[192:195], v[116:119]
	v_mfma_f32_16x16x32_bf16 v[112:115], v[184:187], v[192:195], v[112:115]
	v_mfma_f32_16x16x32_bf16 v[100:103], v[176:179], v[208:211], v[100:103]
	v_mfma_f32_16x16x32_bf16 v[96:99], v[184:187], v[208:211], v[96:99]
	v_mfma_f32_16x16x32_bf16 v[84:87], v[176:179], v[216:219], v[84:87]
	v_mfma_f32_16x16x32_bf16 v[80:83], v[184:187], v[216:219], v[80:83]
	v_mfma_f32_16x16x32_bf16 v[68:71], v[176:179], v[224:227], v[68:71]
	v_mfma_f32_16x16x32_bf16 v[64:67], v[184:187], v[224:227], v[64:67]
	v_mfma_f32_16x16x32_bf16 v[116:119], v[180:183], v[196:199], v[116:119]
	v_mfma_f32_16x16x32_bf16 v[112:115], v[188:191], v[196:199], v[112:115]
	v_mfma_f32_16x16x32_bf16 v[100:103], v[180:183], v[212:215], v[100:103]
	v_mfma_f32_16x16x32_bf16 v[96:99], v[188:191], v[212:215], v[96:99]
	v_mfma_f32_16x16x32_bf16 v[84:87], v[180:183], v[220:223], v[84:87]
	v_mfma_f32_16x16x32_bf16 v[80:83], v[188:191], v[220:223], v[80:83]
	v_mfma_f32_16x16x32_bf16 v[68:71], v[180:183], v[228:231], v[68:71]
	v_mfma_f32_16x16x32_bf16 v[64:67], v[188:191], v[228:231], v[64:67]
	s_barrier
	s_add_i32 s46, s90, s53
	v_lshl_add_u64 v[200:201], s[78:79], 0, v[146:147]
	s_mov_b32 m0, s46
	ds_read_b128 v[192:195], v205 offset:16384
	ds_read_b128 v[196:199], v205 offset:17408
	ds_read_b128 v[208:211], v205 offset:18432
	ds_read_b128 v[212:215], v205 offset:19456
	ds_read_b128 v[216:219], v205 offset:20480
	ds_read_b128 v[220:223], v205 offset:21504
	ds_read_b128 v[224:227], v205 offset:22528
	ds_read_b128 v[228:231], v205 offset:23552
	global_load_lds_dwordx4 v[200:201], off
	s_add_i32 m0, s46, 0x2000
	s_add_u32 s46, s78, 0x80000
	v_lshl_add_u64 v[232:233], s[78:79], 0, v[150:151]
	s_addc_u32 s47, s79, 0
	s_add_i32 s82, s91, s53
	global_load_lds_dwordx4 v[232:233], off
	v_lshl_add_u64 v[234:235], s[46:47], 0, v[146:147]
	s_mov_b32 m0, s82
	v_lshl_add_u64 v[236:237], s[80:81], 0, v[148:149]
	global_load_lds_dwordx4 v[234:235], off
	v_lshl_add_u64 v[234:235], s[46:47], 0, v[150:151]
	s_add_i32 m0, s82, 0x2000
	s_nop 0
	global_load_lds_dwordx4 v[234:235], off
	v_lshl_add_u64 v[234:235], s[80:81], 0, v[144:145]
	s_mov_b32 m0, s55
	s_nop 0
	global_load_lds_dwordx4 v[234:235], off
	s_mov_b32 m0, s57
	s_nop 0
	global_load_lds_dwordx4 v[236:237], off
	s_waitcnt vmcnt(8)
	s_waitcnt lgkmcnt(0)
	s_barrier
; #define PG8_STAGE(bufoff, gbase, voff) do { _Pragma("unroll") for (int _i = 0; _i < 2; ++_i) \
;         __builtin_amdgcn_global_load_lds((const unsigned*)((const char*)(gbase) + (voff)[_i]), (LAS unsigned*)(lds + (bufoff) + ldsw + _i * 8192), 16, 0, 0); } while (0)
; #define PG8_LDA(dst, b, h) do { _Pragma("unroll") for (int m = 0; m < 4; ++m) _Pragma("unroll") for (int k = 0; k < 2; ++k) dst[m][k] = *(const LAS bf16x8*)(lds + PG8_SA(b, h) + aoff + m * 2048 + k * 1024); } while (0)
; #define PG8_LDB(dst, b, h) do { _Pragma("unroll") for (int n = 0; n < 2; ++n) _Pragma("unroll") for (int k = 0; k < 2; ++k) dst[n][k] = *(const LAS bf16x8*)(lds + PG8_SB(b, h) + boff + n * 2048 + k * 1024); } while (0)
; #define PG8_MMA(ai, bj, At, Bt) do { __builtin_amdgcn_s_setprio(1); _Pragma("unroll") for (int m = 0; m < 4; ++m) _Pragma("unroll") for (int n = 0; n < 2; ++n) _Pragma("unroll") for (int k = 0; k < 2; ++k) \
;         acc[ai][bj][m][n] = __builtin_amdgcn_mfma_f32_16x16x32_bf16(Bt[n][k], At[m][k], acc[ai][bj][m][n], 0, 0, 0); __builtin_amdgcn_s_setprio(0); } while (0)
; #define PG8_WAIT_V(n) asm volatile("s_waitcnt vmcnt(" #n ")" ::: "memory")
; #define PG8_WAIT_L(n) asm volatile("s_waitcnt lgkmcnt(" #n ")" ::: "memory")
; #define PG8_BAR __builtin_amdgcn_s_barrier()
; #define PG8_SCHED __builtin_amdgcn_sched_barrier(0)
; template <class Epi, class Sched, bool ALIGN_EPI = true>
; __device__ __forceinline__ void gemm_phase(LAS unsigned char* lds, const Gemm g, const Sched& S, const Epi& E) {
;     ...
;             PG8_WAIT_V(8); PG8_WAIT_L(0); PG8_BAR; PG8_MMA(1, 0, At, B0); PG8_MMA(1, 1, At, B1); PG8_BAR; PG8_SCHED;
;             PG8_LDB(B0, 1, 0); PG8_LDB(B1, 1, 1); PG8_SCHED; PG8_LDA(At, 1, 0); PG8_STAGE(PG8_SA(0, 1), a2 + hstep, voffA);
;             PG8_WAIT_V(8); PG8_WAIT_L(0); PG8_BAR; PG8_MMA(0, 0, At, B0); PG8_MMA(0, 1, At, B1); PG8_BAR; PG8_SCHED;
;             PG8_LDA(At, 1, 1); PG8_STAGE(PG8_SB(1, 0), b3, voffB); PG8_STAGE(PG8_SB(1, 1), b3 + hstep, voffB); PG8_STAGE(PG8_SA(1, 0), a3, voffA);
	s_waitcnt lgkmcnt(0)
	v_mfma_f32_16x16x32_bf16 v[60:63], v[128:131], v[192:195], v[60:63]
	v_mfma_f32_16x16x32_bf16 v[56:59], v[136:139], v[192:195], v[56:59]
	v_mfma_f32_16x16x32_bf16 v[44:47], v[128:131], v[208:211], v[44:47]
	v_mfma_f32_16x16x32_bf16 v[40:43], v[136:139], v[208:211], v[40:43]
	v_mfma_f32_16x16x32_bf16 v[28:31], v[128:131], v[216:219], v[28:31]
	v_mfma_f32_16x16x32_bf16 v[24:27], v[136:139], v[216:219], v[24:27]
	v_mfma_f32_16x16x32_bf16 v[12:15], v[128:131], v[224:227], v[12:15]
	v_mfma_f32_16x16x32_bf16 v[8:11], v[136:139], v[224:227], v[8:11]
	v_mfma_f32_16x16x32_bf16 v[60:63], v[132:135], v[196:199], v[60:63]
	v_mfma_f32_16x16x32_bf16 v[56:59], v[140:143], v[196:199], v[56:59]
	v_mfma_f32_16x16x32_bf16 v[44:47], v[132:135], v[212:215], v[44:47]
	v_mfma_f32_16x16x32_bf16 v[40:43], v[140:143], v[212:215], v[40:43]
	v_mfma_f32_16x16x32_bf16 v[28:31], v[132:135], v[220:223], v[28:31]
	v_mfma_f32_16x16x32_bf16 v[24:27], v[140:143], v[220:223], v[24:27]
	v_mfma_f32_16x16x32_bf16 v[12:15], v[132:135], v[228:231], v[12:15]
	v_mfma_f32_16x16x32_bf16 v[8:11], v[140:143], v[228:231], v[8:11]
	v_mfma_f32_16x16x32_bf16 v[52:55], v[176:179], v[192:195], v[52:55]
	v_mfma_f32_16x16x32_bf16 v[48:51], v[184:187], v[192:195], v[48:51]
	v_mfma_f32_16x16x32_bf16 v[36:39], v[176:179], v[208:211], v[36:39]
	v_mfma_f32_16x16x32_bf16 v[32:35], v[184:187], v[208:211], v[32:35]
	v_mfma_f32_16x16x32_bf16 v[20:23], v[176:179], v[216:219], v[20:23]
	v_mfma_f32_16x16x32_bf16 v[16:19], v[184:187], v[216:219], v[16:19]
	v_mfma_f32_16x16x32_bf16 v[4:7], v[176:179], v[224:227], v[4:7]
	v_mfma_f32_16x16x32_bf16 v[0:3], v[184:187], v[224:227], v[0:3]
	v_mfma_f32_16x16x32_bf16 v[52:55], v[180:183], v[196:199], v[52:55]
	v_mfma_f32_16x16x32_bf16 v[48:51], v[188:191], v[196:199], v[48:51]
	v_mfma_f32_16x16x32_bf16 v[36:39], v[180:183], v[212:215], v[36:39]
	v_mfma_f32_16x16x32_bf16 v[32:35], v[188:191], v[212:215], v[32:35]
	v_mfma_f32_16x16x32_bf16 v[20:23], v[180:183], v[220:223], v[20:23]
	v_mfma_f32_16x16x32_bf16 v[16:19], v[188:191], v[220:223], v[16:19]
	v_mfma_f32_16x16x32_bf16 v[4:7], v[180:183], v[228:231], v[4:7]
	v_mfma_f32_16x16x32_bf16 v[0:3], v[188:191], v[228:231], v[0:3]
	s_barrier
	s_add_i32 s82, 0, 0x18000
	s_add_i32 s92, 0, 0x1c000
	v_add_u32_e32 v140, s82, v161
	v_add_u32_e32 v152, s92, v161
	ds_read_b128 v[128:131], v140
	ds_read_b128 v[132:135], v140 offset:1024
	ds_read_b128 v[136:139], v140 offset:2048
	ds_read_b128 v[140:143], v140 offset:3072
	ds_read_b128 v[176:179], v152
	ds_read_b128 v[180:183], v152 offset:1024
	ds_read_b128 v[184:187], v152 offset:2048
	ds_read_b128 v[188:191], v152 offset:3072
	s_add_u32 s46, s80, 0x80000
	s_addc_u32 s47, s81, 0
	s_mov_b32 m0, s83
	v_lshl_add_u64 v[238:239], s[46:47], 0, v[144:145]
	ds_read_b128 v[192:195], v205 offset:32768
	ds_read_b128 v[196:199], v205 offset:33792
	ds_read_b128 v[208:211], v205 offset:34816
	ds_read_b128 v[212:215], v205 offset:35840
	ds_read_b128 v[216:219], v205 offset:36864
	ds_read_b128 v[220:223], v205 offset:37888
	ds_read_b128 v[224:227], v205 offset:38912
	ds_read_b128 v[228:231], v205 offset:39936
	global_load_lds_dwordx4 v[238:239], off
	v_lshl_add_u64 v[238:239], s[46:47], 0, v[148:149]
	s_mov_b32 m0, s84
	s_nop 0
	global_load_lds_dwordx4 v[238:239], off
	s_waitcnt vmcnt(8)
	s_waitcnt lgkmcnt(0)
	s_barrier
	s_waitcnt lgkmcnt(0)
	v_mfma_f32_16x16x32_bf16 v[124:127], v[128:131], v[192:195], v[124:127]
	v_mfma_f32_16x16x32_bf16 v[120:123], v[136:139], v[192:195], v[120:123]
	v_mfma_f32_16x16x32_bf16 v[108:111], v[128:131], v[208:211], v[108:111]
	v_mfma_f32_16x16x32_bf16 v[104:107], v[136:139], v[208:211], v[104:107]
	v_mfma_f32_16x16x32_bf16 v[92:95], v[128:131], v[216:219], v[92:95]
	v_mfma_f32_16x16x32_bf16 v[88:91], v[136:139], v[216:219], v[88:91]
	v_mfma_f32_16x16x32_bf16 v[76:79], v[128:131], v[224:227], v[76:79]
	v_mfma_f32_16x16x32_bf16 v[72:75], v[136:139], v[224:227], v[72:75]
	v_mfma_f32_16x16x32_bf16 v[124:127], v[132:135], v[196:199], v[124:127]
	v_mfma_f32_16x16x32_bf16 v[120:123], v[140:143], v[196:199], v[120:123]
	v_mfma_f32_16x16x32_bf16 v[108:111], v[132:135], v[212:215], v[108:111]
	v_mfma_f32_16x16x32_bf16 v[104:107], v[140:143], v[212:215], v[104:107]
	v_mfma_f32_16x16x32_bf16 v[92:95], v[132:135], v[220:223], v[92:95]
	v_mfma_f32_16x16x32_bf16 v[88:91], v[140:143], v[220:223], v[88:91]
	v_mfma_f32_16x16x32_bf16 v[76:79], v[132:135], v[228:231], v[76:79]
	v_mfma_f32_16x16x32_bf16 v[72:75], v[140:143], v[228:231], v[72:75]
	v_mfma_f32_16x16x32_bf16 v[116:119], v[176:179], v[192:195], v[116:119]
	v_mfma_f32_16x16x32_bf16 v[112:115], v[184:187], v[192:195], v[112:115]
	v_mfma_f32_16x16x32_bf16 v[100:103], v[176:179], v[208:211], v[100:103]
	v_mfma_f32_16x16x32_bf16 v[96:99], v[184:187], v[208:211], v[96:99]
	v_mfma_f32_16x16x32_bf16 v[84:87], v[176:179], v[216:219], v[84:87]
	v_mfma_f32_16x16x32_bf16 v[80:83], v[184:187], v[216:219], v[80:83]
	v_mfma_f32_16x16x32_bf16 v[68:71], v[176:179], v[224:227], v[68:71]
	v_mfma_f32_16x16x32_bf16 v[64:67], v[184:187], v[224:227], v[64:67]
	v_mfma_f32_16x16x32_bf16 v[116:119], v[180:183], v[196:199], v[116:119]
	v_mfma_f32_16x16x32_bf16 v[112:115], v[188:191], v[196:199], v[112:115]
	v_mfma_f32_16x16x32_bf16 v[100:103], v[180:183], v[212:215], v[100:103]
	v_mfma_f32_16x16x32_bf16 v[96:99], v[188:191], v[212:215], v[96:99]
	v_mfma_f32_16x16x32_bf16 v[84:87], v[180:183], v[220:223], v[84:87]
	v_mfma_f32_16x16x32_bf16 v[80:83], v[188:191], v[220:223], v[80:83]
	v_mfma_f32_16x16x32_bf16 v[68:71], v[180:183], v[228:231], v[68:71]
	v_mfma_f32_16x16x32_bf16 v[64:67], v[188:191], v[228:231], v[64:67]
	s_barrier
; #define PG8_STAGE(bufoff, gbase, voff) do { _Pragma("unroll") for (int _i = 0; _i < 2; ++_i) \
;         __builtin_amdgcn_global_load_lds((const unsigned*)((const char*)(gbase) + (voff)[_i]), (LAS unsigned*)(lds + (bufoff) + ldsw + _i * 8192), 16, 0, 0); } while (0)
; #define PG8_LDA(dst, b, h) do { _Pragma("unroll") for (int m = 0; m < 4; ++m) _Pragma("unroll") for (int k = 0; k < 2; ++k) dst[m][k] = *(const LAS bf16x8*)(lds + PG8_SA(b, h) + aoff + m * 2048 + k * 1024); } while (0)
; #define PG8_MMA(ai, bj, At, Bt) do { __builtin_amdgcn_s_setprio(1); _Pragma("unroll") for (int m = 0; m < 4; ++m) _Pragma("unroll") for (int n = 0; n < 2; ++n) _Pragma("unroll") for (int k = 0; k < 2; ++k) \
;         acc[ai][bj][m][n] = __builtin_amdgcn_mfma_f32_16x16x32_bf16(Bt[n][k], At[m][k], acc[ai][bj][m][n], 0, 0, 0); __builtin_amdgcn_s_setprio(0); } while (0)
; #define PG8_WAIT_V(n) asm volatile("s_waitcnt vmcnt(" #n ")" ::: "memory")
; #define PG8_WAIT_L(n) asm volatile("s_waitcnt lgkmcnt(" #n ")" ::: "memory")
; #define PG8_BAR __builtin_amdgcn_s_barrier()
; #define PG8_SCHED __builtin_amdgcn_sched_barrier(0)
; template <class Epi, class Sched, bool ALIGN_EPI = true>
; __device__ __forceinline__ void gemm_phase(LAS unsigned char* lds, const Gemm g, const Sched& S, const Epi& E) {
;     ...
;             PG8_LDA(At, 1, 1); PG8_STAGE(PG8_SB(1, 0), b3, voffB); PG8_STAGE(PG8_SB(1, 1), b3 + hstep, voffB); PG8_STAGE(PG8_SA(1, 0), a3, voffA);
;             PG8_WAIT_V(8); PG8_WAIT_L(0); PG8_BAR; PG8_MMA(1, 0, At, B0); PG8_MMA(1, 1, At, B1); PG8_BAR; PG8_SCHED;
;         }
	s_add_i32 s46, s82, s53
	v_lshl_add_u64 v[200:201], v[200:201], 0, s[28:29]
	s_mov_b32 m0, s46
	ds_read_b128 v[192:195], v205 offset:49152
	ds_read_b128 v[196:199], v205 offset:50176
	ds_read_b128 v[208:211], v205 offset:51200
	ds_read_b128 v[212:215], v205 offset:52224
	ds_read_b128 v[216:219], v205 offset:53248
	ds_read_b128 v[220:223], v205 offset:54272
	ds_read_b128 v[224:227], v205 offset:55296
	ds_read_b128 v[228:231], v205 offset:56320
	global_load_lds_dwordx4 v[200:201], off
	s_add_i32 m0, s46, 0x2000
	s_add_u32 s46, s78, 0x80080
	v_lshl_add_u64 v[200:201], v[232:233], 0, s[28:29]
	s_addc_u32 s47, s79, 0
	s_add_i32 s78, s92, s53
	global_load_lds_dwordx4 v[200:201], off
	v_lshl_add_u64 v[200:201], s[46:47], 0, v[146:147]
	s_mov_b32 m0, s78
	s_nop 0
	global_load_lds_dwordx4 v[200:201], off
	v_lshl_add_u64 v[200:201], s[46:47], 0, v[150:151]
	s_add_i32 m0, s78, 0x2000
	s_nop 0
	global_load_lds_dwordx4 v[200:201], off
	v_lshl_add_u64 v[200:201], v[234:235], 0, s[28:29]
	s_mov_b32 m0, s87
	s_nop 0
	global_load_lds_dwordx4 v[200:201], off
	v_lshl_add_u64 v[200:201], v[236:237], 0, s[28:29]
	s_mov_b32 m0, s88
	s_nop 0
	global_load_lds_dwordx4 v[200:201], off
	s_waitcnt vmcnt(8)
	s_waitcnt lgkmcnt(0)
	s_barrier
	s_waitcnt lgkmcnt(0)
	v_mfma_f32_16x16x32_bf16 v[60:63], v[128:131], v[192:195], v[60:63]
	v_mfma_f32_16x16x32_bf16 v[56:59], v[136:139], v[192:195], v[56:59]
	v_mfma_f32_16x16x32_bf16 v[44:47], v[128:131], v[208:211], v[44:47]
	v_mfma_f32_16x16x32_bf16 v[40:43], v[136:139], v[208:211], v[40:43]
	v_mfma_f32_16x16x32_bf16 v[28:31], v[128:131], v[216:219], v[28:31]
	v_mfma_f32_16x16x32_bf16 v[24:27], v[136:139], v[216:219], v[24:27]
	v_mfma_f32_16x16x32_bf16 v[12:15], v[128:131], v[224:227], v[12:15]
	v_mfma_f32_16x16x32_bf16 v[8:11], v[136:139], v[224:227], v[8:11]
	v_mfma_f32_16x16x32_bf16 v[60:63], v[132:135], v[196:199], v[60:63]
	v_mfma_f32_16x16x32_bf16 v[56:59], v[140:143], v[196:199], v[56:59]
	v_mfma_f32_16x16x32_bf16 v[44:47], v[132:135], v[212:215], v[44:47]
	v_mfma_f32_16x16x32_bf16 v[40:43], v[140:143], v[212:215], v[40:43]
	v_mfma_f32_16x16x32_bf16 v[28:31], v[132:135], v[220:223], v[28:31]
	v_mfma_f32_16x16x32_bf16 v[24:27], v[140:143], v[220:223], v[24:27]
	v_mfma_f32_16x16x32_bf16 v[12:15], v[132:135], v[228:231], v[12:15]
	v_mfma_f32_16x16x32_bf16 v[8:11], v[140:143], v[228:231], v[8:11]
	v_mfma_f32_16x16x32_bf16 v[52:55], v[176:179], v[192:195], v[52:55]
	v_mfma_f32_16x16x32_bf16 v[48:51], v[184:187], v[192:195], v[48:51]
	v_mfma_f32_16x16x32_bf16 v[36:39], v[176:179], v[208:211], v[36:39]
	v_mfma_f32_16x16x32_bf16 v[32:35], v[184:187], v[208:211], v[32:35]
	v_mfma_f32_16x16x32_bf16 v[20:23], v[176:179], v[216:219], v[20:23]
	v_mfma_f32_16x16x32_bf16 v[16:19], v[184:187], v[216:219], v[16:19]
	v_mfma_f32_16x16x32_bf16 v[4:7], v[176:179], v[224:227], v[4:7]
	v_mfma_f32_16x16x32_bf16 v[0:3], v[184:187], v[224:227], v[0:3]
	v_mfma_f32_16x16x32_bf16 v[52:55], v[180:183], v[196:199], v[52:55]
	v_mfma_f32_16x16x32_bf16 v[48:51], v[188:191], v[196:199], v[48:51]
	v_mfma_f32_16x16x32_bf16 v[36:39], v[180:183], v[212:215], v[36:39]
	v_mfma_f32_16x16x32_bf16 v[32:35], v[188:191], v[212:215], v[32:35]
	v_mfma_f32_16x16x32_bf16 v[20:23], v[180:183], v[220:223], v[20:23]
	v_mfma_f32_16x16x32_bf16 v[16:19], v[188:191], v[220:223], v[16:19]
	v_mfma_f32_16x16x32_bf16 v[4:7], v[180:183], v[228:231], v[4:7]
	v_mfma_f32_16x16x32_bf16 v[0:3], v[188:191], v[228:231], v[0:3]
	s_barrier
	s_add_i32 vcc_hi, vcc_hi, 2
	s_add_u32 s76, s76, 0x100
	s_addc_u32 s77, s77, 0
	s_add_u32 s97, s97, 0x100
	s_addc_u32 vcc_lo, vcc_lo, 0
	s_cmp_gt_u32 vcc_hi, 29
	s_cbranch_scc0 .LBB0_223
	s_and_b64 vcc, exec, s[34:35]
	s_cbranch_vccz .LBB0_226
	s_barrier

; #define PG8_STAGE(bufoff, gbase, voff) do { _Pragma("unroll") for (int _i = 0; _i < 2; ++_i) \
;         __builtin_amdgcn_global_load_lds((const unsigned*)((const char*)(gbase) + (voff)[_i]), (LAS unsigned*)(lds + (bufoff) + ldsw + _i * 8192), 16, 0, 0); } while (0)
; #define PG8_LDA(dst, b, h) do { _Pragma("unroll") for (int m = 0; m < 4; ++m) _Pragma("unroll") for (int k = 0; k < 2; ++k) dst[m][k] = *(const LAS bf16x8*)(lds + PG8_SA(b, h) + aoff + m * 2048 + k * 1024); } while (0)
; #define PG8_LDB(dst, b, h) do { _Pragma("unroll") for (int n = 0; n < 2; ++n) _Pragma("unroll") for (int k = 0; k < 2; ++k) dst[n][k] = *(const LAS bf16x8*)(lds + PG8_SB(b, h) + boff + n * 2048 + k * 1024); } while (0)
; #define PG8_MMA(ai, bj, At, Bt) do { __builtin_amdgcn_s_setprio(1); _Pragma("unroll") for (int m = 0; m < 4; ++m) _Pragma("unroll") for (int n = 0; n < 2; ++n) _Pragma("unroll") for (int k = 0; k < 2; ++k) \
;         acc[ai][bj][m][n] = __builtin_amdgcn_mfma_f32_16x16x32_bf16(Bt[n][k], At[m][k], acc[ai][bj][m][n], 0, 0, 0); __builtin_amdgcn_s_setprio(0); } while (0)
; #define PG8_WAIT_V(n) asm volatile("s_waitcnt vmcnt(" #n ")" ::: "memory")
; #define PG8_WAIT_L(n) asm volatile("s_waitcnt lgkmcnt(" #n ")" ::: "memory")
; #define PG8_BAR __builtin_amdgcn_s_barrier()
; #define PG8_SCHED __builtin_amdgcn_sched_barrier(0)
; template <class Epi, class Sched, bool ALIGN_EPI = true>
; __device__ __forceinline__ void gemm_phase(LAS unsigned char* lds, const Gemm g, const Sched& S, const Epi& E) {
;     ...
;         for (int t = 0; t < nt; t += 2) {
;             const bool last = (t == nt - 2);
;             const char* a1 = cA + (size_t)(t + 1) * kstep;
;             const char* a2 = last ? nA : cA + (size_t)(t + 2) * kstep; const char* b2 = last ? nB : cB + (size_t)(t + 2) * kstep;
;             const char* a3 = a2 + kstep; const char* b3 = b2 + kstep;
;             PG8_LDB(B0, 0, 0); PG8_LDB(B1, 0, 1); PG8_SCHED; PG8_LDA(At, 0, 0); PG8_STAGE(PG8_SA(1, 1), a1 + hstep, voffA);
;             PG8_WAIT_V(8); PG8_WAIT_L(0); PG8_BAR; PG8_MMA(0, 0, At, B0); PG8_MMA(0, 1, At, B1); PG8_BAR; PG8_SCHED;
;             PG8_LDA(At, 0, 1); PG8_STAGE(PG8_SB(0, 0), b2, voffB); PG8_STAGE(PG8_SB(0, 1), b2 + hstep, voffB); PG8_STAGE(PG8_SA(0, 0), a2, voffA);
.LBB0_560:
	ds_read_b128 v[128:131], v206
	ds_read_b128 v[132:135], v206 offset:1024
	ds_read_b128 v[136:139], v206 offset:2048
	ds_read_b128 v[140:143], v206 offset:3072
	ds_read_b128 v[144:147], v207
	ds_read_b128 v[148:151], v207 offset:1024
	ds_read_b128 v[152:155], v207 offset:2048
	ds_read_b128 v[156:159], v207 offset:3072
	s_add_u32 s28, s26, 0xfff80080
	s_addc_u32 s29, s27, -1
	s_cmp_eq_u32 s58, 28
	s_cselect_b32 s31, s53, s29
	s_cselect_b32 s30, s54, s28
	s_cselect_b32 s29, s9, s57
	s_cselect_b32 s28, s55, s56
	v_lshl_add_u64 v[214:215], s[26:27], 0, v[184:185]
	s_add_i32 m0, s38, 0xc000
	ds_read_b128 v[160:163], v208
	ds_read_b128 v[164:167], v208 offset:1024
	ds_read_b128 v[168:171], v208 offset:2048
	ds_read_b128 v[172:175], v208 offset:3072
	ds_read_b128 v[188:191], v208 offset:4096
	ds_read_b128 v[192:195], v208 offset:5120
	ds_read_b128 v[196:199], v208 offset:6144
	ds_read_b128 v[210:213], v208 offset:7168
	global_load_lds_dwordx4 v[214:215], off
	v_lshl_add_u64 v[214:215], s[26:27], 0, v[186:187]
	s_add_i32 m0, s38, 0xe000
	s_nop 0
	global_load_lds_dwordx4 v[214:215], off
	s_waitcnt vmcnt(8)
	s_waitcnt lgkmcnt(0)
	s_barrier
	s_waitcnt lgkmcnt(0)
	v_mfma_f32_16x16x32_bf16 v[124:127], v[128:131], v[160:163], v[124:127]
	v_mfma_f32_16x16x32_bf16 v[120:123], v[136:139], v[160:163], v[120:123]
	v_mfma_f32_16x16x32_bf16 v[108:111], v[128:131], v[168:171], v[108:111]
	v_mfma_f32_16x16x32_bf16 v[104:107], v[136:139], v[168:171], v[104:107]
	v_mfma_f32_16x16x32_bf16 v[92:95], v[128:131], v[188:191], v[92:95]
	v_mfma_f32_16x16x32_bf16 v[88:91], v[136:139], v[188:191], v[88:91]
	v_mfma_f32_16x16x32_bf16 v[76:79], v[128:131], v[196:199], v[76:79]
	v_mfma_f32_16x16x32_bf16 v[72:75], v[136:139], v[196:199], v[72:75]
	v_mfma_f32_16x16x32_bf16 v[124:127], v[132:135], v[164:167], v[124:127]
	v_mfma_f32_16x16x32_bf16 v[120:123], v[140:143], v[164:167], v[120:123]
	v_mfma_f32_16x16x32_bf16 v[108:111], v[132:135], v[172:175], v[108:111]
	v_mfma_f32_16x16x32_bf16 v[104:107], v[140:143], v[172:175], v[104:107]
	v_mfma_f32_16x16x32_bf16 v[92:95], v[132:135], v[192:195], v[92:95]
	v_mfma_f32_16x16x32_bf16 v[88:91], v[140:143], v[192:195], v[88:91]
	v_mfma_f32_16x16x32_bf16 v[76:79], v[132:135], v[210:213], v[76:79]
	v_mfma_f32_16x16x32_bf16 v[72:75], v[140:143], v[210:213], v[72:75]
	v_mfma_f32_16x16x32_bf16 v[116:119], v[144:147], v[160:163], v[116:119]
	v_mfma_f32_16x16x32_bf16 v[112:115], v[152:155], v[160:163], v[112:115]
	v_mfma_f32_16x16x32_bf16 v[100:103], v[144:147], v[168:171], v[100:103]
	v_mfma_f32_16x16x32_bf16 v[96:99], v[152:155], v[168:171], v[96:99]
	v_mfma_f32_16x16x32_bf16 v[84:87], v[144:147], v[188:191], v[84:87]
	v_mfma_f32_16x16x32_bf16 v[80:83], v[152:155], v[188:191], v[80:83]
	v_mfma_f32_16x16x32_bf16 v[68:71], v[144:147], v[196:199], v[68:71]
	v_mfma_f32_16x16x32_bf16 v[64:67], v[152:155], v[196:199], v[64:67]
	v_mfma_f32_16x16x32_bf16 v[116:119], v[148:151], v[164:167], v[116:119]
	v_mfma_f32_16x16x32_bf16 v[112:115], v[156:159], v[164:167], v[112:115]
	v_mfma_f32_16x16x32_bf16 v[100:103], v[148:151], v[172:175], v[100:103]
	v_mfma_f32_16x16x32_bf16 v[96:99], v[156:159], v[172:175], v[96:99]
	v_mfma_f32_16x16x32_bf16 v[84:87], v[148:151], v[192:195], v[84:87]
	v_mfma_f32_16x16x32_bf16 v[80:83], v[156:159], v[192:195], v[80:83]
	v_mfma_f32_16x16x32_bf16 v[68:71], v[148:151], v[210:213], v[68:71]
	v_mfma_f32_16x16x32_bf16 v[64:67], v[156:159], v[210:213], v[64:67]
	s_barrier
	s_add_i32 s46, s44, s37
	v_lshl_add_u64 v[214:215], s[28:29], 0, v[178:179]
	s_mov_b32 m0, s46
	ds_read_b128 v[160:163], v208 offset:16384
	ds_read_b128 v[164:167], v208 offset:17408
	ds_read_b128 v[168:171], v208 offset:18432
	ds_read_b128 v[172:175], v208 offset:19456
	ds_read_b128 v[188:191], v208 offset:20480
	ds_read_b128 v[192:195], v208 offset:21504
	ds_read_b128 v[196:199], v208 offset:22528
	ds_read_b128 v[210:213], v208 offset:23552
	global_load_lds_dwordx4 v[214:215], off
	s_add_i32 m0, s46, 0x2000
	s_add_u32 s46, s28, 0x80000
	v_lshl_add_u64 v[216:217], s[28:29], 0, v[182:183]
	s_addc_u32 s47, s29, 0
	s_add_i32 s59, s45, s37
	global_load_lds_dwordx4 v[216:217], off
	v_lshl_add_u64 v[218:219], s[46:47], 0, v[178:179]
	s_mov_b32 m0, s59
	v_lshl_add_u64 v[220:221], s[30:31], 0, v[180:181]
	global_load_lds_dwordx4 v[218:219], off
	v_lshl_add_u64 v[218:219], s[46:47], 0, v[182:183]
	s_add_i32 m0, s59, 0x2000
	s_nop 0
	global_load_lds_dwordx4 v[218:219], off
	v_lshl_add_u64 v[218:219], s[30:31], 0, v[176:177]
	s_mov_b32 m0, s38
	s_nop 0
	global_load_lds_dwordx4 v[218:219], off
	s_mov_b32 m0, s39
	s_nop 0
	global_load_lds_dwordx4 v[220:221], off
	s_waitcnt vmcnt(8)
	s_waitcnt lgkmcnt(0)
	s_barrier
; #define PG8_STAGE(bufoff, gbase, voff) do { _Pragma("unroll") for (int _i = 0; _i < 2; ++_i) \
;         __builtin_amdgcn_global_load_lds((const unsigned*)((const char*)(gbase) + (voff)[_i]), (LAS unsigned*)(lds + (bufoff) + ldsw + _i * 8192), 16, 0, 0); } while (0)
; #define PG8_LDA(dst, b, h) do { _Pragma("unroll") for (int m = 0; m < 4; ++m) _Pragma("unroll") for (int k = 0; k < 2; ++k) dst[m][k] = *(const LAS bf16x8*)(lds + PG8_SA(b, h) + aoff + m * 2048 + k * 1024); } while (0)
; #define PG8_LDB(dst, b, h) do { _Pragma("unroll") for (int n = 0; n < 2; ++n) _Pragma("unroll") for (int k = 0; k < 2; ++k) dst[n][k] = *(const LAS bf16x8*)(lds + PG8_SB(b, h) + boff + n * 2048 + k * 1024); } while (0)
; #define PG8_MMA(ai, bj, At, Bt) do { __builtin_amdgcn_s_setprio(1); _Pragma("unroll") for (int m = 0; m < 4; ++m) _Pragma("unroll") for (int n = 0; n < 2; ++n) _Pragma("unroll") for (int k = 0; k < 2; ++k) \
;         acc[ai][bj][m][n] = __builtin_amdgcn_mfma_f32_16x16x32_bf16(Bt[n][k], At[m][k], acc[ai][bj][m][n], 0, 0, 0); __builtin_amdgcn_s_setprio(0); } while (0)
; #define PG8_WAIT_V(n) asm volatile("s_waitcnt vmcnt(" #n ")" ::: "memory")
; #define PG8_WAIT_L(n) asm volatile("s_waitcnt lgkmcnt(" #n ")" ::: "memory")
; #define PG8_BAR __builtin_amdgcn_s_barrier()
; #define PG8_SCHED __builtin_amdgcn_sched_barrier(0)
; template <class Epi, class Sched, bool ALIGN_EPI = true>
; __device__ __forceinline__ void gemm_phase(LAS unsigned char* lds, const Gemm g, const Sched& S, const Epi& E) {
;     ...
;             PG8_WAIT_V(8); PG8_WAIT_L(0); PG8_BAR; PG8_MMA(1, 0, At, B0); PG8_MMA(1, 1, At, B1); PG8_BAR; PG8_SCHED;
;             PG8_LDB(B0, 1, 0); PG8_LDB(B1, 1, 1); PG8_SCHED; PG8_LDA(At, 1, 0); PG8_STAGE(PG8_SA(0, 1), a2 + hstep, voffA);
;             PG8_WAIT_V(8); PG8_WAIT_L(0); PG8_BAR; PG8_MMA(0, 0, At, B0); PG8_MMA(0, 1, At, B1); PG8_BAR; PG8_SCHED;
;             PG8_LDA(At, 1, 1); PG8_STAGE(PG8_SB(1, 0), b3, voffB); PG8_STAGE(PG8_SB(1, 1), b3 + hstep, voffB); PG8_STAGE(PG8_SA(1, 0), a3, voffA);
	s_waitcnt lgkmcnt(0)
	v_mfma_f32_16x16x32_bf16 v[60:63], v[128:131], v[160:163], v[60:63]
	v_mfma_f32_16x16x32_bf16 v[56:59], v[136:139], v[160:163], v[56:59]
	v_mfma_f32_16x16x32_bf16 v[44:47], v[128:131], v[168:171], v[44:47]
	v_mfma_f32_16x16x32_bf16 v[40:43], v[136:139], v[168:171], v[40:43]
	v_mfma_f32_16x16x32_bf16 v[28:31], v[128:131], v[188:191], v[28:31]
	v_mfma_f32_16x16x32_bf16 v[24:27], v[136:139], v[188:191], v[24:27]
	v_mfma_f32_16x16x32_bf16 v[12:15], v[128:131], v[196:199], v[12:15]
	v_mfma_f32_16x16x32_bf16 v[8:11], v[136:139], v[196:199], v[8:11]
	v_mfma_f32_16x16x32_bf16 v[60:63], v[132:135], v[164:167], v[60:63]
	v_mfma_f32_16x16x32_bf16 v[56:59], v[140:143], v[164:167], v[56:59]
	v_mfma_f32_16x16x32_bf16 v[44:47], v[132:135], v[172:175], v[44:47]
	v_mfma_f32_16x16x32_bf16 v[40:43], v[140:143], v[172:175], v[40:43]
	v_mfma_f32_16x16x32_bf16 v[28:31], v[132:135], v[192:195], v[28:31]
	v_mfma_f32_16x16x32_bf16 v[24:27], v[140:143], v[192:195], v[24:27]
	v_mfma_f32_16x16x32_bf16 v[12:15], v[132:135], v[210:213], v[12:15]
	v_mfma_f32_16x16x32_bf16 v[8:11], v[140:143], v[210:213], v[8:11]
	v_mfma_f32_16x16x32_bf16 v[52:55], v[144:147], v[160:163], v[52:55]
	v_mfma_f32_16x16x32_bf16 v[48:51], v[152:155], v[160:163], v[48:51]
	v_mfma_f32_16x16x32_bf16 v[36:39], v[144:147], v[168:171], v[36:39]
	v_mfma_f32_16x16x32_bf16 v[32:35], v[152:155], v[168:171], v[32:35]
	v_mfma_f32_16x16x32_bf16 v[20:23], v[144:147], v[188:191], v[20:23]
	v_mfma_f32_16x16x32_bf16 v[16:19], v[152:155], v[188:191], v[16:19]
	v_mfma_f32_16x16x32_bf16 v[4:7], v[144:147], v[196:199], v[4:7]
	v_mfma_f32_16x16x32_bf16 v[0:3], v[152:155], v[196:199], v[0:3]
	v_mfma_f32_16x16x32_bf16 v[52:55], v[148:151], v[164:167], v[52:55]
	v_mfma_f32_16x16x32_bf16 v[48:51], v[156:159], v[164:167], v[48:51]
	v_mfma_f32_16x16x32_bf16 v[36:39], v[148:151], v[172:175], v[36:39]
	v_mfma_f32_16x16x32_bf16 v[32:35], v[156:159], v[172:175], v[32:35]
	v_mfma_f32_16x16x32_bf16 v[20:23], v[148:151], v[192:195], v[20:23]
	v_mfma_f32_16x16x32_bf16 v[16:19], v[156:159], v[192:195], v[16:19]
	v_mfma_f32_16x16x32_bf16 v[4:7], v[148:151], v[210:213], v[4:7]
	v_mfma_f32_16x16x32_bf16 v[0:3], v[156:159], v[210:213], v[0:3]
	s_barrier
	s_add_i32 s46, 0, 0x18000
	s_add_i32 s47, 0, 0x1c000
	v_add_u32_e32 v140, s46, v204
	v_add_u32_e32 v156, s47, v204
	ds_read_b128 v[128:131], v140
	ds_read_b128 v[132:135], v140 offset:1024
	ds_read_b128 v[136:139], v140 offset:2048
	ds_read_b128 v[140:143], v140 offset:3072
	ds_read_b128 v[144:147], v156
	ds_read_b128 v[148:151], v156 offset:1024
	ds_read_b128 v[152:155], v156 offset:2048
	ds_read_b128 v[156:159], v156 offset:3072
	s_add_u32 s30, s30, 0x80000
	s_addc_u32 s31, s31, 0
	s_mov_b32 m0, s40
	v_lshl_add_u64 v[222:223], s[30:31], 0, v[176:177]
	ds_read_b128 v[160:163], v208 offset:32768
	ds_read_b128 v[164:167], v208 offset:33792
	ds_read_b128 v[168:171], v208 offset:34816
	ds_read_b128 v[172:175], v208 offset:35840
	ds_read_b128 v[188:191], v208 offset:36864
	ds_read_b128 v[192:195], v208 offset:37888
	ds_read_b128 v[196:199], v208 offset:38912
	ds_read_b128 v[210:213], v208 offset:39936
	global_load_lds_dwordx4 v[222:223], off
	v_lshl_add_u64 v[222:223], s[30:31], 0, v[180:181]
	s_mov_b32 m0, s41
	s_nop 0
	global_load_lds_dwordx4 v[222:223], off
	s_waitcnt vmcnt(8)
	s_waitcnt lgkmcnt(0)
	s_barrier
	s_waitcnt lgkmcnt(0)
	v_mfma_f32_16x16x32_bf16 v[124:127], v[128:131], v[160:163], v[124:127]
	v_mfma_f32_16x16x32_bf16 v[120:123], v[136:139], v[160:163], v[120:123]
	v_mfma_f32_16x16x32_bf16 v[108:111], v[128:131], v[168:171], v[108:111]
	v_mfma_f32_16x16x32_bf16 v[104:107], v[136:139], v[168:171], v[104:107]
	v_mfma_f32_16x16x32_bf16 v[92:95], v[128:131], v[188:191], v[92:95]
	v_mfma_f32_16x16x32_bf16 v[88:91], v[136:139], v[188:191], v[88:91]
	v_mfma_f32_16x16x32_bf16 v[76:79], v[128:131], v[196:199], v[76:79]
	v_mfma_f32_16x16x32_bf16 v[72:75], v[136:139], v[196:199], v[72:75]
	v_mfma_f32_16x16x32_bf16 v[124:127], v[132:135], v[164:167], v[124:127]
	v_mfma_f32_16x16x32_bf16 v[120:123], v[140:143], v[164:167], v[120:123]
	v_mfma_f32_16x16x32_bf16 v[108:111], v[132:135], v[172:175], v[108:111]
	v_mfma_f32_16x16x32_bf16 v[104:107], v[140:143], v[172:175], v[104:107]
	v_mfma_f32_16x16x32_bf16 v[92:95], v[132:135], v[192:195], v[92:95]
	v_mfma_f32_16x16x32_bf16 v[88:91], v[140:143], v[192:195], v[88:91]
	v_mfma_f32_16x16x32_bf16 v[76:79], v[132:135], v[210:213], v[76:79]
	v_mfma_f32_16x16x32_bf16 v[72:75], v[140:143], v[210:213], v[72:75]
	v_mfma_f32_16x16x32_bf16 v[116:119], v[144:147], v[160:163], v[116:119]
	v_mfma_f32_16x16x32_bf16 v[112:115], v[152:155], v[160:163], v[112:115]
	v_mfma_f32_16x16x32_bf16 v[100:103], v[144:147], v[168:171], v[100:103]
	v_mfma_f32_16x16x32_bf16 v[96:99], v[152:155], v[168:171], v[96:99]
	v_mfma_f32_16x16x32_bf16 v[84:87], v[144:147], v[188:191], v[84:87]
	v_mfma_f32_16x16x32_bf16 v[80:83], v[152:155], v[188:191], v[80:83]
	v_mfma_f32_16x16x32_bf16 v[68:71], v[144:147], v[196:199], v[68:71]
	v_mfma_f32_16x16x32_bf16 v[64:67], v[152:155], v[196:199], v[64:67]
	v_mfma_f32_16x16x32_bf16 v[116:119], v[148:151], v[164:167], v[116:119]
	v_mfma_f32_16x16x32_bf16 v[112:115], v[156:159], v[164:167], v[112:115]
	v_mfma_f32_16x16x32_bf16 v[100:103], v[148:151], v[172:175], v[100:103]
	v_mfma_f32_16x16x32_bf16 v[96:99], v[156:159], v[172:175], v[96:99]
	v_mfma_f32_16x16x32_bf16 v[84:87], v[148:151], v[192:195], v[84:87]
	v_mfma_f32_16x16x32_bf16 v[80:83], v[156:159], v[192:195], v[80:83]
	v_mfma_f32_16x16x32_bf16 v[68:71], v[148:151], v[210:213], v[68:71]
	v_mfma_f32_16x16x32_bf16 v[64:67], v[156:159], v[210:213], v[64:67]
	s_barrier
; #define PG8_STAGE(bufoff, gbase, voff) do { _Pragma("unroll") for (int _i = 0; _i < 2; ++_i) \
;         __builtin_amdgcn_global_load_lds((const unsigned*)((const char*)(gbase) + (voff)[_i]), (LAS unsigned*)(lds + (bufoff) + ldsw + _i * 8192), 16, 0, 0); } while (0)
; #define PG8_LDA(dst, b, h) do { _Pragma("unroll") for (int m = 0; m < 4; ++m) _Pragma("unroll") for (int k = 0; k < 2; ++k) dst[m][k] = *(const LAS bf16x8*)(lds + PG8_SA(b, h) + aoff + m * 2048 + k * 1024); } while (0)
; #define PG8_MMA(ai, bj, At, Bt) do { __builtin_amdgcn_s_setprio(1); _Pragma("unroll") for (int m = 0; m < 4; ++m) _Pragma("unroll") for (int n = 0; n < 2; ++n) _Pragma("unroll") for (int k = 0; k < 2; ++k) \
;         acc[ai][bj][m][n] = __builtin_amdgcn_mfma_f32_16x16x32_bf16(Bt[n][k], At[m][k], acc[ai][bj][m][n], 0, 0, 0); __builtin_amdgcn_s_setprio(0); } while (0)
; #define PG8_WAIT_V(n) asm volatile("s_waitcnt vmcnt(" #n ")" ::: "memory")
; #define PG8_WAIT_L(n) asm volatile("s_waitcnt lgkmcnt(" #n ")" ::: "memory")
; #define PG8_BAR __builtin_amdgcn_s_barrier()
; #define PG8_SCHED __builtin_amdgcn_sched_barrier(0)
; template <class Epi, class Sched, bool ALIGN_EPI = true>
; __device__ __forceinline__ void gemm_phase(LAS unsigned char* lds, const Gemm g, const Sched& S, const Epi& E) {
;     ...
;             PG8_LDA(At, 1, 1); PG8_STAGE(PG8_SB(1, 0), b3, voffB); PG8_STAGE(PG8_SB(1, 1), b3 + hstep, voffB); PG8_STAGE(PG8_SA(1, 0), a3, voffA);
;             PG8_WAIT_V(8); PG8_WAIT_L(0); PG8_BAR; PG8_MMA(1, 0, At, B0); PG8_MMA(1, 1, At, B1); PG8_BAR; PG8_SCHED;
;         }
	s_add_i32 s30, s46, s37
	v_lshl_add_u64 v[214:215], v[214:215], 0, s[20:21]
	s_mov_b32 m0, s30
	ds_read_b128 v[160:163], v208 offset:49152
	ds_read_b128 v[164:167], v208 offset:50176
	ds_read_b128 v[168:171], v208 offset:51200
	ds_read_b128 v[172:175], v208 offset:52224
	ds_read_b128 v[188:191], v208 offset:53248
	ds_read_b128 v[192:195], v208 offset:54272
	ds_read_b128 v[196:199], v208 offset:55296
	ds_read_b128 v[210:213], v208 offset:56320
	global_load_lds_dwordx4 v[214:215], off
	s_add_i32 m0, s30, 0x2000
	s_add_u32 s28, s28, 0x80080
	v_lshl_add_u64 v[214:215], v[216:217], 0, s[20:21]
	s_addc_u32 s29, s29, 0
	s_add_i32 s30, s47, s37
	global_load_lds_dwordx4 v[214:215], off
	v_lshl_add_u64 v[214:215], s[28:29], 0, v[178:179]
	s_mov_b32 m0, s30
	s_nop 0
	global_load_lds_dwordx4 v[214:215], off
	v_lshl_add_u64 v[214:215], s[28:29], 0, v[182:183]
	s_add_i32 m0, s30, 0x2000
	s_nop 0
	global_load_lds_dwordx4 v[214:215], off
	v_lshl_add_u64 v[214:215], v[218:219], 0, s[20:21]
	s_mov_b32 m0, s42
	s_nop 0
	global_load_lds_dwordx4 v[214:215], off
	v_lshl_add_u64 v[214:215], v[220:221], 0, s[20:21]
	s_mov_b32 m0, s43
	s_nop 0
	global_load_lds_dwordx4 v[214:215], off
	s_waitcnt vmcnt(8)
	s_waitcnt lgkmcnt(0)
	s_barrier
	s_waitcnt lgkmcnt(0)
	v_mfma_f32_16x16x32_bf16 v[60:63], v[128:131], v[160:163], v[60:63]
	v_mfma_f32_16x16x32_bf16 v[56:59], v[136:139], v[160:163], v[56:59]
	v_mfma_f32_16x16x32_bf16 v[44:47], v[128:131], v[168:171], v[44:47]
	v_mfma_f32_16x16x32_bf16 v[40:43], v[136:139], v[168:171], v[40:43]
	v_mfma_f32_16x16x32_bf16 v[28:31], v[128:131], v[188:191], v[28:31]
	v_mfma_f32_16x16x32_bf16 v[24:27], v[136:139], v[188:191], v[24:27]
	v_mfma_f32_16x16x32_bf16 v[12:15], v[128:131], v[196:199], v[12:15]
	v_mfma_f32_16x16x32_bf16 v[8:11], v[136:139], v[196:199], v[8:11]
	v_mfma_f32_16x16x32_bf16 v[60:63], v[132:135], v[164:167], v[60:63]
	v_mfma_f32_16x16x32_bf16 v[56:59], v[140:143], v[164:167], v[56:59]
	v_mfma_f32_16x16x32_bf16 v[44:47], v[132:135], v[172:175], v[44:47]
	v_mfma_f32_16x16x32_bf16 v[40:43], v[140:143], v[172:175], v[40:43]
	v_mfma_f32_16x16x32_bf16 v[28:31], v[132:135], v[192:195], v[28:31]
	v_mfma_f32_16x16x32_bf16 v[24:27], v[140:143], v[192:195], v[24:27]
	v_mfma_f32_16x16x32_bf16 v[12:15], v[132:135], v[210:213], v[12:15]
	v_mfma_f32_16x16x32_bf16 v[8:11], v[140:143], v[210:213], v[8:11]
	v_mfma_f32_16x16x32_bf16 v[52:55], v[144:147], v[160:163], v[52:55]
	v_mfma_f32_16x16x32_bf16 v[48:51], v[152:155], v[160:163], v[48:51]
	v_mfma_f32_16x16x32_bf16 v[36:39], v[144:147], v[168:171], v[36:39]
	v_mfma_f32_16x16x32_bf16 v[32:35], v[152:155], v[168:171], v[32:35]
	v_mfma_f32_16x16x32_bf16 v[20:23], v[144:147], v[188:191], v[20:23]
	v_mfma_f32_16x16x32_bf16 v[16:19], v[152:155], v[188:191], v[16:19]
	v_mfma_f32_16x16x32_bf16 v[4:7], v[144:147], v[196:199], v[4:7]
	v_mfma_f32_16x16x32_bf16 v[0:3], v[152:155], v[196:199], v[0:3]
	v_mfma_f32_16x16x32_bf16 v[52:55], v[148:151], v[164:167], v[52:55]
	v_mfma_f32_16x16x32_bf16 v[48:51], v[156:159], v[164:167], v[48:51]
	v_mfma_f32_16x16x32_bf16 v[36:39], v[148:151], v[172:175], v[36:39]
	v_mfma_f32_16x16x32_bf16 v[32:35], v[156:159], v[172:175], v[32:35]
	v_mfma_f32_16x16x32_bf16 v[20:23], v[148:151], v[192:195], v[20:23]
	v_mfma_f32_16x16x32_bf16 v[16:19], v[156:159], v[192:195], v[16:19]
	v_mfma_f32_16x16x32_bf16 v[4:7], v[148:151], v[210:213], v[4:7]
	v_mfma_f32_16x16x32_bf16 v[0:3], v[156:159], v[210:213], v[0:3]
	s_barrier
	s_add_i32 s58, s58, 2
	s_add_u32 s26, s26, 0x100
	s_addc_u32 s27, s27, 0
	s_add_u32 s56, s56, 0x100
	s_addc_u32 s57, s57, 0
	s_cmp_gt_u32 s58, 29
	s_cbranch_scc0 .LBB0_560
	s_and_b64 vcc, exec, s[22:23]
	s_cbranch_vccz .LBB0_563
	s_barrier

; #define PG8_STAGE(bufoff, gbase, voff) do { _Pragma("unroll") for (int _i = 0; _i < 2; ++_i) \
;         __builtin_amdgcn_global_load_lds((const unsigned*)((const char*)(gbase) + (voff)[_i]), (LAS unsigned*)(lds + (bufoff) + ldsw + _i * 8192), 16, 0, 0); } while (0)
; #define PG8_LDA(dst, b, h) do { _Pragma("unroll") for (int m = 0; m < 4; ++m) _Pragma("unroll") for (int k = 0; k < 2; ++k) dst[m][k] = *(const LAS bf16x8*)(lds + PG8_SA(b, h) + aoff + m * 2048 + k * 1024); } while (0)
; #define PG8_LDB(dst, b, h) do { _Pragma("unroll") for (int n = 0; n < 2; ++n) _Pragma("unroll") for (int k = 0; k < 2; ++k) dst[n][k] = *(const LAS bf16x8*)(lds + PG8_SB(b, h) + boff + n * 2048 + k * 1024); } while (0)
; #define PG8_MMA(ai, bj, At, Bt) do { __builtin_amdgcn_s_setprio(1); _Pragma("unroll") for (int m = 0; m < 4; ++m) _Pragma("unroll") for (int n = 0; n < 2; ++n) _Pragma("unroll") for (int k = 0; k < 2; ++k) \
;         acc[ai][bj][m][n] = __builtin_amdgcn_mfma_f32_16x16x32_bf16(Bt[n][k], At[m][k], acc[ai][bj][m][n], 0, 0, 0); __builtin_amdgcn_s_setprio(0); } while (0)
; #define PG8_WAIT_V(n) asm volatile("s_waitcnt vmcnt(" #n ")" ::: "memory")
; #define PG8_WAIT_L(n) asm volatile("s_waitcnt lgkmcnt(" #n ")" ::: "memory")
; #define PG8_BAR __builtin_amdgcn_s_barrier()
; #define PG8_SCHED __builtin_amdgcn_sched_barrier(0)
; template <class Epi, class Sched, bool ALIGN_EPI = true>
; __device__ __forceinline__ void gemm_phase(LAS unsigned char* lds, const Gemm g, const Sched& S, const Epi& E) {
;     ...
;         for (int t = 0; t < nt; t += 2) {
;             const bool last = (t == nt - 2);
;             const char* a1 = cA + (size_t)(t + 1) * kstep;
;             const char* a2 = last ? nA : cA + (size_t)(t + 2) * kstep; const char* b2 = last ? nB : cB + (size_t)(t + 2) * kstep;
;             const char* a3 = a2 + kstep; const char* b3 = b2 + kstep;
;             PG8_LDB(B0, 0, 0); PG8_LDB(B1, 0, 1); PG8_SCHED; PG8_LDA(At, 0, 0); PG8_STAGE(PG8_SA(1, 1), a1 + hstep, voffA);
;             PG8_WAIT_V(8); PG8_WAIT_L(0); PG8_BAR; PG8_MMA(0, 0, At, B0); PG8_MMA(0, 1, At, B1); PG8_BAR; PG8_SCHED;
;             PG8_LDA(At, 0, 1); PG8_STAGE(PG8_SB(0, 0), b2, voffB); PG8_STAGE(PG8_SB(0, 1), b2 + hstep, voffB); PG8_STAGE(PG8_SA(0, 0), a2, voffA);
.LBB0_647:
	ds_read_b128 v[152:155], v147
	ds_read_b128 v[156:159], v147 offset:1024
	ds_read_b128 v[160:163], v147 offset:2048
	ds_read_b128 v[164:167], v147 offset:3072
	ds_read_b128 v[168:171], v148
	ds_read_b128 v[172:175], v148 offset:1024
	ds_read_b128 v[176:179], v148 offset:2048
	ds_read_b128 v[180:183], v148 offset:3072
	s_add_u32 s26, s24, 0xfff80080
	s_addc_u32 s27, s25, -1
	s_cmp_eq_u32 s56, 28
	s_cselect_b32 s29, s51, s27
	s_cselect_b32 s28, s52, s26
	s_cselect_b32 s27, s7, s55
	s_cselect_b32 s26, s53, s54
	v_lshl_add_u64 v[140:141], s[24:25], 0, v[136:137]
	s_add_i32 m0, s37, 0xc000
	ds_read_b128 v[184:187], v149
	ds_read_b128 v[188:191], v149 offset:1024
	ds_read_b128 v[192:195], v149 offset:2048
	ds_read_b128 v[196:199], v149 offset:3072
	ds_read_b128 v[204:207], v149 offset:4096
	ds_read_b128 v[208:211], v149 offset:5120
	ds_read_b128 v[212:215], v149 offset:6144
	ds_read_b128 v[216:219], v149 offset:7168
	global_load_lds_dwordx4 v[140:141], off
	v_lshl_add_u64 v[140:141], s[24:25], 0, v[138:139]
	s_add_i32 m0, s37, 0xe000
	s_nop 0
	global_load_lds_dwordx4 v[140:141], off
	s_waitcnt vmcnt(8)
	s_waitcnt lgkmcnt(0)
	s_barrier
	s_waitcnt lgkmcnt(0)
	v_mfma_f32_16x16x32_bf16 v[112:115], v[152:155], v[184:187], v[112:115]
	v_mfma_f32_16x16x32_bf16 v[108:111], v[160:163], v[184:187], v[108:111]
	v_mfma_f32_16x16x32_bf16 v[100:103], v[152:155], v[192:195], v[100:103]
	v_mfma_f32_16x16x32_bf16 v[96:99], v[160:163], v[192:195], v[96:99]
	v_mfma_f32_16x16x32_bf16 v[92:95], v[152:155], v[204:207], v[92:95]
	v_mfma_f32_16x16x32_bf16 v[84:87], v[160:163], v[204:207], v[84:87]
	v_mfma_f32_16x16x32_bf16 v[76:79], v[152:155], v[212:215], v[76:79]
	v_mfma_f32_16x16x32_bf16 v[68:71], v[160:163], v[212:215], v[68:71]
	v_mfma_f32_16x16x32_bf16 v[112:115], v[156:159], v[188:191], v[112:115]
	v_mfma_f32_16x16x32_bf16 v[108:111], v[164:167], v[188:191], v[108:111]
	v_mfma_f32_16x16x32_bf16 v[100:103], v[156:159], v[196:199], v[100:103]
	v_mfma_f32_16x16x32_bf16 v[96:99], v[164:167], v[196:199], v[96:99]
	v_mfma_f32_16x16x32_bf16 v[92:95], v[156:159], v[208:211], v[92:95]
	v_mfma_f32_16x16x32_bf16 v[84:87], v[164:167], v[208:211], v[84:87]
	v_mfma_f32_16x16x32_bf16 v[76:79], v[156:159], v[216:219], v[76:79]
	v_mfma_f32_16x16x32_bf16 v[68:71], v[164:167], v[216:219], v[68:71]
	v_mfma_f32_16x16x32_bf16 v[124:127], v[168:171], v[184:187], v[124:127]
	v_mfma_f32_16x16x32_bf16 v[120:123], v[176:179], v[184:187], v[120:123]
	v_mfma_f32_16x16x32_bf16 v[116:119], v[168:171], v[192:195], v[116:119]
	v_mfma_f32_16x16x32_bf16 v[104:107], v[176:179], v[192:195], v[104:107]
	v_mfma_f32_16x16x32_bf16 v[88:91], v[168:171], v[204:207], v[88:91]
	v_mfma_f32_16x16x32_bf16 v[80:83], v[176:179], v[204:207], v[80:83]
	v_mfma_f32_16x16x32_bf16 v[72:75], v[168:171], v[212:215], v[72:75]
	v_mfma_f32_16x16x32_bf16 v[64:67], v[176:179], v[212:215], v[64:67]
	v_mfma_f32_16x16x32_bf16 v[124:127], v[172:175], v[188:191], v[124:127]
	v_mfma_f32_16x16x32_bf16 v[120:123], v[180:183], v[188:191], v[120:123]
	v_mfma_f32_16x16x32_bf16 v[116:119], v[172:175], v[196:199], v[116:119]
	v_mfma_f32_16x16x32_bf16 v[104:107], v[180:183], v[196:199], v[104:107]
	v_mfma_f32_16x16x32_bf16 v[88:91], v[172:175], v[208:211], v[88:91]
	v_mfma_f32_16x16x32_bf16 v[80:83], v[180:183], v[208:211], v[80:83]
	v_mfma_f32_16x16x32_bf16 v[72:75], v[172:175], v[216:219], v[72:75]
	v_mfma_f32_16x16x32_bf16 v[64:67], v[180:183], v[216:219], v[64:67]
	s_barrier
	s_add_i32 s46, s43, s36
	v_lshl_add_u64 v[140:141], s[26:27], 0, v[130:131]
	s_mov_b32 m0, s46
	ds_read_b128 v[184:187], v149 offset:16384
	ds_read_b128 v[188:191], v149 offset:17408
	ds_read_b128 v[192:195], v149 offset:18432
	ds_read_b128 v[196:199], v149 offset:19456
	ds_read_b128 v[204:207], v149 offset:20480
	ds_read_b128 v[208:211], v149 offset:21504
	ds_read_b128 v[212:215], v149 offset:22528
	ds_read_b128 v[216:219], v149 offset:23552
	global_load_lds_dwordx4 v[140:141], off
	s_add_i32 m0, s46, 0x2000
	s_add_u32 s46, s26, 0x80000
	v_lshl_add_u64 v[200:201], s[26:27], 0, v[134:135]
	s_addc_u32 s47, s27, 0
	s_add_i32 s57, s44, s36
	global_load_lds_dwordx4 v[200:201], off
	v_lshl_add_u64 v[220:221], s[46:47], 0, v[130:131]
	s_mov_b32 m0, s57
	v_lshl_add_u64 v[222:223], s[28:29], 0, v[132:133]
	global_load_lds_dwordx4 v[220:221], off
	v_lshl_add_u64 v[220:221], s[46:47], 0, v[134:135]
	s_add_i32 m0, s57, 0x2000
	s_nop 0
	global_load_lds_dwordx4 v[220:221], off
	v_lshl_add_u64 v[220:221], s[28:29], 0, v[128:129]
	s_mov_b32 m0, s37
	s_nop 0
	global_load_lds_dwordx4 v[220:221], off
	s_mov_b32 m0, s38
	s_nop 0
	global_load_lds_dwordx4 v[222:223], off
	s_waitcnt vmcnt(8)
	s_waitcnt lgkmcnt(0)
	s_barrier
; #define PG8_STAGE(bufoff, gbase, voff) do { _Pragma("unroll") for (int _i = 0; _i < 2; ++_i) \
;         __builtin_amdgcn_global_load_lds((const unsigned*)((const char*)(gbase) + (voff)[_i]), (LAS unsigned*)(lds + (bufoff) + ldsw + _i * 8192), 16, 0, 0); } while (0)
; #define PG8_LDA(dst, b, h) do { _Pragma("unroll") for (int m = 0; m < 4; ++m) _Pragma("unroll") for (int k = 0; k < 2; ++k) dst[m][k] = *(const LAS bf16x8*)(lds + PG8_SA(b, h) + aoff + m * 2048 + k * 1024); } while (0)
; #define PG8_LDB(dst, b, h) do { _Pragma("unroll") for (int n = 0; n < 2; ++n) _Pragma("unroll") for (int k = 0; k < 2; ++k) dst[n][k] = *(const LAS bf16x8*)(lds + PG8_SB(b, h) + boff + n * 2048 + k * 1024); } while (0)
; #define PG8_MMA(ai, bj, At, Bt) do { __builtin_amdgcn_s_setprio(1); _Pragma("unroll") for (int m = 0; m < 4; ++m) _Pragma("unroll") for (int n = 0; n < 2; ++n) _Pragma("unroll") for (int k = 0; k < 2; ++k) \
;         acc[ai][bj][m][n] = __builtin_amdgcn_mfma_f32_16x16x32_bf16(Bt[n][k], At[m][k], acc[ai][bj][m][n], 0, 0, 0); __builtin_amdgcn_s_setprio(0); } while (0)
; #define PG8_WAIT_V(n) asm volatile("s_waitcnt vmcnt(" #n ")" ::: "memory")
; #define PG8_WAIT_L(n) asm volatile("s_waitcnt lgkmcnt(" #n ")" ::: "memory")
; #define PG8_BAR __builtin_amdgcn_s_barrier()
; #define PG8_SCHED __builtin_amdgcn_sched_barrier(0)
; template <class Epi, class Sched, bool ALIGN_EPI = true>
; __device__ __forceinline__ void gemm_phase(LAS unsigned char* lds, const Gemm g, const Sched& S, const Epi& E) {
;     ...
;             PG8_WAIT_V(8); PG8_WAIT_L(0); PG8_BAR; PG8_MMA(1, 0, At, B0); PG8_MMA(1, 1, At, B1); PG8_BAR; PG8_SCHED;
;             PG8_LDB(B0, 1, 0); PG8_LDB(B1, 1, 1); PG8_SCHED; PG8_LDA(At, 1, 0); PG8_STAGE(PG8_SA(0, 1), a2 + hstep, voffA);
;             PG8_WAIT_V(8); PG8_WAIT_L(0); PG8_BAR; PG8_MMA(0, 0, At, B0); PG8_MMA(0, 1, At, B1); PG8_BAR; PG8_SCHED;
;             PG8_LDA(At, 1, 1); PG8_STAGE(PG8_SB(1, 0), b3, voffB); PG8_STAGE(PG8_SB(1, 1), b3 + hstep, voffB); PG8_STAGE(PG8_SA(1, 0), a3, voffA);
	s_waitcnt lgkmcnt(0)
	v_mfma_f32_16x16x32_bf16 v[60:63], v[152:155], v[184:187], v[60:63]
	v_mfma_f32_16x16x32_bf16 v[52:55], v[160:163], v[184:187], v[52:55]
	v_mfma_f32_16x16x32_bf16 v[44:47], v[152:155], v[192:195], v[44:47]
	v_mfma_f32_16x16x32_bf16 v[36:39], v[160:163], v[192:195], v[36:39]
	v_mfma_f32_16x16x32_bf16 v[28:31], v[152:155], v[204:207], v[28:31]
	v_mfma_f32_16x16x32_bf16 v[20:23], v[160:163], v[204:207], v[20:23]
	v_mfma_f32_16x16x32_bf16 v[12:15], v[152:155], v[212:215], v[12:15]
	v_mfma_f32_16x16x32_bf16 v[4:7], v[160:163], v[212:215], v[4:7]
	v_mfma_f32_16x16x32_bf16 v[60:63], v[156:159], v[188:191], v[60:63]
	v_mfma_f32_16x16x32_bf16 v[52:55], v[164:167], v[188:191], v[52:55]
	v_mfma_f32_16x16x32_bf16 v[44:47], v[156:159], v[196:199], v[44:47]
	v_mfma_f32_16x16x32_bf16 v[36:39], v[164:167], v[196:199], v[36:39]
	v_mfma_f32_16x16x32_bf16 v[28:31], v[156:159], v[208:211], v[28:31]
	v_mfma_f32_16x16x32_bf16 v[20:23], v[164:167], v[208:211], v[20:23]
	v_mfma_f32_16x16x32_bf16 v[12:15], v[156:159], v[216:219], v[12:15]
	v_mfma_f32_16x16x32_bf16 v[4:7], v[164:167], v[216:219], v[4:7]
	v_mfma_f32_16x16x32_bf16 v[56:59], v[168:171], v[184:187], v[56:59]
	v_mfma_f32_16x16x32_bf16 v[48:51], v[176:179], v[184:187], v[48:51]
	v_mfma_f32_16x16x32_bf16 v[40:43], v[168:171], v[192:195], v[40:43]
	v_mfma_f32_16x16x32_bf16 v[32:35], v[176:179], v[192:195], v[32:35]
	v_mfma_f32_16x16x32_bf16 v[24:27], v[168:171], v[204:207], v[24:27]
	v_mfma_f32_16x16x32_bf16 v[16:19], v[176:179], v[204:207], v[16:19]
	v_mfma_f32_16x16x32_bf16 v[8:11], v[168:171], v[212:215], v[8:11]
	v_mfma_f32_16x16x32_bf16 v[0:3], v[176:179], v[212:215], v[0:3]
	v_mfma_f32_16x16x32_bf16 v[56:59], v[172:175], v[188:191], v[56:59]
	v_mfma_f32_16x16x32_bf16 v[48:51], v[180:183], v[188:191], v[48:51]
	v_mfma_f32_16x16x32_bf16 v[40:43], v[172:175], v[196:199], v[40:43]
	v_mfma_f32_16x16x32_bf16 v[32:35], v[180:183], v[196:199], v[32:35]
	v_mfma_f32_16x16x32_bf16 v[24:27], v[172:175], v[208:211], v[24:27]
	v_mfma_f32_16x16x32_bf16 v[16:19], v[180:183], v[208:211], v[16:19]
	v_mfma_f32_16x16x32_bf16 v[8:11], v[172:175], v[216:219], v[8:11]
	v_mfma_f32_16x16x32_bf16 v[0:3], v[180:183], v[216:219], v[0:3]
	s_barrier
	s_add_i32 s46, 0, 0x18000
	v_add_u32_e32 v151, s46, v145
	s_add_i32 s47, 0, 0x1c000
	ds_read_b128 v[152:155], v151
	ds_read_b128 v[156:159], v151 offset:1024
	ds_read_b128 v[160:163], v151 offset:2048
	ds_read_b128 v[164:167], v151 offset:3072
	v_add_u32_e32 v151, s47, v145
	ds_read_b128 v[168:171], v151
	ds_read_b128 v[172:175], v151 offset:1024
	ds_read_b128 v[176:179], v151 offset:2048
	ds_read_b128 v[180:183], v151 offset:3072
	s_add_u32 s28, s28, 0x80000
	s_addc_u32 s29, s29, 0
	s_mov_b32 m0, s39
	v_lshl_add_u64 v[224:225], s[28:29], 0, v[128:129]
	ds_read_b128 v[184:187], v149 offset:32768
	ds_read_b128 v[188:191], v149 offset:33792
	ds_read_b128 v[192:195], v149 offset:34816
	ds_read_b128 v[196:199], v149 offset:35840
	ds_read_b128 v[204:207], v149 offset:36864
	ds_read_b128 v[208:211], v149 offset:37888
	ds_read_b128 v[212:215], v149 offset:38912
	ds_read_b128 v[216:219], v149 offset:39936
	global_load_lds_dwordx4 v[224:225], off
	v_lshl_add_u64 v[224:225], s[28:29], 0, v[132:133]
	s_mov_b32 m0, s40
	s_nop 0
	global_load_lds_dwordx4 v[224:225], off
	s_waitcnt vmcnt(8)
	s_waitcnt lgkmcnt(0)
	s_barrier
	s_waitcnt lgkmcnt(0)
	v_mfma_f32_16x16x32_bf16 v[112:115], v[152:155], v[184:187], v[112:115]
	v_mfma_f32_16x16x32_bf16 v[108:111], v[160:163], v[184:187], v[108:111]
	v_mfma_f32_16x16x32_bf16 v[100:103], v[152:155], v[192:195], v[100:103]
	v_mfma_f32_16x16x32_bf16 v[96:99], v[160:163], v[192:195], v[96:99]
	v_mfma_f32_16x16x32_bf16 v[92:95], v[152:155], v[204:207], v[92:95]
	v_mfma_f32_16x16x32_bf16 v[84:87], v[160:163], v[204:207], v[84:87]
	v_mfma_f32_16x16x32_bf16 v[76:79], v[152:155], v[212:215], v[76:79]
	v_mfma_f32_16x16x32_bf16 v[68:71], v[160:163], v[212:215], v[68:71]
	v_mfma_f32_16x16x32_bf16 v[112:115], v[156:159], v[188:191], v[112:115]
	v_mfma_f32_16x16x32_bf16 v[108:111], v[164:167], v[188:191], v[108:111]
	v_mfma_f32_16x16x32_bf16 v[100:103], v[156:159], v[196:199], v[100:103]
	v_mfma_f32_16x16x32_bf16 v[96:99], v[164:167], v[196:199], v[96:99]
	v_mfma_f32_16x16x32_bf16 v[92:95], v[156:159], v[208:211], v[92:95]
	v_mfma_f32_16x16x32_bf16 v[84:87], v[164:167], v[208:211], v[84:87]
	v_mfma_f32_16x16x32_bf16 v[76:79], v[156:159], v[216:219], v[76:79]
	v_mfma_f32_16x16x32_bf16 v[68:71], v[164:167], v[216:219], v[68:71]
	v_mfma_f32_16x16x32_bf16 v[124:127], v[168:171], v[184:187], v[124:127]
	v_mfma_f32_16x16x32_bf16 v[120:123], v[176:179], v[184:187], v[120:123]
	v_mfma_f32_16x16x32_bf16 v[116:119], v[168:171], v[192:195], v[116:119]
	v_mfma_f32_16x16x32_bf16 v[104:107], v[176:179], v[192:195], v[104:107]
	v_mfma_f32_16x16x32_bf16 v[88:91], v[168:171], v[204:207], v[88:91]
	v_mfma_f32_16x16x32_bf16 v[80:83], v[176:179], v[204:207], v[80:83]
	v_mfma_f32_16x16x32_bf16 v[72:75], v[168:171], v[212:215], v[72:75]
	v_mfma_f32_16x16x32_bf16 v[64:67], v[176:179], v[212:215], v[64:67]
	v_mfma_f32_16x16x32_bf16 v[124:127], v[172:175], v[188:191], v[124:127]
	v_mfma_f32_16x16x32_bf16 v[120:123], v[180:183], v[188:191], v[120:123]
	v_mfma_f32_16x16x32_bf16 v[116:119], v[172:175], v[196:199], v[116:119]
	v_mfma_f32_16x16x32_bf16 v[104:107], v[180:183], v[196:199], v[104:107]
	v_mfma_f32_16x16x32_bf16 v[88:91], v[172:175], v[208:211], v[88:91]
	v_mfma_f32_16x16x32_bf16 v[80:83], v[180:183], v[208:211], v[80:83]
	v_mfma_f32_16x16x32_bf16 v[72:75], v[172:175], v[216:219], v[72:75]
	v_mfma_f32_16x16x32_bf16 v[64:67], v[180:183], v[216:219], v[64:67]
	s_barrier
; #define PG8_STAGE(bufoff, gbase, voff) do { _Pragma("unroll") for (int _i = 0; _i < 2; ++_i) \
;         __builtin_amdgcn_global_load_lds((const unsigned*)((const char*)(gbase) + (voff)[_i]), (LAS unsigned*)(lds + (bufoff) + ldsw + _i * 8192), 16, 0, 0); } while (0)
; #define PG8_LDA(dst, b, h) do { _Pragma("unroll") for (int m = 0; m < 4; ++m) _Pragma("unroll") for (int k = 0; k < 2; ++k) dst[m][k] = *(const LAS bf16x8*)(lds + PG8_SA(b, h) + aoff + m * 2048 + k * 1024); } while (0)
; #define PG8_MMA(ai, bj, At, Bt) do { __builtin_amdgcn_s_setprio(1); _Pragma("unroll") for (int m = 0; m < 4; ++m) _Pragma("unroll") for (int n = 0; n < 2; ++n) _Pragma("unroll") for (int k = 0; k < 2; ++k) \
;         acc[ai][bj][m][n] = __builtin_amdgcn_mfma_f32_16x16x32_bf16(Bt[n][k], At[m][k], acc[ai][bj][m][n], 0, 0, 0); __builtin_amdgcn_s_setprio(0); } while (0)
; #define PG8_WAIT_V(n) asm volatile("s_waitcnt vmcnt(" #n ")" ::: "memory")
; #define PG8_WAIT_L(n) asm volatile("s_waitcnt lgkmcnt(" #n ")" ::: "memory")
; #define PG8_BAR __builtin_amdgcn_s_barrier()
; #define PG8_SCHED __builtin_amdgcn_sched_barrier(0)
; template <class Epi, class Sched, bool ALIGN_EPI = true>
; __device__ __forceinline__ void gemm_phase(LAS unsigned char* lds, const Gemm g, const Sched& S, const Epi& E) {
;     ...
;             PG8_LDA(At, 1, 1); PG8_STAGE(PG8_SB(1, 0), b3, voffB); PG8_STAGE(PG8_SB(1, 1), b3 + hstep, voffB); PG8_STAGE(PG8_SA(1, 0), a3, voffA);
;             PG8_WAIT_V(8); PG8_WAIT_L(0); PG8_BAR; PG8_MMA(1, 0, At, B0); PG8_MMA(1, 1, At, B1); PG8_BAR; PG8_SCHED;
;         }
	s_add_i32 s28, s46, s36
	v_lshl_add_u64 v[140:141], v[140:141], 0, s[18:19]
	s_mov_b32 m0, s28
	ds_read_b128 v[184:187], v149 offset:49152
	ds_read_b128 v[188:191], v149 offset:50176
	ds_read_b128 v[192:195], v149 offset:51200
	ds_read_b128 v[196:199], v149 offset:52224
	ds_read_b128 v[204:207], v149 offset:53248
	ds_read_b128 v[208:211], v149 offset:54272
	ds_read_b128 v[212:215], v149 offset:55296
	ds_read_b128 v[216:219], v149 offset:56320
	global_load_lds_dwordx4 v[140:141], off
	s_add_i32 m0, s28, 0x2000
	s_add_u32 s26, s26, 0x80080
	v_lshl_add_u64 v[140:141], v[200:201], 0, s[18:19]
	s_addc_u32 s27, s27, 0
	s_add_i32 s28, s47, s36
	global_load_lds_dwordx4 v[140:141], off
	v_lshl_add_u64 v[140:141], s[26:27], 0, v[130:131]
	s_mov_b32 m0, s28
	s_nop 0
	global_load_lds_dwordx4 v[140:141], off
	v_lshl_add_u64 v[140:141], s[26:27], 0, v[134:135]
	s_add_i32 m0, s28, 0x2000
	s_nop 0
	global_load_lds_dwordx4 v[140:141], off
	v_lshl_add_u64 v[140:141], v[220:221], 0, s[18:19]
	s_mov_b32 m0, s41
	s_nop 0
	global_load_lds_dwordx4 v[140:141], off
	v_lshl_add_u64 v[140:141], v[222:223], 0, s[18:19]
	s_mov_b32 m0, s42
	s_nop 0
	global_load_lds_dwordx4 v[140:141], off
	s_waitcnt vmcnt(8)
	s_waitcnt lgkmcnt(0)
	s_barrier
	s_waitcnt lgkmcnt(0)
	v_mfma_f32_16x16x32_bf16 v[60:63], v[152:155], v[184:187], v[60:63]
	v_mfma_f32_16x16x32_bf16 v[52:55], v[160:163], v[184:187], v[52:55]
	v_mfma_f32_16x16x32_bf16 v[44:47], v[152:155], v[192:195], v[44:47]
	v_mfma_f32_16x16x32_bf16 v[36:39], v[160:163], v[192:195], v[36:39]
	v_mfma_f32_16x16x32_bf16 v[28:31], v[152:155], v[204:207], v[28:31]
	v_mfma_f32_16x16x32_bf16 v[20:23], v[160:163], v[204:207], v[20:23]
	v_mfma_f32_16x16x32_bf16 v[12:15], v[152:155], v[212:215], v[12:15]
	v_mfma_f32_16x16x32_bf16 v[4:7], v[160:163], v[212:215], v[4:7]
	v_mfma_f32_16x16x32_bf16 v[60:63], v[156:159], v[188:191], v[60:63]
	v_mfma_f32_16x16x32_bf16 v[52:55], v[164:167], v[188:191], v[52:55]
	v_mfma_f32_16x16x32_bf16 v[44:47], v[156:159], v[196:199], v[44:47]
	v_mfma_f32_16x16x32_bf16 v[36:39], v[164:167], v[196:199], v[36:39]
	v_mfma_f32_16x16x32_bf16 v[28:31], v[156:159], v[208:211], v[28:31]
	v_mfma_f32_16x16x32_bf16 v[20:23], v[164:167], v[208:211], v[20:23]
	v_mfma_f32_16x16x32_bf16 v[12:15], v[156:159], v[216:219], v[12:15]
	v_mfma_f32_16x16x32_bf16 v[4:7], v[164:167], v[216:219], v[4:7]
	v_mfma_f32_16x16x32_bf16 v[56:59], v[168:171], v[184:187], v[56:59]
	v_mfma_f32_16x16x32_bf16 v[48:51], v[176:179], v[184:187], v[48:51]
	v_mfma_f32_16x16x32_bf16 v[40:43], v[168:171], v[192:195], v[40:43]
	v_mfma_f32_16x16x32_bf16 v[32:35], v[176:179], v[192:195], v[32:35]
	v_mfma_f32_16x16x32_bf16 v[24:27], v[168:171], v[204:207], v[24:27]
	v_mfma_f32_16x16x32_bf16 v[16:19], v[176:179], v[204:207], v[16:19]
	v_mfma_f32_16x16x32_bf16 v[8:11], v[168:171], v[212:215], v[8:11]
	v_mfma_f32_16x16x32_bf16 v[0:3], v[176:179], v[212:215], v[0:3]
	v_mfma_f32_16x16x32_bf16 v[56:59], v[172:175], v[188:191], v[56:59]
	v_mfma_f32_16x16x32_bf16 v[48:51], v[180:183], v[188:191], v[48:51]
	v_mfma_f32_16x16x32_bf16 v[40:43], v[172:175], v[196:199], v[40:43]
	v_mfma_f32_16x16x32_bf16 v[32:35], v[180:183], v[196:199], v[32:35]
	v_mfma_f32_16x16x32_bf16 v[24:27], v[172:175], v[208:211], v[24:27]
	v_mfma_f32_16x16x32_bf16 v[16:19], v[180:183], v[208:211], v[16:19]
	v_mfma_f32_16x16x32_bf16 v[8:11], v[172:175], v[216:219], v[8:11]
	v_mfma_f32_16x16x32_bf16 v[0:3], v[180:183], v[216:219], v[0:3]
	s_barrier
	s_add_i32 s56, s56, 2
	s_add_u32 s24, s24, 0x100
	s_addc_u32 s25, s25, 0
	s_add_u32 s54, s54, 0x100
	s_addc_u32 s55, s55, 0
	s_cmp_gt_u32 s56, 29
	s_cbranch_scc0 .LBB0_647
	s_and_b64 vcc, exec, s[20:21]
	s_cbranch_vccz .LBB0_650
	s_barrier

; #define PG8_STAGE(bufoff, gbase, voff) do { _Pragma("unroll") for (int _i = 0; _i < 2; ++_i) \
;         __builtin_amdgcn_global_load_lds((const unsigned*)((const char*)(gbase) + (voff)[_i]), (LAS unsigned*)(lds + (bufoff) + ldsw + _i * 8192), 16, 0, 0); } while (0)
; #define PG8_LDA(dst, b, h) do { _Pragma("unroll") for (int m = 0; m < 4; ++m) _Pragma("unroll") for (int k = 0; k < 2; ++k) dst[m][k] = *(const LAS bf16x8*)(lds + PG8_SA(b, h) + aoff + m * 2048 + k * 1024); } while (0)
; #define PG8_LDB(dst, b, h) do { _Pragma("unroll") for (int n = 0; n < 2; ++n) _Pragma("unroll") for (int k = 0; k < 2; ++k) dst[n][k] = *(const LAS bf16x8*)(lds + PG8_SB(b, h) + boff + n * 2048 + k * 1024); } while (0)
; #define PG8_MMA(ai, bj, At, Bt) do { __builtin_amdgcn_s_setprio(1); _Pragma("unroll") for (int m = 0; m < 4; ++m) _Pragma("unroll") for (int n = 0; n < 2; ++n) _Pragma("unroll") for (int k = 0; k < 2; ++k) \
;         acc[ai][bj][m][n] = __builtin_amdgcn_mfma_f32_16x16x32_bf16(Bt[n][k], At[m][k], acc[ai][bj][m][n], 0, 0, 0); __builtin_amdgcn_s_setprio(0); } while (0)
; #define PG8_WAIT_V(n) asm volatile("s_waitcnt vmcnt(" #n ")" ::: "memory")
; #define PG8_WAIT_L(n) asm volatile("s_waitcnt lgkmcnt(" #n ")" ::: "memory")
; template <class Epi, class Sched, bool ALIGN_EPI = true>
; __device__ __forceinline__ void gemm_phase(LAS unsigned char* lds, const Gemm g, const Sched& S, const Epi& E) {
;     ...
;     for (;;) {
;         const bool has_next = PG8_NEXT(ui + 1, nxt);
;         const char* nA = has_next ? (const char*)g.A + (size_t)nxt.pm * tstep : cA; const char* nB = has_next ? (const char*)g.Bt + (size_t)nxt.pn * tstep : cB;
;         for (int t = 0; t < nt; t += 2) {
;             const bool last = (t == nt - 2);
;             const char* a1 = cA + (size_t)(t + 1) * kstep;
;             const char* a2 = last ? nA : cA + (size_t)(t + 2) * kstep; const char* b2 = last ? nB : cB + (size_t)(t + 2) * kstep;
;             const char* a3 = a2 + kstep; const char* b3 = b2 + kstep;
;             PG8_LDB(B0, 0, 0); PG8_LDB(B1, 0, 1); PG8_SCHED; PG8_LDA(At, 0, 0); PG8_STAGE(PG8_SA(1, 1), a1 + hstep, voffA);
;             PG8_WAIT_V(8); PG8_WAIT_L(0); PG8_BAR; PG8_MMA(0, 0, At, B0); PG8_MMA(0, 1, At, B1); PG8_BAR; PG8_SCHED;
;             PG8_LDA(At, 0, 1); PG8_STAGE(PG8_SB(0, 0), b2, voffB); PG8_STAGE(PG8_SB(0, 1), b2 + hstep, voffB); PG8_STAGE(PG8_SA(0, 0), a2, voffA);
.LBB0_667:
	v_readlane_b32 s14, v137, s56
	ds_read_b128 v[0:3], v140
	ds_read_b128 v[4:7], v140 offset:1024
	ds_read_b128 v[8:11], v140 offset:2048
	ds_read_b128 v[12:15], v140 offset:3072
	ds_read_b128 v[16:19], v141
	ds_read_b128 v[20:23], v141 offset:1024
	ds_read_b128 v[24:27], v141 offset:2048
	ds_read_b128 v[28:31], v141 offset:3072
	s_cmp_gt_i32 s14, -1
	s_mov_b64 s[48:49], s[6:7]
	s_cselect_b64 s[38:39], -1, 0
	s_lshl_b64 s[6:7], s[14:15], 17
	s_add_u32 s36, s3, s6
	s_addc_u32 s37, s50, s7
	v_readlane_b32 s34, v136, s56
	s_and_b64 s[6:7], s[38:39], exec
	s_cselect_b32 s45, s37, s43
	s_cselect_b32 s44, s36, s42
	s_ashr_i32 s35, s34, 31
	s_lshl_b64 s[6:7], s[34:35], 17
	s_add_u32 s6, s51, s6
	s_addc_u32 s7, s52, s7
	s_and_b64 s[40:41], s[38:39], exec
	s_cselect_b32 s41, s7, s49
	s_cselect_b32 s40, s6, s48
	s_add_u32 s46, s42, 0x10080
	s_addc_u32 s47, s43, 0
	s_mov_b32 m0, s59
	v_lshl_add_u64 v[64:65], s[46:47], 0, v[128:129]
	ds_read_b128 v[32:35], v142
	ds_read_b128 v[36:39], v142 offset:1024
	ds_read_b128 v[40:43], v142 offset:2048
	ds_read_b128 v[44:47], v142 offset:3072
	ds_read_b128 v[48:51], v142 offset:4096
	ds_read_b128 v[52:55], v142 offset:5120
	ds_read_b128 v[56:59], v142 offset:6144
	ds_read_b128 v[60:63], v142 offset:7168
	global_load_lds_dwordx4 v[64:65], off
	v_lshl_add_u64 v[64:65], s[46:47], 0, v[132:133]
	s_mov_b32 m0, s60
	s_nop 0
	global_load_lds_dwordx4 v[64:65], off
	s_waitcnt vmcnt(8)
	s_waitcnt lgkmcnt(0)
	s_barrier
	s_waitcnt lgkmcnt(0)
	v_mfma_f32_16x16x32_bf16 v[64:67], v[0:3], v[32:35], 0
	v_mfma_f32_16x16x32_bf16 v[68:71], v[8:11], v[32:35], 0
	v_mfma_f32_16x16x32_bf16 v[72:75], v[0:3], v[40:43], 0
	v_mfma_f32_16x16x32_bf16 v[76:79], v[8:11], v[40:43], 0
	v_mfma_f32_16x16x32_bf16 v[80:83], v[0:3], v[48:51], 0
	v_mfma_f32_16x16x32_bf16 v[84:87], v[8:11], v[48:51], 0
	v_mfma_f32_16x16x32_bf16 v[88:91], v[0:3], v[56:59], 0
	v_mfma_f32_16x16x32_bf16 v[92:95], v[8:11], v[56:59], 0
	v_mfma_f32_16x16x32_bf16 v[64:67], v[4:7], v[36:39], v[64:67]
	v_mfma_f32_16x16x32_bf16 v[68:71], v[12:15], v[36:39], v[68:71]
	v_mfma_f32_16x16x32_bf16 v[72:75], v[4:7], v[44:47], v[72:75]
	v_mfma_f32_16x16x32_bf16 v[76:79], v[12:15], v[44:47], v[76:79]
	v_mfma_f32_16x16x32_bf16 v[80:83], v[4:7], v[52:55], v[80:83]
	v_mfma_f32_16x16x32_bf16 v[84:87], v[12:15], v[52:55], v[84:87]
	v_mfma_f32_16x16x32_bf16 v[88:91], v[4:7], v[60:63], v[88:91]
	v_mfma_f32_16x16x32_bf16 v[92:95], v[12:15], v[60:63], v[92:95]
	v_mfma_f32_16x16x32_bf16 v[96:99], v[16:19], v[32:35], 0
	v_mfma_f32_16x16x32_bf16 v[32:35], v[24:27], v[32:35], 0
	v_mfma_f32_16x16x32_bf16 v[96:99], v[20:23], v[36:39], v[96:99]
	v_mfma_f32_16x16x32_bf16 v[32:35], v[28:31], v[36:39], v[32:35]
	v_mfma_f32_16x16x32_bf16 v[36:39], v[16:19], v[40:43], 0
	v_mfma_f32_16x16x32_bf16 v[40:43], v[24:27], v[40:43], 0
	v_mfma_f32_16x16x32_bf16 v[36:39], v[20:23], v[44:47], v[36:39]
	v_mfma_f32_16x16x32_bf16 v[40:43], v[28:31], v[44:47], v[40:43]
	v_mfma_f32_16x16x32_bf16 v[44:47], v[16:19], v[48:51], 0
	v_mfma_f32_16x16x32_bf16 v[48:51], v[24:27], v[48:51], 0
	v_mfma_f32_16x16x32_bf16 v[44:47], v[20:23], v[52:55], v[44:47]
	v_mfma_f32_16x16x32_bf16 v[48:51], v[28:31], v[52:55], v[48:51]
	v_mfma_f32_16x16x32_bf16 v[52:55], v[16:19], v[56:59], 0
	v_mfma_f32_16x16x32_bf16 v[56:59], v[24:27], v[56:59], 0
	v_mfma_f32_16x16x32_bf16 v[52:55], v[20:23], v[60:63], v[52:55]
	v_mfma_f32_16x16x32_bf16 v[56:59], v[28:31], v[60:63], v[56:59]
	s_barrier
	v_lshl_add_u64 v[212:213], s[48:49], 0, v[130:131]
	s_mov_b32 m0, s61
	v_lshl_add_u64 v[146:147], v[212:213], 0, s[16:17]
	v_lshl_add_u64 v[214:215], s[48:49], 0, v[134:135]
	s_add_u32 s46, s48, 0x10100
	ds_read_b128 v[60:63], v142 offset:16384
	ds_read_b128 v[100:103], v142 offset:17408
	ds_read_b128 v[104:107], v142 offset:18432
	ds_read_b128 v[108:111], v142 offset:19456
	ds_read_b128 v[112:115], v142 offset:20480
	ds_read_b128 v[116:119], v142 offset:21504
	ds_read_b128 v[120:123], v142 offset:22528
	ds_read_b128 v[124:127], v142 offset:23552
	global_load_lds_dwordx4 v[146:147], off
	v_lshl_add_u64 v[146:147], v[214:215], 0, s[16:17]
	s_mov_b32 m0, s62
	s_addc_u32 s47, s49, 0
	global_load_lds_dwordx4 v[146:147], off
	v_lshl_add_u64 v[146:147], s[46:47], 0, v[130:131]
	s_mov_b32 m0, s63
	v_lshl_add_u64 v[216:217], s[42:43], 0, v[128:129]
	global_load_lds_dwordx4 v[146:147], off
	v_lshl_add_u64 v[146:147], s[46:47], 0, v[134:135]
	s_mov_b32 m0, s76
	v_lshl_add_u64 v[218:219], s[42:43], 0, v[132:133]
	global_load_lds_dwordx4 v[146:147], off
	v_lshl_add_u64 v[146:147], v[216:217], 0, s[16:17]
	s_mov_b32 m0, s23
	s_nop 0
	global_load_lds_dwordx4 v[146:147], off
	v_lshl_add_u64 v[146:147], v[218:219], 0, s[16:17]
	s_mov_b32 m0, s53
	s_nop 0
	global_load_lds_dwordx4 v[146:147], off
	s_waitcnt vmcnt(8)
	s_waitcnt lgkmcnt(0)
	s_barrier
; #define PG8_STAGE(bufoff, gbase, voff) do { _Pragma("unroll") for (int _i = 0; _i < 2; ++_i) \
;         __builtin_amdgcn_global_load_lds((const unsigned*)((const char*)(gbase) + (voff)[_i]), (LAS unsigned*)(lds + (bufoff) + ldsw + _i * 8192), 16, 0, 0); } while (0)
; #define PG8_LDA(dst, b, h) do { _Pragma("unroll") for (int m = 0; m < 4; ++m) _Pragma("unroll") for (int k = 0; k < 2; ++k) dst[m][k] = *(const LAS bf16x8*)(lds + PG8_SA(b, h) + aoff + m * 2048 + k * 1024); } while (0)
; #define PG8_LDB(dst, b, h) do { _Pragma("unroll") for (int n = 0; n < 2; ++n) _Pragma("unroll") for (int k = 0; k < 2; ++k) dst[n][k] = *(const LAS bf16x8*)(lds + PG8_SB(b, h) + boff + n * 2048 + k * 1024); } while (0)
; #define PG8_MMA(ai, bj, At, Bt) do { __builtin_amdgcn_s_setprio(1); _Pragma("unroll") for (int m = 0; m < 4; ++m) _Pragma("unroll") for (int n = 0; n < 2; ++n) _Pragma("unroll") for (int k = 0; k < 2; ++k) \
;         acc[ai][bj][m][n] = __builtin_amdgcn_mfma_f32_16x16x32_bf16(Bt[n][k], At[m][k], acc[ai][bj][m][n], 0, 0, 0); __builtin_amdgcn_s_setprio(0); } while (0)
; #define PG8_WAIT_V(n) asm volatile("s_waitcnt vmcnt(" #n ")" ::: "memory")
; #define PG8_WAIT_L(n) asm volatile("s_waitcnt lgkmcnt(" #n ")" ::: "memory")
; #define PG8_BAR __builtin_amdgcn_s_barrier()
; #define PG8_SCHED __builtin_amdgcn_sched_barrier(0)
; template <class Epi, class Sched, bool ALIGN_EPI = true>
; __device__ __forceinline__ void gemm_phase(LAS unsigned char* lds, const Gemm g, const Sched& S, const Epi& E) {
;     ...
;             PG8_WAIT_V(8); PG8_WAIT_L(0); PG8_BAR; PG8_MMA(1, 0, At, B0); PG8_MMA(1, 1, At, B1); PG8_BAR; PG8_SCHED;
;             PG8_LDB(B0, 1, 0); PG8_LDB(B1, 1, 1); PG8_SCHED; PG8_LDA(At, 1, 0); PG8_STAGE(PG8_SA(0, 1), a2 + hstep, voffA);
;             PG8_WAIT_V(8); PG8_WAIT_L(0); PG8_BAR; PG8_MMA(0, 0, At, B0); PG8_MMA(0, 1, At, B1); PG8_BAR; PG8_SCHED;
;             PG8_LDA(At, 1, 1); PG8_STAGE(PG8_SB(1, 0), b3, voffB); PG8_STAGE(PG8_SB(1, 1), b3 + hstep, voffB); PG8_STAGE(PG8_SA(1, 0), a3, voffA);
	s_waitcnt lgkmcnt(0)
	v_mfma_f32_16x16x32_bf16 v[146:149], v[0:3], v[60:63], 0
	v_mfma_f32_16x16x32_bf16 v[154:157], v[0:3], v[104:107], 0
	v_mfma_f32_16x16x32_bf16 v[162:165], v[0:3], v[112:115], 0
	v_mfma_f32_16x16x32_bf16 v[0:3], v[0:3], v[120:123], 0
	v_mfma_f32_16x16x32_bf16 v[146:149], v[4:7], v[100:103], v[146:149]
	v_mfma_f32_16x16x32_bf16 v[154:157], v[4:7], v[108:111], v[154:157]
	v_mfma_f32_16x16x32_bf16 v[162:165], v[4:7], v[116:119], v[162:165]
	v_mfma_f32_16x16x32_bf16 v[0:3], v[4:7], v[124:127], v[0:3]
	v_mfma_f32_16x16x32_bf16 v[4:7], v[8:11], v[120:123], 0
	v_mfma_f32_16x16x32_bf16 v[150:153], v[8:11], v[60:63], 0
	v_mfma_f32_16x16x32_bf16 v[158:161], v[8:11], v[104:107], 0
	v_mfma_f32_16x16x32_bf16 v[166:169], v[8:11], v[112:115], 0
	v_mfma_f32_16x16x32_bf16 v[4:7], v[12:15], v[124:127], v[4:7]
	v_mfma_f32_16x16x32_bf16 v[150:153], v[12:15], v[100:103], v[150:153]
	v_mfma_f32_16x16x32_bf16 v[158:161], v[12:15], v[108:111], v[158:161]
	v_mfma_f32_16x16x32_bf16 v[166:169], v[12:15], v[116:119], v[166:169]
	v_mfma_f32_16x16x32_bf16 v[8:11], v[16:19], v[60:63], 0
	v_mfma_f32_16x16x32_bf16 v[12:15], v[24:27], v[60:63], 0
	v_mfma_f32_16x16x32_bf16 v[8:11], v[20:23], v[100:103], v[8:11]
	v_mfma_f32_16x16x32_bf16 v[12:15], v[28:31], v[100:103], v[12:15]
	v_mfma_f32_16x16x32_bf16 v[60:63], v[16:19], v[104:107], 0
	v_mfma_f32_16x16x32_bf16 v[100:103], v[24:27], v[104:107], 0
	v_mfma_f32_16x16x32_bf16 v[104:107], v[16:19], v[112:115], 0
	v_mfma_f32_16x16x32_bf16 v[16:19], v[16:19], v[120:123], 0
	v_mfma_f32_16x16x32_bf16 v[60:63], v[20:23], v[108:111], v[60:63]
	v_mfma_f32_16x16x32_bf16 v[100:103], v[28:31], v[108:111], v[100:103]
	v_mfma_f32_16x16x32_bf16 v[104:107], v[20:23], v[116:119], v[104:107]
	v_mfma_f32_16x16x32_bf16 v[108:111], v[24:27], v[112:115], 0
	v_mfma_f32_16x16x32_bf16 v[16:19], v[20:23], v[124:127], v[16:19]
	v_mfma_f32_16x16x32_bf16 v[20:23], v[24:27], v[120:123], 0
	v_mfma_f32_16x16x32_bf16 v[108:111], v[28:31], v[116:119], v[108:111]
	v_mfma_f32_16x16x32_bf16 v[20:23], v[28:31], v[124:127], v[20:23]
	s_barrier
	ds_read_b128 v[24:27], v143
	ds_read_b128 v[28:31], v143 offset:1024
	ds_read_b128 v[112:115], v143 offset:2048
	ds_read_b128 v[116:119], v143 offset:3072
	ds_read_b128 v[120:123], v144
	ds_read_b128 v[124:127], v144 offset:1024
	ds_read_b128 v[170:173], v144 offset:2048
	ds_read_b128 v[174:177], v144 offset:3072
	s_add_u32 s46, s42, 0x10100
	s_addc_u32 s47, s43, 0
	s_mov_b32 m0, s54
	v_lshl_add_u64 v[220:221], s[46:47], 0, v[128:129]
	ds_read_b128 v[178:181], v142 offset:32768
	ds_read_b128 v[182:185], v142 offset:33792
	ds_read_b128 v[186:189], v142 offset:34816
	ds_read_b128 v[190:193], v142 offset:35840
	ds_read_b128 v[194:197], v142 offset:36864
	ds_read_b128 v[198:201], v142 offset:37888
	ds_read_b128 v[204:207], v142 offset:38912
	ds_read_b128 v[208:211], v142 offset:39936
	global_load_lds_dwordx4 v[220:221], off
	v_lshl_add_u64 v[220:221], s[46:47], 0, v[132:133]
	s_mov_b32 m0, s55
	s_nop 0
	global_load_lds_dwordx4 v[220:221], off
	s_waitcnt vmcnt(8)
	s_waitcnt lgkmcnt(0)
	s_barrier
	s_waitcnt lgkmcnt(0)
	v_mfma_f32_16x16x32_bf16 v[64:67], v[24:27], v[178:181], v[64:67]
	v_mfma_f32_16x16x32_bf16 v[68:71], v[112:115], v[178:181], v[68:71]
	v_mfma_f32_16x16x32_bf16 v[72:75], v[24:27], v[186:189], v[72:75]
	v_mfma_f32_16x16x32_bf16 v[76:79], v[112:115], v[186:189], v[76:79]
	v_mfma_f32_16x16x32_bf16 v[80:83], v[24:27], v[194:197], v[80:83]
	v_mfma_f32_16x16x32_bf16 v[84:87], v[112:115], v[194:197], v[84:87]
	v_mfma_f32_16x16x32_bf16 v[88:91], v[24:27], v[204:207], v[88:91]
	v_mfma_f32_16x16x32_bf16 v[92:95], v[112:115], v[204:207], v[92:95]
	v_mfma_f32_16x16x32_bf16 v[64:67], v[28:31], v[182:185], v[64:67]
	v_mfma_f32_16x16x32_bf16 v[68:71], v[116:119], v[182:185], v[68:71]
	v_mfma_f32_16x16x32_bf16 v[72:75], v[28:31], v[190:193], v[72:75]
	v_mfma_f32_16x16x32_bf16 v[76:79], v[116:119], v[190:193], v[76:79]
	v_mfma_f32_16x16x32_bf16 v[80:83], v[28:31], v[198:201], v[80:83]
	v_mfma_f32_16x16x32_bf16 v[84:87], v[116:119], v[198:201], v[84:87]
	v_mfma_f32_16x16x32_bf16 v[88:91], v[28:31], v[208:211], v[88:91]
	v_mfma_f32_16x16x32_bf16 v[92:95], v[116:119], v[208:211], v[92:95]
	v_mfma_f32_16x16x32_bf16 v[96:99], v[120:123], v[178:181], v[96:99]
	v_mfma_f32_16x16x32_bf16 v[32:35], v[170:173], v[178:181], v[32:35]
	v_mfma_f32_16x16x32_bf16 v[36:39], v[120:123], v[186:189], v[36:39]
	v_mfma_f32_16x16x32_bf16 v[40:43], v[170:173], v[186:189], v[40:43]
	v_mfma_f32_16x16x32_bf16 v[44:47], v[120:123], v[194:197], v[44:47]
	v_mfma_f32_16x16x32_bf16 v[48:51], v[170:173], v[194:197], v[48:51]
	v_mfma_f32_16x16x32_bf16 v[52:55], v[120:123], v[204:207], v[52:55]
	v_mfma_f32_16x16x32_bf16 v[56:59], v[170:173], v[204:207], v[56:59]
	v_mfma_f32_16x16x32_bf16 v[96:99], v[124:127], v[182:185], v[96:99]
	v_mfma_f32_16x16x32_bf16 v[32:35], v[174:177], v[182:185], v[32:35]
	v_mfma_f32_16x16x32_bf16 v[36:39], v[124:127], v[190:193], v[36:39]
	v_mfma_f32_16x16x32_bf16 v[40:43], v[174:177], v[190:193], v[40:43]
	v_mfma_f32_16x16x32_bf16 v[44:47], v[124:127], v[198:201], v[44:47]
	v_mfma_f32_16x16x32_bf16 v[48:51], v[174:177], v[198:201], v[48:51]
	v_mfma_f32_16x16x32_bf16 v[52:55], v[124:127], v[208:211], v[52:55]
	v_mfma_f32_16x16x32_bf16 v[56:59], v[174:177], v[208:211], v[56:59]
	s_barrier
; #define PG8_STAGE(bufoff, gbase, voff) do { _Pragma("unroll") for (int _i = 0; _i < 2; ++_i) \
;         __builtin_amdgcn_global_load_lds((const unsigned*)((const char*)(gbase) + (voff)[_i]), (LAS unsigned*)(lds + (bufoff) + ldsw + _i * 8192), 16, 0, 0); } while (0)
; #define PG8_LDA(dst, b, h) do { _Pragma("unroll") for (int m = 0; m < 4; ++m) _Pragma("unroll") for (int k = 0; k < 2; ++k) dst[m][k] = *(const LAS bf16x8*)(lds + PG8_SA(b, h) + aoff + m * 2048 + k * 1024); } while (0)
; #define PG8_LDB(dst, b, h) do { _Pragma("unroll") for (int n = 0; n < 2; ++n) _Pragma("unroll") for (int k = 0; k < 2; ++k) dst[n][k] = *(const LAS bf16x8*)(lds + PG8_SB(b, h) + boff + n * 2048 + k * 1024); } while (0)
; #define PG8_MMA(ai, bj, At, Bt) do { __builtin_amdgcn_s_setprio(1); _Pragma("unroll") for (int m = 0; m < 4; ++m) _Pragma("unroll") for (int n = 0; n < 2; ++n) _Pragma("unroll") for (int k = 0; k < 2; ++k) \
;         acc[ai][bj][m][n] = __builtin_amdgcn_mfma_f32_16x16x32_bf16(Bt[n][k], At[m][k], acc[ai][bj][m][n], 0, 0, 0); __builtin_amdgcn_s_setprio(0); } while (0)
; #define PG8_WAIT_V(n) asm volatile("s_waitcnt vmcnt(" #n ")" ::: "memory")
; template <class Epi, class Sched, bool ALIGN_EPI = true>
; __device__ __forceinline__ void gemm_phase(LAS unsigned char* lds, const Gemm g, const Sched& S, const Epi& E) {
;     ...
;             PG8_LDB(B0, 0, 0); PG8_LDB(B1, 0, 1); PG8_SCHED; PG8_LDA(At, 0, 0); PG8_STAGE(PG8_SA(1, 1), a1 + hstep, voffA);
;             PG8_WAIT_V(8); PG8_WAIT_L(0); PG8_BAR; PG8_MMA(0, 0, At, B0); PG8_MMA(0, 1, At, B1); PG8_BAR; PG8_SCHED;
;             PG8_LDA(At, 0, 1); PG8_STAGE(PG8_SB(0, 0), b2, voffB); PG8_STAGE(PG8_SB(0, 1), b2 + hstep, voffB); PG8_STAGE(PG8_SA(0, 0), a2, voffA);
;             PG8_WAIT_V(8); PG8_WAIT_L(0); PG8_BAR; PG8_MMA(1, 0, At, B0); PG8_MMA(1, 1, At, B1); PG8_BAR; PG8_SCHED;
;             PG8_LDB(B0, 1, 0); PG8_LDB(B1, 1, 1); PG8_SCHED; PG8_LDA(At, 1, 0); PG8_STAGE(PG8_SA(0, 1), a2 + hstep, voffA);
;             PG8_WAIT_V(8); PG8_WAIT_L(0); PG8_BAR; PG8_MMA(0, 0, At, B0); PG8_MMA(0, 1, At, B1); PG8_BAR; PG8_SCHED;
;             PG8_LDA(At, 1, 1); PG8_STAGE(PG8_SB(1, 0), b3, voffB); PG8_STAGE(PG8_SB(1, 1), b3 + hstep, voffB); PG8_STAGE(PG8_SA(1, 0), a3, voffA);
;             PG8_WAIT_V(8); PG8_WAIT_L(0); PG8_BAR; PG8_MMA(1, 0, At, B0); PG8_MMA(1, 1, At, B1); PG8_BAR; PG8_SCHED;
	s_mov_b32 m0, s77
	v_lshl_add_u64 v[212:213], v[212:213], 0, s[18:19]
	s_add_u32 s46, s48, 0x10180
	ds_read_b128 v[178:181], v142 offset:49152
	ds_read_b128 v[182:185], v142 offset:50176
	ds_read_b128 v[186:189], v142 offset:51200
	ds_read_b128 v[190:193], v142 offset:52224
	ds_read_b128 v[194:197], v142 offset:53248
	ds_read_b128 v[198:201], v142 offset:54272
	ds_read_b128 v[204:207], v142 offset:55296
	ds_read_b128 v[208:211], v142 offset:56320
	global_load_lds_dwordx4 v[212:213], off
	v_lshl_add_u64 v[212:213], v[214:215], 0, s[18:19]
	s_mov_b32 m0, s78
	s_addc_u32 s47, s49, 0
	global_load_lds_dwordx4 v[212:213], off
	v_lshl_add_u64 v[212:213], s[46:47], 0, v[130:131]
	s_mov_b32 m0, s79
	s_nop 0
	global_load_lds_dwordx4 v[212:213], off
	v_lshl_add_u64 v[212:213], s[46:47], 0, v[134:135]
	s_mov_b32 m0, s80
	s_nop 0
	global_load_lds_dwordx4 v[212:213], off
	v_lshl_add_u64 v[212:213], v[216:217], 0, s[18:19]
	s_mov_b32 m0, s57
	s_nop 0
	global_load_lds_dwordx4 v[212:213], off
	v_lshl_add_u64 v[212:213], v[218:219], 0, s[18:19]
	s_mov_b32 m0, s58
	s_nop 0
	global_load_lds_dwordx4 v[212:213], off
	s_waitcnt vmcnt(8)
	s_waitcnt lgkmcnt(0)
	s_barrier
	s_waitcnt lgkmcnt(0)
	v_mfma_f32_16x16x32_bf16 v[0:3], v[24:27], v[204:207], v[0:3]
	v_mfma_f32_16x16x32_bf16 v[4:7], v[112:115], v[204:207], v[4:7]
	v_mfma_f32_16x16x32_bf16 v[146:149], v[24:27], v[178:181], v[146:149]
	v_mfma_f32_16x16x32_bf16 v[150:153], v[112:115], v[178:181], v[150:153]
	v_mfma_f32_16x16x32_bf16 v[154:157], v[24:27], v[186:189], v[154:157]
	v_mfma_f32_16x16x32_bf16 v[158:161], v[112:115], v[186:189], v[158:161]
	v_mfma_f32_16x16x32_bf16 v[162:165], v[24:27], v[194:197], v[162:165]
	v_mfma_f32_16x16x32_bf16 v[166:169], v[112:115], v[194:197], v[166:169]
	v_mfma_f32_16x16x32_bf16 v[0:3], v[28:31], v[208:211], v[0:3]
	v_mfma_f32_16x16x32_bf16 v[4:7], v[116:119], v[208:211], v[4:7]
	v_mfma_f32_16x16x32_bf16 v[146:149], v[28:31], v[182:185], v[146:149]
	v_mfma_f32_16x16x32_bf16 v[150:153], v[116:119], v[182:185], v[150:153]
	v_mfma_f32_16x16x32_bf16 v[154:157], v[28:31], v[190:193], v[154:157]
	v_mfma_f32_16x16x32_bf16 v[158:161], v[116:119], v[190:193], v[158:161]
	v_mfma_f32_16x16x32_bf16 v[162:165], v[28:31], v[198:201], v[162:165]
	v_mfma_f32_16x16x32_bf16 v[166:169], v[116:119], v[198:201], v[166:169]
	v_mfma_f32_16x16x32_bf16 v[8:11], v[120:123], v[178:181], v[8:11]
	v_mfma_f32_16x16x32_bf16 v[12:15], v[170:173], v[178:181], v[12:15]
	v_mfma_f32_16x16x32_bf16 v[24:27], v[120:123], v[186:189], v[60:63]
	v_mfma_f32_16x16x32_bf16 v[28:31], v[170:173], v[186:189], v[100:103]
	v_mfma_f32_16x16x32_bf16 v[60:63], v[120:123], v[194:197], v[104:107]
	v_mfma_f32_16x16x32_bf16 v[100:103], v[170:173], v[194:197], v[108:111]
	v_mfma_f32_16x16x32_bf16 v[16:19], v[120:123], v[204:207], v[16:19]
	v_mfma_f32_16x16x32_bf16 v[20:23], v[170:173], v[204:207], v[20:23]
	v_mfma_f32_16x16x32_bf16 v[8:11], v[124:127], v[182:185], v[8:11]
	v_mfma_f32_16x16x32_bf16 v[12:15], v[174:177], v[182:185], v[12:15]
	v_mfma_f32_16x16x32_bf16 v[24:27], v[124:127], v[190:193], v[24:27]
	v_mfma_f32_16x16x32_bf16 v[28:31], v[174:177], v[190:193], v[28:31]
	v_mfma_f32_16x16x32_bf16 v[60:63], v[124:127], v[198:201], v[60:63]
	v_mfma_f32_16x16x32_bf16 v[100:103], v[174:177], v[198:201], v[100:103]
	v_mfma_f32_16x16x32_bf16 v[16:19], v[124:127], v[208:211], v[16:19]
	v_mfma_f32_16x16x32_bf16 v[20:23], v[174:177], v[208:211], v[20:23]
	s_barrier
	ds_read_b128 v[104:107], v140
	ds_read_b128 v[108:111], v140 offset:1024
	ds_read_b128 v[112:115], v140 offset:2048
	ds_read_b128 v[116:119], v140 offset:3072
	ds_read_b128 v[120:123], v141
	ds_read_b128 v[124:127], v141 offset:1024
	ds_read_b128 v[170:173], v141 offset:2048
	ds_read_b128 v[174:177], v141 offset:3072
	s_add_u32 s42, s42, 0x10180
	s_addc_u32 s43, s43, 0
	s_mov_b32 m0, s59
	v_lshl_add_u64 v[212:213], s[42:43], 0, v[128:129]
	ds_read_b128 v[178:181], v142
	ds_read_b128 v[182:185], v142 offset:1024
	ds_read_b128 v[186:189], v142 offset:2048
	ds_read_b128 v[190:193], v142 offset:3072
	ds_read_b128 v[194:197], v142 offset:4096
	ds_read_b128 v[198:201], v142 offset:5120
	ds_read_b128 v[204:207], v142 offset:6144
	ds_read_b128 v[208:211], v142 offset:7168
	global_load_lds_dwordx4 v[212:213], off
	v_lshl_add_u64 v[212:213], s[42:43], 0, v[132:133]
	s_mov_b32 m0, s60
	s_nop 0
	global_load_lds_dwordx4 v[212:213], off
	s_waitcnt vmcnt(8)
	s_waitcnt lgkmcnt(0)
	s_barrier
	s_waitcnt lgkmcnt(0)
	v_mfma_f32_16x16x32_bf16 v[64:67], v[104:107], v[178:181], v[64:67]
	v_mfma_f32_16x16x32_bf16 v[68:71], v[112:115], v[178:181], v[68:71]
	v_mfma_f32_16x16x32_bf16 v[72:75], v[104:107], v[186:189], v[72:75]
	v_mfma_f32_16x16x32_bf16 v[76:79], v[112:115], v[186:189], v[76:79]
	v_mfma_f32_16x16x32_bf16 v[80:83], v[104:107], v[194:197], v[80:83]
	v_mfma_f32_16x16x32_bf16 v[84:87], v[112:115], v[194:197], v[84:87]
	v_mfma_f32_16x16x32_bf16 v[88:91], v[104:107], v[204:207], v[88:91]
	v_mfma_f32_16x16x32_bf16 v[92:95], v[112:115], v[204:207], v[92:95]
	v_mfma_f32_16x16x32_bf16 v[64:67], v[108:111], v[182:185], v[64:67]
	v_mfma_f32_16x16x32_bf16 v[68:71], v[116:119], v[182:185], v[68:71]
	v_mfma_f32_16x16x32_bf16 v[72:75], v[108:111], v[190:193], v[72:75]
	v_mfma_f32_16x16x32_bf16 v[76:79], v[116:119], v[190:193], v[76:79]
	v_mfma_f32_16x16x32_bf16 v[80:83], v[108:111], v[198:201], v[80:83]
	v_mfma_f32_16x16x32_bf16 v[84:87], v[116:119], v[198:201], v[84:87]
	v_mfma_f32_16x16x32_bf16 v[88:91], v[108:111], v[208:211], v[88:91]
	v_mfma_f32_16x16x32_bf16 v[92:95], v[116:119], v[208:211], v[92:95]
	v_mfma_f32_16x16x32_bf16 v[32:35], v[170:173], v[178:181], v[32:35]
	v_mfma_f32_16x16x32_bf16 v[36:39], v[120:123], v[186:189], v[36:39]
	v_mfma_f32_16x16x32_bf16 v[40:43], v[170:173], v[186:189], v[40:43]
	v_mfma_f32_16x16x32_bf16 v[44:47], v[120:123], v[194:197], v[44:47]
	v_mfma_f32_16x16x32_bf16 v[48:51], v[170:173], v[194:197], v[48:51]
	v_mfma_f32_16x16x32_bf16 v[52:55], v[120:123], v[204:207], v[52:55]
	v_mfma_f32_16x16x32_bf16 v[56:59], v[170:173], v[204:207], v[56:59]
	v_mfma_f32_16x16x32_bf16 v[96:99], v[120:123], v[178:181], v[96:99]
	v_mfma_f32_16x16x32_bf16 v[32:35], v[174:177], v[182:185], v[32:35]
	v_mfma_f32_16x16x32_bf16 v[36:39], v[124:127], v[190:193], v[36:39]
	v_mfma_f32_16x16x32_bf16 v[40:43], v[174:177], v[190:193], v[40:43]
	v_mfma_f32_16x16x32_bf16 v[44:47], v[124:127], v[198:201], v[44:47]
	v_mfma_f32_16x16x32_bf16 v[48:51], v[174:177], v[198:201], v[48:51]
	v_mfma_f32_16x16x32_bf16 v[52:55], v[124:127], v[208:211], v[52:55]
	v_mfma_f32_16x16x32_bf16 v[56:59], v[174:177], v[208:211], v[56:59]
	v_mfma_f32_16x16x32_bf16 v[212:215], v[124:127], v[182:185], v[96:99]
	s_barrier
; #define PG8_STAGE(bufoff, gbase, voff) do { _Pragma("unroll") for (int _i = 0; _i < 2; ++_i) \
;         __builtin_amdgcn_global_load_lds((const unsigned*)((const char*)(gbase) + (voff)[_i]), (LAS unsigned*)(lds + (bufoff) + ldsw + _i * 8192), 16, 0, 0); } while (0)
; #define PG8_LDA(dst, b, h) do { _Pragma("unroll") for (int m = 0; m < 4; ++m) _Pragma("unroll") for (int k = 0; k < 2; ++k) dst[m][k] = *(const LAS bf16x8*)(lds + PG8_SA(b, h) + aoff + m * 2048 + k * 1024); } while (0)
; #define PG8_LDB(dst, b, h) do { _Pragma("unroll") for (int n = 0; n < 2; ++n) _Pragma("unroll") for (int k = 0; k < 2; ++k) dst[n][k] = *(const LAS bf16x8*)(lds + PG8_SB(b, h) + boff + n * 2048 + k * 1024); } while (0)
; #define PG8_MMA(ai, bj, At, Bt) do { __builtin_amdgcn_s_setprio(1); _Pragma("unroll") for (int m = 0; m < 4; ++m) _Pragma("unroll") for (int n = 0; n < 2; ++n) _Pragma("unroll") for (int k = 0; k < 2; ++k) \
;         acc[ai][bj][m][n] = __builtin_amdgcn_mfma_f32_16x16x32_bf16(Bt[n][k], At[m][k], acc[ai][bj][m][n], 0, 0, 0); __builtin_amdgcn_s_setprio(0); } while (0)
; #define PG8_WAIT_V(n) asm volatile("s_waitcnt vmcnt(" #n ")" ::: "memory")
; #define PG8_WAIT_L(n) asm volatile("s_waitcnt lgkmcnt(" #n ")" ::: "memory")
; #define PG8_BAR __builtin_amdgcn_s_barrier()
; #define PG8_SCHED __builtin_amdgcn_sched_barrier(0)
; template <class Epi, class Sched, bool ALIGN_EPI = true>
; __device__ __forceinline__ void gemm_phase(LAS unsigned char* lds, const Gemm g, const Sched& S, const Epi& E) {
;     ...
;             PG8_LDA(At, 0, 1); PG8_STAGE(PG8_SB(0, 0), b2, voffB); PG8_STAGE(PG8_SB(0, 1), b2 + hstep, voffB); PG8_STAGE(PG8_SA(0, 0), a2, voffA);
;             PG8_WAIT_V(8); PG8_WAIT_L(0); PG8_BAR; PG8_MMA(1, 0, At, B0); PG8_MMA(1, 1, At, B1); PG8_BAR; PG8_SCHED;
;             PG8_LDB(B0, 1, 0); PG8_LDB(B1, 1, 1); PG8_SCHED; PG8_LDA(At, 1, 0); PG8_STAGE(PG8_SA(0, 1), a2 + hstep, voffA);
;             PG8_WAIT_V(8); PG8_WAIT_L(0); PG8_BAR; PG8_MMA(0, 0, At, B0); PG8_MMA(0, 1, At, B1); PG8_BAR; PG8_SCHED;
	s_mov_b32 m0, s61
	v_lshl_add_u64 v[248:249], s[40:41], 0, v[130:131]
	s_add_u32 s42, s40, 0x10000
	ds_read_b128 v[96:99], v142 offset:16384
	ds_read_b128 v[178:181], v142 offset:17408
	ds_read_b128 v[182:185], v142 offset:18432
	ds_read_b128 v[186:189], v142 offset:19456
	ds_read_b128 v[190:193], v142 offset:20480
	ds_read_b128 v[194:197], v142 offset:21504
	ds_read_b128 v[198:201], v142 offset:22528
	ds_read_b128 v[204:207], v142 offset:23552
	global_load_lds_dwordx4 v[248:249], off
	v_lshl_add_u64 v[250:251], s[40:41], 0, v[134:135]
	s_mov_b32 m0, s62
	s_addc_u32 s43, s41, 0
	global_load_lds_dwordx4 v[250:251], off
	v_lshl_add_u64 v[208:209], s[42:43], 0, v[130:131]
	s_mov_b32 m0, s63
	v_lshl_add_u64 v[252:253], s[44:45], 0, v[128:129]
	global_load_lds_dwordx4 v[208:209], off
	v_lshl_add_u64 v[208:209], s[42:43], 0, v[134:135]
	s_mov_b32 m0, s76
	v_lshl_add_u64 v[202:203], s[44:45], 0, v[132:133]
	global_load_lds_dwordx4 v[208:209], off
	s_mov_b32 m0, s23
	s_nop 0
	global_load_lds_dwordx4 v[252:253], off
	s_mov_b32 m0, s53
	s_nop 0
	global_load_lds_dwordx4 v[202:203], off
	s_waitcnt vmcnt(8)
	s_waitcnt lgkmcnt(0)
	s_barrier
	s_waitcnt lgkmcnt(0)
	v_mfma_f32_16x16x32_bf16 v[0:3], v[104:107], v[198:201], v[0:3]
	v_mfma_f32_16x16x32_bf16 v[4:7], v[112:115], v[198:201], v[4:7]
	v_mfma_f32_16x16x32_bf16 v[146:149], v[104:107], v[96:99], v[146:149]
	v_mfma_f32_16x16x32_bf16 v[150:153], v[112:115], v[96:99], v[150:153]
	v_mfma_f32_16x16x32_bf16 v[154:157], v[104:107], v[182:185], v[154:157]
	v_mfma_f32_16x16x32_bf16 v[158:161], v[112:115], v[182:185], v[158:161]
	v_mfma_f32_16x16x32_bf16 v[162:165], v[104:107], v[190:193], v[162:165]
	v_mfma_f32_16x16x32_bf16 v[166:169], v[112:115], v[190:193], v[166:169]
	v_mfma_f32_16x16x32_bf16 v[0:3], v[108:111], v[204:207], v[0:3]
	v_mfma_f32_16x16x32_bf16 v[4:7], v[116:119], v[204:207], v[4:7]
	v_mfma_f32_16x16x32_bf16 v[146:149], v[108:111], v[178:181], v[146:149]
	v_mfma_f32_16x16x32_bf16 v[150:153], v[116:119], v[178:181], v[150:153]
	v_mfma_f32_16x16x32_bf16 v[154:157], v[108:111], v[186:189], v[154:157]
	v_mfma_f32_16x16x32_bf16 v[158:161], v[116:119], v[186:189], v[158:161]
	v_mfma_f32_16x16x32_bf16 v[162:165], v[108:111], v[194:197], v[162:165]
	v_mfma_f32_16x16x32_bf16 v[166:169], v[116:119], v[194:197], v[166:169]
	v_mfma_f32_16x16x32_bf16 v[8:11], v[120:123], v[96:99], v[8:11]
	v_mfma_f32_16x16x32_bf16 v[12:15], v[170:173], v[96:99], v[12:15]
	v_mfma_f32_16x16x32_bf16 v[24:27], v[120:123], v[182:185], v[24:27]
	v_mfma_f32_16x16x32_bf16 v[8:11], v[124:127], v[178:181], v[8:11]
	v_mfma_f32_16x16x32_bf16 v[12:15], v[174:177], v[178:181], v[12:15]
	v_mfma_f32_16x16x32_bf16 v[178:181], v[124:127], v[186:189], v[24:27]
	v_mfma_f32_16x16x32_bf16 v[24:27], v[170:173], v[182:185], v[28:31]
	v_mfma_f32_16x16x32_bf16 v[182:185], v[174:177], v[186:189], v[24:27]
	v_mfma_f32_16x16x32_bf16 v[24:27], v[120:123], v[190:193], v[60:63]
	v_mfma_f32_16x16x32_bf16 v[186:189], v[124:127], v[194:197], v[24:27]
	v_mfma_f32_16x16x32_bf16 v[24:27], v[170:173], v[190:193], v[100:103]
	v_mfma_f32_16x16x32_bf16 v[16:19], v[120:123], v[198:201], v[16:19]
	v_mfma_f32_16x16x32_bf16 v[190:193], v[174:177], v[194:197], v[24:27]
	v_mfma_f32_16x16x32_bf16 v[194:197], v[124:127], v[204:207], v[16:19]
	v_mfma_f32_16x16x32_bf16 v[16:19], v[170:173], v[198:201], v[20:23]
	v_mfma_f32_16x16x32_bf16 v[170:173], v[174:177], v[204:207], v[16:19]
	s_barrier
	ds_read_b128 v[60:63], v143
	ds_read_b128 v[174:177], v143 offset:1024
	ds_read_b128 v[198:201], v143 offset:2048
	ds_read_b128 v[204:207], v143 offset:3072
	ds_read_b128 v[208:211], v144
	ds_read_b128 v[216:219], v144 offset:1024
	ds_read_b128 v[220:223], v144 offset:2048
	ds_read_b128 v[224:227], v144 offset:3072
	s_add_u32 s42, s44, 0x10000
	s_addc_u32 s43, s45, 0
	s_mov_b32 m0, s54
	v_lshl_add_u64 v[24:25], s[42:43], 0, v[128:129]
	ds_read_b128 v[16:19], v142 offset:32768
	ds_read_b128 v[20:23], v142 offset:33792
	ds_read_b128 v[108:111], v142 offset:34816
	ds_read_b128 v[228:231], v142 offset:35840
	ds_read_b128 v[232:235], v142 offset:36864
	ds_read_b128 v[236:239], v142 offset:37888
	ds_read_b128 v[240:243], v142 offset:38912
	ds_read_b128 v[244:247], v142 offset:39936
	global_load_lds_dwordx4 v[24:25], off
	v_lshl_add_u64 v[24:25], s[42:43], 0, v[132:133]
	s_mov_b32 m0, s55
	s_nop 0
	global_load_lds_dwordx4 v[24:25], off
	s_waitcnt vmcnt(8)
	s_waitcnt lgkmcnt(0)
	s_barrier
; #define PG8_STAGE(bufoff, gbase, voff) do { _Pragma("unroll") for (int _i = 0; _i < 2; ++_i) \
;         __builtin_amdgcn_global_load_lds((const unsigned*)((const char*)(gbase) + (voff)[_i]), (LAS unsigned*)(lds + (bufoff) + ldsw + _i * 8192), 16, 0, 0); } while (0)
; #define PG8_LDA(dst, b, h) do { _Pragma("unroll") for (int m = 0; m < 4; ++m) _Pragma("unroll") for (int k = 0; k < 2; ++k) dst[m][k] = *(const LAS bf16x8*)(lds + PG8_SA(b, h) + aoff + m * 2048 + k * 1024); } while (0)
; #define PG8_MMA(ai, bj, At, Bt) do { __builtin_amdgcn_s_setprio(1); _Pragma("unroll") for (int m = 0; m < 4; ++m) _Pragma("unroll") for (int n = 0; n < 2; ++n) _Pragma("unroll") for (int k = 0; k < 2; ++k) \
;         acc[ai][bj][m][n] = __builtin_amdgcn_mfma_f32_16x16x32_bf16(Bt[n][k], At[m][k], acc[ai][bj][m][n], 0, 0, 0); __builtin_amdgcn_s_setprio(0); } while (0)
; #define PG8_WAIT_V(n) asm volatile("s_waitcnt vmcnt(" #n ")" ::: "memory")
; #define PG8_WAIT_L(n) asm volatile("s_waitcnt lgkmcnt(" #n ")" ::: "memory")
; #define PG8_BAR __builtin_amdgcn_s_barrier()
; #define PG8_SCHED __builtin_amdgcn_sched_barrier(0)
; template <class Epi, class Sched, bool ALIGN_EPI = true>
; __device__ __forceinline__ void gemm_phase(LAS unsigned char* lds, const Gemm g, const Sched& S, const Epi& E) {
;     ...
;             PG8_WAIT_V(8); PG8_WAIT_L(0); PG8_BAR; PG8_MMA(0, 0, At, B0); PG8_MMA(0, 1, At, B1); PG8_BAR; PG8_SCHED;
;             PG8_LDA(At, 1, 1); PG8_STAGE(PG8_SB(1, 0), b3, voffB); PG8_STAGE(PG8_SB(1, 1), b3 + hstep, voffB); PG8_STAGE(PG8_SA(1, 0), a3, voffA);
;             PG8_WAIT_V(8); PG8_WAIT_L(0); PG8_BAR; PG8_MMA(1, 0, At, B0); PG8_MMA(1, 1, At, B1); PG8_BAR; PG8_SCHED;
;         }
;         if constexpr (ALIGN_EPI) { if (wr == 0) PG8_BAR; }
	s_waitcnt lgkmcnt(0)
	v_mfma_f32_16x16x32_bf16 v[24:27], v[60:63], v[16:19], v[64:67]
	v_mfma_f32_16x16x32_bf16 v[112:115], v[174:177], v[20:23], v[24:27]
	v_mfma_f32_16x16x32_bf16 v[24:27], v[198:201], v[16:19], v[68:71]
	v_mfma_f32_16x16x32_bf16 v[116:119], v[204:207], v[20:23], v[24:27]
	v_mfma_f32_16x16x32_bf16 v[24:27], v[60:63], v[108:111], v[72:75]
	v_mfma_f32_16x16x32_bf16 v[96:99], v[174:177], v[228:231], v[24:27]
	v_mfma_f32_16x16x32_bf16 v[24:27], v[198:201], v[108:111], v[76:79]
	v_mfma_f32_16x16x32_bf16 v[100:103], v[204:207], v[228:231], v[24:27]
	v_mfma_f32_16x16x32_bf16 v[24:27], v[60:63], v[232:235], v[80:83]
	v_mfma_f32_16x16x32_bf16 v[64:67], v[174:177], v[236:239], v[24:27]
	v_mfma_f32_16x16x32_bf16 v[24:27], v[198:201], v[232:235], v[84:87]
	v_mfma_f32_16x16x32_bf16 v[68:71], v[204:207], v[236:239], v[24:27]
	v_mfma_f32_16x16x32_bf16 v[24:27], v[60:63], v[240:243], v[88:91]
	v_mfma_f32_16x16x32_bf16 v[28:31], v[198:201], v[240:243], v[92:95]
	v_mfma_f32_16x16x32_bf16 v[24:27], v[174:177], v[244:247], v[24:27]
	v_mfma_f32_16x16x32_bf16 v[28:31], v[204:207], v[244:247], v[28:31]
	v_mfma_f32_16x16x32_bf16 v[72:75], v[208:211], v[16:19], v[212:215]
	v_mfma_f32_16x16x32_bf16 v[16:19], v[220:223], v[16:19], v[32:35]
	v_mfma_f32_16x16x32_bf16 v[124:127], v[224:227], v[20:23], v[16:19]
	v_mfma_f32_16x16x32_bf16 v[16:19], v[208:211], v[108:111], v[36:39]
	v_mfma_f32_16x16x32_bf16 v[104:107], v[216:219], v[228:231], v[16:19]
	v_mfma_f32_16x16x32_bf16 v[16:19], v[220:223], v[108:111], v[40:43]
	v_mfma_f32_16x16x32_bf16 v[108:111], v[224:227], v[228:231], v[16:19]
	v_mfma_f32_16x16x32_bf16 v[16:19], v[208:211], v[232:235], v[44:47]
	v_mfma_f32_16x16x32_bf16 v[120:123], v[216:219], v[20:23], v[72:75]
	v_mfma_f32_16x16x32_bf16 v[72:75], v[216:219], v[236:239], v[16:19]
	v_mfma_f32_16x16x32_bf16 v[16:19], v[220:223], v[232:235], v[48:51]
	v_mfma_f32_16x16x32_bf16 v[76:79], v[224:227], v[236:239], v[16:19]
	v_mfma_f32_16x16x32_bf16 v[16:19], v[208:211], v[240:243], v[52:55]
	v_mfma_f32_16x16x32_bf16 v[40:43], v[216:219], v[244:247], v[16:19]
	v_mfma_f32_16x16x32_bf16 v[16:19], v[220:223], v[240:243], v[56:59]
	v_mfma_f32_16x16x32_bf16 v[44:47], v[224:227], v[244:247], v[16:19]
	s_barrier
	s_mov_b32 m0, s77
	s_nop 3
	v_lshl_add_u64 v[16:17], v[248:249], 0, s[12:13]
	s_add_u32 s40, s40, 0x10080
	ds_read_b128 v[32:35], v142 offset:49152
	ds_read_b128 v[36:39], v142 offset:50176
	ds_read_b128 v[212:215], v142 offset:51200
	ds_read_b128 v[228:231], v142 offset:52224
	ds_read_b128 v[232:235], v142 offset:53248
	ds_read_b128 v[236:239], v142 offset:54272
	ds_read_b128 v[240:243], v142 offset:55296
	ds_read_b128 v[244:247], v142 offset:56320
	global_load_lds_dwordx4 v[16:17], off
	v_lshl_add_u64 v[16:17], v[250:251], 0, s[12:13]
	s_mov_b32 m0, s78
	s_addc_u32 s41, s41, 0
	global_load_lds_dwordx4 v[16:17], off
	v_lshl_add_u64 v[16:17], s[40:41], 0, v[130:131]
	s_mov_b32 m0, s79
	s_nop 0
	global_load_lds_dwordx4 v[16:17], off
	v_lshl_add_u64 v[16:17], s[40:41], 0, v[134:135]
	s_mov_b32 m0, s80
	s_nop 0
	global_load_lds_dwordx4 v[16:17], off
	v_lshl_add_u64 v[16:17], v[252:253], 0, s[12:13]
	s_mov_b32 m0, s57
	s_nop 0
	global_load_lds_dwordx4 v[16:17], off
	v_lshl_add_u64 v[16:17], v[202:203], 0, s[12:13]
	s_mov_b32 m0, s58
	s_nop 0
	global_load_lds_dwordx4 v[16:17], off
	s_waitcnt vmcnt(8)
	s_waitcnt lgkmcnt(0)
	s_barrier
	s_waitcnt lgkmcnt(0)
	v_mfma_f32_16x16x32_bf16 v[16:19], v[60:63], v[32:35], v[146:149]
	v_mfma_f32_16x16x32_bf16 v[80:83], v[174:177], v[36:39], v[16:19]
	v_mfma_f32_16x16x32_bf16 v[16:19], v[198:201], v[32:35], v[150:153]
	v_mfma_f32_16x16x32_bf16 v[84:87], v[204:207], v[36:39], v[16:19]
	v_mfma_f32_16x16x32_bf16 v[16:19], v[60:63], v[212:215], v[154:157]
	v_mfma_f32_16x16x32_bf16 v[48:51], v[174:177], v[228:231], v[16:19]
	v_mfma_f32_16x16x32_bf16 v[16:19], v[198:201], v[212:215], v[158:161]
	v_mfma_f32_16x16x32_bf16 v[52:55], v[204:207], v[228:231], v[16:19]
	v_mfma_f32_16x16x32_bf16 v[16:19], v[60:63], v[232:235], v[162:165]
	v_mfma_f32_16x16x32_bf16 v[20:23], v[198:201], v[232:235], v[166:169]
	v_mfma_f32_16x16x32_bf16 v[0:3], v[60:63], v[240:243], v[0:3]
	v_mfma_f32_16x16x32_bf16 v[4:7], v[198:201], v[240:243], v[4:7]
	v_mfma_f32_16x16x32_bf16 v[16:19], v[174:177], v[236:239], v[16:19]
	v_mfma_f32_16x16x32_bf16 v[20:23], v[204:207], v[236:239], v[20:23]
	v_mfma_f32_16x16x32_bf16 v[0:3], v[174:177], v[244:247], v[0:3]
	v_mfma_f32_16x16x32_bf16 v[4:7], v[204:207], v[244:247], v[4:7]
	v_mfma_f32_16x16x32_bf16 v[8:11], v[208:211], v[32:35], v[8:11]
	v_mfma_f32_16x16x32_bf16 v[88:91], v[216:219], v[36:39], v[8:11]
	v_mfma_f32_16x16x32_bf16 v[8:11], v[220:223], v[32:35], v[12:15]
	v_mfma_f32_16x16x32_bf16 v[92:95], v[224:227], v[36:39], v[8:11]
	v_mfma_f32_16x16x32_bf16 v[8:11], v[208:211], v[212:215], v[178:181]
	v_mfma_f32_16x16x32_bf16 v[56:59], v[216:219], v[228:231], v[8:11]
	v_mfma_f32_16x16x32_bf16 v[8:11], v[220:223], v[212:215], v[182:185]
	v_mfma_f32_16x16x32_bf16 v[60:63], v[224:227], v[228:231], v[8:11]
	v_mfma_f32_16x16x32_bf16 v[8:11], v[208:211], v[232:235], v[186:189]
	v_mfma_f32_16x16x32_bf16 v[32:35], v[216:219], v[236:239], v[8:11]
	v_mfma_f32_16x16x32_bf16 v[8:11], v[220:223], v[232:235], v[190:193]
	v_mfma_f32_16x16x32_bf16 v[36:39], v[224:227], v[236:239], v[8:11]
	v_mfma_f32_16x16x32_bf16 v[8:11], v[208:211], v[240:243], v[194:197]
	v_mfma_f32_16x16x32_bf16 v[12:15], v[220:223], v[240:243], v[170:173]
	v_mfma_f32_16x16x32_bf16 v[8:11], v[216:219], v[244:247], v[8:11]
	v_mfma_f32_16x16x32_bf16 v[12:15], v[224:227], v[244:247], v[12:15]
	s_barrier
	s_and_b64 vcc, exec, s[4:5]
	s_cbranch_vccnz .LBB0_669
	s_barrier

; #define PG8_STAGE(bufoff, gbase, voff) do { _Pragma("unroll") for (int _i = 0; _i < 2; ++_i) \
;         __builtin_amdgcn_global_load_lds((const unsigned*)((const char*)(gbase) + (voff)[_i]), (LAS unsigned*)(lds + (bufoff) + ldsw + _i * 8192), 16, 0, 0); } while (0)
; #define PG8_LDA(dst, b, h) do { _Pragma("unroll") for (int m = 0; m < 4; ++m) _Pragma("unroll") for (int k = 0; k < 2; ++k) dst[m][k] = *(const LAS bf16x8*)(lds + PG8_SA(b, h) + aoff + m * 2048 + k * 1024); } while (0)
; #define PG8_LDB(dst, b, h) do { _Pragma("unroll") for (int n = 0; n < 2; ++n) _Pragma("unroll") for (int k = 0; k < 2; ++k) dst[n][k] = *(const LAS bf16x8*)(lds + PG8_SB(b, h) + boff + n * 2048 + k * 1024); } while (0)
; #define PG8_MMA(ai, bj, At, Bt) do { __builtin_amdgcn_s_setprio(1); _Pragma("unroll") for (int m = 0; m < 4; ++m) _Pragma("unroll") for (int n = 0; n < 2; ++n) _Pragma("unroll") for (int k = 0; k < 2; ++k) \
;         acc[ai][bj][m][n] = __builtin_amdgcn_mfma_f32_16x16x32_bf16(Bt[n][k], At[m][k], acc[ai][bj][m][n], 0, 0, 0); __builtin_amdgcn_s_setprio(0); } while (0)
; #define PG8_WAIT_V(n) asm volatile("s_waitcnt vmcnt(" #n ")" ::: "memory")
; #define PG8_WAIT_L(n) asm volatile("s_waitcnt lgkmcnt(" #n ")" ::: "memory")
; #define PG8_BAR __builtin_amdgcn_s_barrier()
; #define PG8_SCHED __builtin_amdgcn_sched_barrier(0)
; template <class Epi, class Sched, bool ALIGN_EPI = true>
; __device__ __forceinline__ void gemm_phase(LAS unsigned char* lds, const Gemm g, const Sched& S, const Epi& E) {
;     ...
;         for (int t = 0; t < nt; t += 2) {
;             const bool last = (t == nt - 2);
;             const char* a1 = cA + (size_t)(t + 1) * kstep;
;             const char* a2 = last ? nA : cA + (size_t)(t + 2) * kstep; const char* b2 = last ? nB : cB + (size_t)(t + 2) * kstep;
;             const char* a3 = a2 + kstep; const char* b3 = b2 + kstep;
;             PG8_LDB(B0, 0, 0); PG8_LDB(B1, 0, 1); PG8_SCHED; PG8_LDA(At, 0, 0); PG8_STAGE(PG8_SA(1, 1), a1 + hstep, voffA);
;             PG8_WAIT_V(8); PG8_WAIT_L(0); PG8_BAR; PG8_MMA(0, 0, At, B0); PG8_MMA(0, 1, At, B1); PG8_BAR; PG8_SCHED;
;             PG8_LDA(At, 0, 1); PG8_STAGE(PG8_SB(0, 0), b2, voffB); PG8_STAGE(PG8_SB(0, 1), b2 + hstep, voffB); PG8_STAGE(PG8_SA(0, 0), a2, voffA);
;             PG8_WAIT_V(8); PG8_WAIT_L(0); PG8_BAR; PG8_MMA(1, 0, At, B0); PG8_MMA(1, 1, At, B1); PG8_BAR; PG8_SCHED;
.LBB0_746:
	ds_read_b128 v[128:131], v187
	ds_read_b128 v[132:135], v187 offset:1024
	ds_read_b128 v[136:139], v187 offset:2048
	ds_read_b128 v[140:143], v187 offset:3072
	ds_read_b128 v[144:147], v188
	ds_read_b128 v[148:151], v188 offset:1024
	ds_read_b128 v[164:167], v188 offset:2048
	ds_read_b128 v[168:171], v188 offset:3072
	s_add_u32 s24, s22, 0x100
	s_addc_u32 s25, s23, 0
	s_cmpk_eq_i32 s56, 0x54
	s_cselect_b32 s29, s19, s25
	s_cselect_b32 s28, s18, s24
	s_cselect_b32 s27, s21, s55
	s_cselect_b32 s26, s20, s54
	s_mov_b32 m0, s43
	v_lshl_add_u64 v[180:181], s[22:23], 0, v[160:161]
	ds_read_b128 v[172:175], v189
	ds_read_b128 v[176:179], v189 offset:1024
	ds_read_b128 v[192:195], v189 offset:2048
	ds_read_b128 v[196:199], v189 offset:3072
	ds_read_b128 v[204:207], v189 offset:4096
	ds_read_b128 v[208:211], v189 offset:5120
	ds_read_b128 v[212:215], v189 offset:6144
	ds_read_b128 v[216:219], v189 offset:7168
	global_load_lds_dwordx4 v[180:181], off
	v_lshl_add_u64 v[180:181], s[22:23], 0, v[162:163]
	s_mov_b32 m0, s44
	s_nop 0
	global_load_lds_dwordx4 v[180:181], off
	s_waitcnt vmcnt(8)
	s_waitcnt lgkmcnt(0)
	s_barrier
	s_waitcnt lgkmcnt(0)
	v_mfma_f32_16x16x32_bf16 v[124:127], v[128:131], v[172:175], v[124:127]
	v_mfma_f32_16x16x32_bf16 v[120:123], v[136:139], v[172:175], v[120:123]
	v_mfma_f32_16x16x32_bf16 v[108:111], v[128:131], v[192:195], v[108:111]
	v_mfma_f32_16x16x32_bf16 v[104:107], v[136:139], v[192:195], v[104:107]
	v_mfma_f32_16x16x32_bf16 v[92:95], v[128:131], v[204:207], v[92:95]
	v_mfma_f32_16x16x32_bf16 v[88:91], v[136:139], v[204:207], v[88:91]
	v_mfma_f32_16x16x32_bf16 v[76:79], v[128:131], v[212:215], v[76:79]
	v_mfma_f32_16x16x32_bf16 v[72:75], v[136:139], v[212:215], v[72:75]
	v_mfma_f32_16x16x32_bf16 v[124:127], v[132:135], v[176:179], v[124:127]
	v_mfma_f32_16x16x32_bf16 v[120:123], v[140:143], v[176:179], v[120:123]
	v_mfma_f32_16x16x32_bf16 v[108:111], v[132:135], v[196:199], v[108:111]
	v_mfma_f32_16x16x32_bf16 v[104:107], v[140:143], v[196:199], v[104:107]
	v_mfma_f32_16x16x32_bf16 v[92:95], v[132:135], v[208:211], v[92:95]
	v_mfma_f32_16x16x32_bf16 v[88:91], v[140:143], v[208:211], v[88:91]
	v_mfma_f32_16x16x32_bf16 v[76:79], v[132:135], v[216:219], v[76:79]
	v_mfma_f32_16x16x32_bf16 v[72:75], v[140:143], v[216:219], v[72:75]
	v_mfma_f32_16x16x32_bf16 v[116:119], v[144:147], v[172:175], v[116:119]
	v_mfma_f32_16x16x32_bf16 v[112:115], v[164:167], v[172:175], v[112:115]
	v_mfma_f32_16x16x32_bf16 v[100:103], v[144:147], v[192:195], v[100:103]
	v_mfma_f32_16x16x32_bf16 v[96:99], v[164:167], v[192:195], v[96:99]
	v_mfma_f32_16x16x32_bf16 v[84:87], v[144:147], v[204:207], v[84:87]
	v_mfma_f32_16x16x32_bf16 v[80:83], v[164:167], v[204:207], v[80:83]
	v_mfma_f32_16x16x32_bf16 v[68:71], v[144:147], v[212:215], v[68:71]
	v_mfma_f32_16x16x32_bf16 v[64:67], v[164:167], v[212:215], v[64:67]
	v_mfma_f32_16x16x32_bf16 v[116:119], v[148:151], v[176:179], v[116:119]
	v_mfma_f32_16x16x32_bf16 v[112:115], v[168:171], v[176:179], v[112:115]
	v_mfma_f32_16x16x32_bf16 v[100:103], v[148:151], v[196:199], v[100:103]
	v_mfma_f32_16x16x32_bf16 v[96:99], v[168:171], v[196:199], v[96:99]
	v_mfma_f32_16x16x32_bf16 v[84:87], v[148:151], v[208:211], v[84:87]
	v_mfma_f32_16x16x32_bf16 v[80:83], v[168:171], v[208:211], v[80:83]
	v_mfma_f32_16x16x32_bf16 v[68:71], v[148:151], v[216:219], v[68:71]
	v_mfma_f32_16x16x32_bf16 v[64:67], v[168:171], v[216:219], v[64:67]
	s_barrier
	s_mov_b32 m0, s45
	v_lshl_add_u64 v[180:181], s[26:27], 0, v[154:155]
	s_add_u32 s22, s26, 0x160000
	ds_read_b128 v[172:175], v189 offset:16384
	ds_read_b128 v[176:179], v189 offset:17408
	ds_read_b128 v[192:195], v189 offset:18432
	ds_read_b128 v[196:199], v189 offset:19456
	ds_read_b128 v[204:207], v189 offset:20480
	ds_read_b128 v[208:211], v189 offset:21504
	ds_read_b128 v[212:215], v189 offset:22528
	ds_read_b128 v[216:219], v189 offset:23552
	global_load_lds_dwordx4 v[180:181], off
	v_lshl_add_u64 v[200:201], s[26:27], 0, v[158:159]
	s_mov_b32 m0, s48
	s_addc_u32 s23, s27, 0
	global_load_lds_dwordx4 v[200:201], off
	v_lshl_add_u64 v[202:203], s[22:23], 0, v[154:155]
	s_mov_b32 m0, s49
	v_lshl_add_u64 v[220:221], s[28:29], 0, v[156:157]
	global_load_lds_dwordx4 v[202:203], off
	v_lshl_add_u64 v[202:203], s[22:23], 0, v[158:159]
	s_add_i32 m0, s49, 0x2000
	s_nop 0
	global_load_lds_dwordx4 v[202:203], off
	v_lshl_add_u64 v[202:203], s[28:29], 0, v[152:153]
	s_mov_b32 m0, s36
	s_nop 0
	global_load_lds_dwordx4 v[202:203], off
	s_mov_b32 m0, s37
	s_nop 0
	global_load_lds_dwordx4 v[220:221], off
	s_waitcnt vmcnt(8)
	s_waitcnt lgkmcnt(0)
	s_barrier
; #define PG8_STAGE(bufoff, gbase, voff) do { _Pragma("unroll") for (int _i = 0; _i < 2; ++_i) \
;         __builtin_amdgcn_global_load_lds((const unsigned*)((const char*)(gbase) + (voff)[_i]), (LAS unsigned*)(lds + (bufoff) + ldsw + _i * 8192), 16, 0, 0); } while (0)
; #define PG8_LDA(dst, b, h) do { _Pragma("unroll") for (int m = 0; m < 4; ++m) _Pragma("unroll") for (int k = 0; k < 2; ++k) dst[m][k] = *(const LAS bf16x8*)(lds + PG8_SA(b, h) + aoff + m * 2048 + k * 1024); } while (0)
; #define PG8_LDB(dst, b, h) do { _Pragma("unroll") for (int n = 0; n < 2; ++n) _Pragma("unroll") for (int k = 0; k < 2; ++k) dst[n][k] = *(const LAS bf16x8*)(lds + PG8_SB(b, h) + boff + n * 2048 + k * 1024); } while (0)
; #define PG8_MMA(ai, bj, At, Bt) do { __builtin_amdgcn_s_setprio(1); _Pragma("unroll") for (int m = 0; m < 4; ++m) _Pragma("unroll") for (int n = 0; n < 2; ++n) _Pragma("unroll") for (int k = 0; k < 2; ++k) \
;         acc[ai][bj][m][n] = __builtin_amdgcn_mfma_f32_16x16x32_bf16(Bt[n][k], At[m][k], acc[ai][bj][m][n], 0, 0, 0); __builtin_amdgcn_s_setprio(0); } while (0)
; #define PG8_WAIT_V(n) asm volatile("s_waitcnt vmcnt(" #n ")" ::: "memory")
; #define PG8_WAIT_L(n) asm volatile("s_waitcnt lgkmcnt(" #n ")" ::: "memory")
; #define PG8_BAR __builtin_amdgcn_s_barrier()
; #define PG8_SCHED __builtin_amdgcn_sched_barrier(0)
; template <class Epi, class Sched, bool ALIGN_EPI = true>
; __device__ __forceinline__ void gemm_phase(LAS unsigned char* lds, const Gemm g, const Sched& S, const Epi& E) {
;     ...
;             PG8_WAIT_V(8); PG8_WAIT_L(0); PG8_BAR; PG8_MMA(1, 0, At, B0); PG8_MMA(1, 1, At, B1); PG8_BAR; PG8_SCHED;
;             PG8_LDB(B0, 1, 0); PG8_LDB(B1, 1, 1); PG8_SCHED; PG8_LDA(At, 1, 0); PG8_STAGE(PG8_SA(0, 1), a2 + hstep, voffA);
;             PG8_WAIT_V(8); PG8_WAIT_L(0); PG8_BAR; PG8_MMA(0, 0, At, B0); PG8_MMA(0, 1, At, B1); PG8_BAR; PG8_SCHED;
	s_waitcnt lgkmcnt(0)
	v_mfma_f32_16x16x32_bf16 v[60:63], v[128:131], v[172:175], v[60:63]
	v_mfma_f32_16x16x32_bf16 v[56:59], v[136:139], v[172:175], v[56:59]
	v_mfma_f32_16x16x32_bf16 v[44:47], v[128:131], v[192:195], v[44:47]
	v_mfma_f32_16x16x32_bf16 v[40:43], v[136:139], v[192:195], v[40:43]
	v_mfma_f32_16x16x32_bf16 v[28:31], v[128:131], v[204:207], v[28:31]
	v_mfma_f32_16x16x32_bf16 v[24:27], v[136:139], v[204:207], v[24:27]
	v_mfma_f32_16x16x32_bf16 v[12:15], v[128:131], v[212:215], v[12:15]
	v_mfma_f32_16x16x32_bf16 v[8:11], v[136:139], v[212:215], v[8:11]
	v_mfma_f32_16x16x32_bf16 v[60:63], v[132:135], v[176:179], v[60:63]
	v_mfma_f32_16x16x32_bf16 v[56:59], v[140:143], v[176:179], v[56:59]
	v_mfma_f32_16x16x32_bf16 v[44:47], v[132:135], v[196:199], v[44:47]
	v_mfma_f32_16x16x32_bf16 v[40:43], v[140:143], v[196:199], v[40:43]
	v_mfma_f32_16x16x32_bf16 v[28:31], v[132:135], v[208:211], v[28:31]
	v_mfma_f32_16x16x32_bf16 v[24:27], v[140:143], v[208:211], v[24:27]
	v_mfma_f32_16x16x32_bf16 v[12:15], v[132:135], v[216:219], v[12:15]
	v_mfma_f32_16x16x32_bf16 v[8:11], v[140:143], v[216:219], v[8:11]
	v_mfma_f32_16x16x32_bf16 v[52:55], v[144:147], v[172:175], v[52:55]
	v_mfma_f32_16x16x32_bf16 v[48:51], v[164:167], v[172:175], v[48:51]
	v_mfma_f32_16x16x32_bf16 v[36:39], v[144:147], v[192:195], v[36:39]
	v_mfma_f32_16x16x32_bf16 v[32:35], v[164:167], v[192:195], v[32:35]
	v_mfma_f32_16x16x32_bf16 v[20:23], v[144:147], v[204:207], v[20:23]
	v_mfma_f32_16x16x32_bf16 v[16:19], v[164:167], v[204:207], v[16:19]
	v_mfma_f32_16x16x32_bf16 v[4:7], v[144:147], v[212:215], v[4:7]
	v_mfma_f32_16x16x32_bf16 v[0:3], v[164:167], v[212:215], v[0:3]
	v_mfma_f32_16x16x32_bf16 v[52:55], v[148:151], v[176:179], v[52:55]
	v_mfma_f32_16x16x32_bf16 v[48:51], v[168:171], v[176:179], v[48:51]
	v_mfma_f32_16x16x32_bf16 v[36:39], v[148:151], v[196:199], v[36:39]
	v_mfma_f32_16x16x32_bf16 v[32:35], v[168:171], v[196:199], v[32:35]
	v_mfma_f32_16x16x32_bf16 v[20:23], v[148:151], v[208:211], v[20:23]
	v_mfma_f32_16x16x32_bf16 v[16:19], v[168:171], v[208:211], v[16:19]
	v_mfma_f32_16x16x32_bf16 v[4:7], v[148:151], v[216:219], v[4:7]
	v_mfma_f32_16x16x32_bf16 v[0:3], v[168:171], v[216:219], v[0:3]
	s_barrier
	s_add_i32 s46, 0, 0x18000
	s_add_i32 s47, 0, 0x1c000
	v_add_u32_e32 v140, s46, v185
	v_add_u32_e32 v168, s47, v185
	ds_read_b128 v[128:131], v140
	ds_read_b128 v[132:135], v140 offset:1024
	ds_read_b128 v[136:139], v140 offset:2048
	ds_read_b128 v[140:143], v140 offset:3072
	ds_read_b128 v[144:147], v168
	ds_read_b128 v[148:151], v168 offset:1024
	ds_read_b128 v[164:167], v168 offset:2048
	ds_read_b128 v[168:171], v168 offset:3072
	s_add_u32 s22, s28, 0x160000
	s_addc_u32 s23, s29, 0
	s_mov_b32 m0, s38
	v_lshl_add_u64 v[222:223], s[22:23], 0, v[152:153]
	ds_read_b128 v[172:175], v189 offset:32768
	ds_read_b128 v[176:179], v189 offset:33792
	ds_read_b128 v[192:195], v189 offset:34816
	ds_read_b128 v[196:199], v189 offset:35840
	ds_read_b128 v[204:207], v189 offset:36864
	ds_read_b128 v[208:211], v189 offset:37888
	ds_read_b128 v[212:215], v189 offset:38912
	ds_read_b128 v[216:219], v189 offset:39936
	global_load_lds_dwordx4 v[222:223], off
	v_lshl_add_u64 v[222:223], s[22:23], 0, v[156:157]
	s_mov_b32 m0, s39
	s_nop 0
	global_load_lds_dwordx4 v[222:223], off
	s_waitcnt vmcnt(8)
	s_waitcnt lgkmcnt(0)
	s_barrier
	s_waitcnt lgkmcnt(0)
	v_mfma_f32_16x16x32_bf16 v[124:127], v[128:131], v[172:175], v[124:127]
	v_mfma_f32_16x16x32_bf16 v[120:123], v[136:139], v[172:175], v[120:123]
	v_mfma_f32_16x16x32_bf16 v[108:111], v[128:131], v[192:195], v[108:111]
	v_mfma_f32_16x16x32_bf16 v[104:107], v[136:139], v[192:195], v[104:107]
	v_mfma_f32_16x16x32_bf16 v[92:95], v[128:131], v[204:207], v[92:95]
	v_mfma_f32_16x16x32_bf16 v[88:91], v[136:139], v[204:207], v[88:91]
	v_mfma_f32_16x16x32_bf16 v[76:79], v[128:131], v[212:215], v[76:79]
	v_mfma_f32_16x16x32_bf16 v[72:75], v[136:139], v[212:215], v[72:75]
	v_mfma_f32_16x16x32_bf16 v[124:127], v[132:135], v[176:179], v[124:127]
	v_mfma_f32_16x16x32_bf16 v[120:123], v[140:143], v[176:179], v[120:123]
	v_mfma_f32_16x16x32_bf16 v[108:111], v[132:135], v[196:199], v[108:111]
	v_mfma_f32_16x16x32_bf16 v[104:107], v[140:143], v[196:199], v[104:107]
	v_mfma_f32_16x16x32_bf16 v[92:95], v[132:135], v[208:211], v[92:95]
	v_mfma_f32_16x16x32_bf16 v[88:91], v[140:143], v[208:211], v[88:91]
	v_mfma_f32_16x16x32_bf16 v[76:79], v[132:135], v[216:219], v[76:79]
	v_mfma_f32_16x16x32_bf16 v[72:75], v[140:143], v[216:219], v[72:75]
	v_mfma_f32_16x16x32_bf16 v[116:119], v[144:147], v[172:175], v[116:119]
	v_mfma_f32_16x16x32_bf16 v[112:115], v[164:167], v[172:175], v[112:115]
	v_mfma_f32_16x16x32_bf16 v[100:103], v[144:147], v[192:195], v[100:103]
	v_mfma_f32_16x16x32_bf16 v[96:99], v[164:167], v[192:195], v[96:99]
	v_mfma_f32_16x16x32_bf16 v[84:87], v[144:147], v[204:207], v[84:87]
	v_mfma_f32_16x16x32_bf16 v[80:83], v[164:167], v[204:207], v[80:83]
	v_mfma_f32_16x16x32_bf16 v[68:71], v[144:147], v[212:215], v[68:71]
	v_mfma_f32_16x16x32_bf16 v[64:67], v[164:167], v[212:215], v[64:67]
	v_mfma_f32_16x16x32_bf16 v[116:119], v[148:151], v[176:179], v[116:119]
	v_mfma_f32_16x16x32_bf16 v[112:115], v[168:171], v[176:179], v[112:115]
	v_mfma_f32_16x16x32_bf16 v[100:103], v[148:151], v[196:199], v[100:103]
	v_mfma_f32_16x16x32_bf16 v[96:99], v[168:171], v[196:199], v[96:99]
	v_mfma_f32_16x16x32_bf16 v[84:87], v[148:151], v[208:211], v[84:87]
	v_mfma_f32_16x16x32_bf16 v[80:83], v[168:171], v[208:211], v[80:83]
	v_mfma_f32_16x16x32_bf16 v[68:71], v[148:151], v[216:219], v[68:71]
	v_mfma_f32_16x16x32_bf16 v[64:67], v[168:171], v[216:219], v[64:67]
	s_barrier
; #define PG8_STAGE(bufoff, gbase, voff) do { _Pragma("unroll") for (int _i = 0; _i < 2; ++_i) \
;         __builtin_amdgcn_global_load_lds((const unsigned*)((const char*)(gbase) + (voff)[_i]), (LAS unsigned*)(lds + (bufoff) + ldsw + _i * 8192), 16, 0, 0); } while (0)
; #define PG8_LDA(dst, b, h) do { _Pragma("unroll") for (int m = 0; m < 4; ++m) _Pragma("unroll") for (int k = 0; k < 2; ++k) dst[m][k] = *(const LAS bf16x8*)(lds + PG8_SA(b, h) + aoff + m * 2048 + k * 1024); } while (0)
; #define PG8_MMA(ai, bj, At, Bt) do { __builtin_amdgcn_s_setprio(1); _Pragma("unroll") for (int m = 0; m < 4; ++m) _Pragma("unroll") for (int n = 0; n < 2; ++n) _Pragma("unroll") for (int k = 0; k < 2; ++k) \
;         acc[ai][bj][m][n] = __builtin_amdgcn_mfma_f32_16x16x32_bf16(Bt[n][k], At[m][k], acc[ai][bj][m][n], 0, 0, 0); __builtin_amdgcn_s_setprio(0); } while (0)
; #define PG8_WAIT_V(n) asm volatile("s_waitcnt vmcnt(" #n ")" ::: "memory")
; #define PG8_WAIT_L(n) asm volatile("s_waitcnt lgkmcnt(" #n ")" ::: "memory")
; #define PG8_BAR __builtin_amdgcn_s_barrier()
; #define PG8_SCHED __builtin_amdgcn_sched_barrier(0)
; template <class Epi, class Sched, bool ALIGN_EPI = true>
; __device__ __forceinline__ void gemm_phase(LAS unsigned char* lds, const Gemm g, const Sched& S, const Epi& E) {
;     ...
;             PG8_LDA(At, 1, 1); PG8_STAGE(PG8_SB(1, 0), b3, voffB); PG8_STAGE(PG8_SB(1, 1), b3 + hstep, voffB); PG8_STAGE(PG8_SA(1, 0), a3, voffA);
;             PG8_WAIT_V(8); PG8_WAIT_L(0); PG8_BAR; PG8_MMA(1, 0, At, B0); PG8_MMA(1, 1, At, B1); PG8_BAR; PG8_SCHED;
;         }
;         if constexpr (ALIGN_EPI) { if (wr == 0) PG8_BAR; }
	s_add_i32 s22, s46, s35
	v_lshl_add_u64 v[180:181], v[180:181], 0, s[14:15]
	s_mov_b32 m0, s22
	ds_read_b128 v[172:175], v189 offset:49152
	ds_read_b128 v[176:179], v189 offset:50176
	ds_read_b128 v[192:195], v189 offset:51200
	ds_read_b128 v[196:199], v189 offset:52224
	ds_read_b128 v[204:207], v189 offset:53248
	ds_read_b128 v[208:211], v189 offset:54272
	ds_read_b128 v[212:215], v189 offset:55296
	ds_read_b128 v[216:219], v189 offset:56320
	global_load_lds_dwordx4 v[180:181], off
	s_add_i32 m0, s22, 0x2000
	s_add_u32 s22, s26, 0x160080
	v_lshl_add_u64 v[180:181], v[200:201], 0, s[14:15]
	s_addc_u32 s23, s27, 0
	s_add_i32 s26, s47, s35
	global_load_lds_dwordx4 v[180:181], off
	v_lshl_add_u64 v[180:181], s[22:23], 0, v[154:155]
	s_mov_b32 m0, s26
	s_nop 0
	global_load_lds_dwordx4 v[180:181], off
	v_lshl_add_u64 v[180:181], s[22:23], 0, v[158:159]
	s_add_i32 m0, s26, 0x2000
	s_nop 0
	global_load_lds_dwordx4 v[180:181], off
	v_lshl_add_u64 v[180:181], v[202:203], 0, s[14:15]
	s_mov_b32 m0, s40
	s_nop 0
	global_load_lds_dwordx4 v[180:181], off
	v_lshl_add_u64 v[180:181], v[220:221], 0, s[14:15]
	s_mov_b32 m0, s41
	s_nop 0
	global_load_lds_dwordx4 v[180:181], off
	s_waitcnt vmcnt(8)
	s_waitcnt lgkmcnt(0)
	s_barrier
	s_waitcnt lgkmcnt(0)
	v_mfma_f32_16x16x32_bf16 v[60:63], v[128:131], v[172:175], v[60:63]
	v_mfma_f32_16x16x32_bf16 v[56:59], v[136:139], v[172:175], v[56:59]
	v_mfma_f32_16x16x32_bf16 v[44:47], v[128:131], v[192:195], v[44:47]
	v_mfma_f32_16x16x32_bf16 v[40:43], v[136:139], v[192:195], v[40:43]
	v_mfma_f32_16x16x32_bf16 v[28:31], v[128:131], v[204:207], v[28:31]
	v_mfma_f32_16x16x32_bf16 v[24:27], v[136:139], v[204:207], v[24:27]
	v_mfma_f32_16x16x32_bf16 v[12:15], v[128:131], v[212:215], v[12:15]
	v_mfma_f32_16x16x32_bf16 v[8:11], v[136:139], v[212:215], v[8:11]
	v_mfma_f32_16x16x32_bf16 v[60:63], v[132:135], v[176:179], v[60:63]
	v_mfma_f32_16x16x32_bf16 v[56:59], v[140:143], v[176:179], v[56:59]
	v_mfma_f32_16x16x32_bf16 v[44:47], v[132:135], v[196:199], v[44:47]
	v_mfma_f32_16x16x32_bf16 v[40:43], v[140:143], v[196:199], v[40:43]
	v_mfma_f32_16x16x32_bf16 v[28:31], v[132:135], v[208:211], v[28:31]
	v_mfma_f32_16x16x32_bf16 v[24:27], v[140:143], v[208:211], v[24:27]
	v_mfma_f32_16x16x32_bf16 v[12:15], v[132:135], v[216:219], v[12:15]
	v_mfma_f32_16x16x32_bf16 v[8:11], v[140:143], v[216:219], v[8:11]
	v_mfma_f32_16x16x32_bf16 v[52:55], v[144:147], v[172:175], v[52:55]
	v_mfma_f32_16x16x32_bf16 v[48:51], v[164:167], v[172:175], v[48:51]
	v_mfma_f32_16x16x32_bf16 v[36:39], v[144:147], v[192:195], v[36:39]
	v_mfma_f32_16x16x32_bf16 v[32:35], v[164:167], v[192:195], v[32:35]
	v_mfma_f32_16x16x32_bf16 v[20:23], v[144:147], v[204:207], v[20:23]
	v_mfma_f32_16x16x32_bf16 v[16:19], v[164:167], v[204:207], v[16:19]
	v_mfma_f32_16x16x32_bf16 v[4:7], v[144:147], v[212:215], v[4:7]
	v_mfma_f32_16x16x32_bf16 v[0:3], v[164:167], v[212:215], v[0:3]
	v_mfma_f32_16x16x32_bf16 v[52:55], v[148:151], v[176:179], v[52:55]
	v_mfma_f32_16x16x32_bf16 v[48:51], v[168:171], v[176:179], v[48:51]
	v_mfma_f32_16x16x32_bf16 v[36:39], v[148:151], v[196:199], v[36:39]
	v_mfma_f32_16x16x32_bf16 v[32:35], v[168:171], v[196:199], v[32:35]
	v_mfma_f32_16x16x32_bf16 v[20:23], v[148:151], v[208:211], v[20:23]
	v_mfma_f32_16x16x32_bf16 v[16:19], v[168:171], v[208:211], v[16:19]
	v_mfma_f32_16x16x32_bf16 v[4:7], v[148:151], v[216:219], v[4:7]
	v_mfma_f32_16x16x32_bf16 v[0:3], v[168:171], v[216:219], v[0:3]
	s_barrier
	s_add_i32 s56, s56, 2
	s_add_u32 s54, s54, 0x100
	s_addc_u32 s55, s55, 0
	s_cmpk_gt_u32 s56, 0x55
	s_mov_b64 s[22:23], s[24:25]
	s_cbranch_scc0 .LBB0_746
	s_and_b64 vcc, exec, s[16:17]
	s_cbranch_vccz .LBB0_749
	s_barrier

; #define PG8_STAGE(bufoff, gbase, voff) do { _Pragma("unroll") for (int _i = 0; _i < 2; ++_i) \
;         __builtin_amdgcn_global_load_lds((const unsigned*)((const char*)(gbase) + (voff)[_i]), (LAS unsigned*)(lds + (bufoff) + ldsw + _i * 8192), 16, 0, 0); } while (0)
; #define PG8_LDA(dst, b, h) do { _Pragma("unroll") for (int m = 0; m < 4; ++m) _Pragma("unroll") for (int k = 0; k < 2; ++k) dst[m][k] = *(const LAS bf16x8*)(lds + PG8_SA(b, h) + aoff + m * 2048 + k * 1024); } while (0)
; #define PG8_LDB(dst, b, h) do { _Pragma("unroll") for (int n = 0; n < 2; ++n) _Pragma("unroll") for (int k = 0; k < 2; ++k) dst[n][k] = *(const LAS bf16x8*)(lds + PG8_SB(b, h) + boff + n * 2048 + k * 1024); } while (0)
; #define PG8_MMA(ai, bj, At, Bt) do { __builtin_amdgcn_s_setprio(1); _Pragma("unroll") for (int m = 0; m < 4; ++m) _Pragma("unroll") for (int n = 0; n < 2; ++n) _Pragma("unroll") for (int k = 0; k < 2; ++k) \
;         acc[ai][bj][m][n] = __builtin_amdgcn_mfma_f32_16x16x32_bf16(Bt[n][k], At[m][k], acc[ai][bj][m][n], 0, 0, 0); __builtin_amdgcn_s_setprio(0); } while (0)
; #define PG8_WAIT_V(n) asm volatile("s_waitcnt vmcnt(" #n ")" ::: "memory")
; #define PG8_WAIT_L(n) asm volatile("s_waitcnt lgkmcnt(" #n ")" ::: "memory")
; #define PG8_BAR __builtin_amdgcn_s_barrier()
; #define PG8_SCHED __builtin_amdgcn_sched_barrier(0)
; template <class Epi, class Sched, bool ALIGN_EPI = true>
; __device__ __forceinline__ void gemm_phase(LAS unsigned char* lds, const Gemm g, const Sched& S, const Epi& E) {
;     ...
;         for (int t = 0; t < nt; t += 2) {
;             const bool last = (t == nt - 2);
;             const char* a1 = cA + (size_t)(t + 1) * kstep;
;             const char* a2 = last ? nA : cA + (size_t)(t + 2) * kstep; const char* b2 = last ? nB : cB + (size_t)(t + 2) * kstep;
;             const char* a3 = a2 + kstep; const char* b3 = b2 + kstep;
;             PG8_LDB(B0, 0, 0); PG8_LDB(B1, 0, 1); PG8_SCHED; PG8_LDA(At, 0, 0); PG8_STAGE(PG8_SA(1, 1), a1 + hstep, voffA);
;             PG8_WAIT_V(8); PG8_WAIT_L(0); PG8_BAR; PG8_MMA(0, 0, At, B0); PG8_MMA(0, 1, At, B1); PG8_BAR; PG8_SCHED;
;             PG8_LDA(At, 0, 1); PG8_STAGE(PG8_SB(0, 0), b2, voffB); PG8_STAGE(PG8_SB(0, 1), b2 + hstep, voffB); PG8_STAGE(PG8_SA(0, 0), a2, voffA);
.LBB0_837:
	ds_read_b128 v[120:123], v208
	ds_read_b128 v[124:127], v208 offset:1024
	ds_read_b128 v[132:135], v208 offset:2048
	ds_read_b128 v[136:139], v208 offset:3072
	ds_read_b128 v[144:147], v209
	ds_read_b128 v[148:151], v209 offset:1024
	ds_read_b128 v[152:155], v209 offset:2048
	ds_read_b128 v[156:159], v209 offset:3072
	s_add_u32 s36, s34, 0xfff80080
	s_addc_u32 s37, s35, -1
	s_cmp_eq_u32 s60, 28
	s_cselect_b32 s39, s55, s37
	s_cselect_b32 s38, s56, s36
	s_cselect_b32 s37, s11, s59
	s_cselect_b32 s36, s57, s58
	v_lshl_add_u64 v[200:201], s[34:35], 0, v[184:185]
	s_add_i32 m0, s42, 0xc000
	ds_read_b128 v[160:163], v210
	ds_read_b128 v[164:167], v210 offset:1024
	ds_read_b128 v[168:171], v210 offset:2048
	ds_read_b128 v[172:175], v210 offset:3072
	ds_read_b128 v[188:191], v210 offset:4096
	ds_read_b128 v[192:195], v210 offset:5120
	ds_read_b128 v[196:199], v210 offset:6144
	ds_read_b128 v[214:217], v210 offset:7168
	global_load_lds_dwordx4 v[200:201], off
	v_lshl_add_u64 v[200:201], s[34:35], 0, v[186:187]
	s_add_i32 m0, s42, 0xe000
	s_nop 0
	global_load_lds_dwordx4 v[200:201], off
	s_waitcnt vmcnt(8)
	s_waitcnt lgkmcnt(0)
	s_barrier
	s_waitcnt lgkmcnt(0)
	v_mfma_f32_16x16x32_bf16 v[140:143], v[120:123], v[160:163], v[140:143]
	v_mfma_f32_16x16x32_bf16 v[128:131], v[132:135], v[160:163], v[128:131]
	v_mfma_f32_16x16x32_bf16 v[108:111], v[120:123], v[168:171], v[108:111]
	v_mfma_f32_16x16x32_bf16 v[104:107], v[132:135], v[168:171], v[104:107]
	v_mfma_f32_16x16x32_bf16 v[92:95], v[120:123], v[188:191], v[92:95]
	v_mfma_f32_16x16x32_bf16 v[88:91], v[132:135], v[188:191], v[88:91]
	v_mfma_f32_16x16x32_bf16 v[76:79], v[120:123], v[196:199], v[76:79]
	v_mfma_f32_16x16x32_bf16 v[72:75], v[132:135], v[196:199], v[72:75]
	v_mfma_f32_16x16x32_bf16 v[140:143], v[124:127], v[164:167], v[140:143]
	v_mfma_f32_16x16x32_bf16 v[128:131], v[136:139], v[164:167], v[128:131]
	v_mfma_f32_16x16x32_bf16 v[108:111], v[124:127], v[172:175], v[108:111]
	v_mfma_f32_16x16x32_bf16 v[104:107], v[136:139], v[172:175], v[104:107]
	v_mfma_f32_16x16x32_bf16 v[92:95], v[124:127], v[192:195], v[92:95]
	v_mfma_f32_16x16x32_bf16 v[88:91], v[136:139], v[192:195], v[88:91]
	v_mfma_f32_16x16x32_bf16 v[76:79], v[124:127], v[214:217], v[76:79]
	v_mfma_f32_16x16x32_bf16 v[72:75], v[136:139], v[214:217], v[72:75]
	v_mfma_f32_16x16x32_bf16 v[116:119], v[144:147], v[160:163], v[116:119]
	v_mfma_f32_16x16x32_bf16 v[112:115], v[152:155], v[160:163], v[112:115]
	v_mfma_f32_16x16x32_bf16 v[100:103], v[144:147], v[168:171], v[100:103]
	v_mfma_f32_16x16x32_bf16 v[96:99], v[152:155], v[168:171], v[96:99]
	v_mfma_f32_16x16x32_bf16 v[84:87], v[144:147], v[188:191], v[84:87]
	v_mfma_f32_16x16x32_bf16 v[80:83], v[152:155], v[188:191], v[80:83]
	v_mfma_f32_16x16x32_bf16 v[68:71], v[144:147], v[196:199], v[68:71]
	v_mfma_f32_16x16x32_bf16 v[64:67], v[152:155], v[196:199], v[64:67]
	v_mfma_f32_16x16x32_bf16 v[116:119], v[148:151], v[164:167], v[116:119]
	v_mfma_f32_16x16x32_bf16 v[112:115], v[156:159], v[164:167], v[112:115]
	v_mfma_f32_16x16x32_bf16 v[100:103], v[148:151], v[172:175], v[100:103]
	v_mfma_f32_16x16x32_bf16 v[96:99], v[156:159], v[172:175], v[96:99]
	v_mfma_f32_16x16x32_bf16 v[84:87], v[148:151], v[192:195], v[84:87]
	v_mfma_f32_16x16x32_bf16 v[80:83], v[156:159], v[192:195], v[80:83]
	v_mfma_f32_16x16x32_bf16 v[68:71], v[148:151], v[214:217], v[68:71]
	v_mfma_f32_16x16x32_bf16 v[64:67], v[156:159], v[214:217], v[64:67]
	s_barrier
	s_add_i32 s46, s50, s41
	v_lshl_add_u64 v[200:201], s[36:37], 0, v[178:179]
	s_mov_b32 m0, s46
	ds_read_b128 v[160:163], v210 offset:16384
	ds_read_b128 v[164:167], v210 offset:17408
	ds_read_b128 v[168:171], v210 offset:18432
	ds_read_b128 v[172:175], v210 offset:19456
	ds_read_b128 v[188:191], v210 offset:20480
	ds_read_b128 v[192:195], v210 offset:21504
	ds_read_b128 v[196:199], v210 offset:22528
	ds_read_b128 v[214:217], v210 offset:23552
	global_load_lds_dwordx4 v[200:201], off
	s_add_i32 m0, s46, 0x2000
	s_add_u32 s46, s36, 0x80000
	v_lshl_add_u64 v[218:219], s[36:37], 0, v[182:183]
	s_addc_u32 s47, s37, 0
	s_add_i32 s61, s51, s41
	global_load_lds_dwordx4 v[218:219], off
	v_lshl_add_u64 v[220:221], s[46:47], 0, v[178:179]
	s_mov_b32 m0, s61
	v_lshl_add_u64 v[222:223], s[38:39], 0, v[180:181]
	global_load_lds_dwordx4 v[220:221], off
	v_lshl_add_u64 v[220:221], s[46:47], 0, v[182:183]
	s_add_i32 m0, s61, 0x2000
	s_nop 0
	global_load_lds_dwordx4 v[220:221], off
	v_lshl_add_u64 v[220:221], s[38:39], 0, v[176:177]
	s_mov_b32 m0, s42
	s_nop 0
	global_load_lds_dwordx4 v[220:221], off
	s_mov_b32 m0, s43
	s_nop 0
	global_load_lds_dwordx4 v[222:223], off
	s_waitcnt vmcnt(8)
	s_waitcnt lgkmcnt(0)
	s_barrier
; #define PG8_STAGE(bufoff, gbase, voff) do { _Pragma("unroll") for (int _i = 0; _i < 2; ++_i) \
;         __builtin_amdgcn_global_load_lds((const unsigned*)((const char*)(gbase) + (voff)[_i]), (LAS unsigned*)(lds + (bufoff) + ldsw + _i * 8192), 16, 0, 0); } while (0)
; #define PG8_LDA(dst, b, h) do { _Pragma("unroll") for (int m = 0; m < 4; ++m) _Pragma("unroll") for (int k = 0; k < 2; ++k) dst[m][k] = *(const LAS bf16x8*)(lds + PG8_SA(b, h) + aoff + m * 2048 + k * 1024); } while (0)
; #define PG8_LDB(dst, b, h) do { _Pragma("unroll") for (int n = 0; n < 2; ++n) _Pragma("unroll") for (int k = 0; k < 2; ++k) dst[n][k] = *(const LAS bf16x8*)(lds + PG8_SB(b, h) + boff + n * 2048 + k * 1024); } while (0)
; #define PG8_MMA(ai, bj, At, Bt) do { __builtin_amdgcn_s_setprio(1); _Pragma("unroll") for (int m = 0; m < 4; ++m) _Pragma("unroll") for (int n = 0; n < 2; ++n) _Pragma("unroll") for (int k = 0; k < 2; ++k) \
;         acc[ai][bj][m][n] = __builtin_amdgcn_mfma_f32_16x16x32_bf16(Bt[n][k], At[m][k], acc[ai][bj][m][n], 0, 0, 0); __builtin_amdgcn_s_setprio(0); } while (0)
; #define PG8_WAIT_V(n) asm volatile("s_waitcnt vmcnt(" #n ")" ::: "memory")
; #define PG8_WAIT_L(n) asm volatile("s_waitcnt lgkmcnt(" #n ")" ::: "memory")
; #define PG8_BAR __builtin_amdgcn_s_barrier()
; #define PG8_SCHED __builtin_amdgcn_sched_barrier(0)
; template <class Epi, class Sched, bool ALIGN_EPI = true>
; __device__ __forceinline__ void gemm_phase(LAS unsigned char* lds, const Gemm g, const Sched& S, const Epi& E) {
;     ...
;             PG8_WAIT_V(8); PG8_WAIT_L(0); PG8_BAR; PG8_MMA(1, 0, At, B0); PG8_MMA(1, 1, At, B1); PG8_BAR; PG8_SCHED;
;             PG8_LDB(B0, 1, 0); PG8_LDB(B1, 1, 1); PG8_SCHED; PG8_LDA(At, 1, 0); PG8_STAGE(PG8_SA(0, 1), a2 + hstep, voffA);
;             PG8_WAIT_V(8); PG8_WAIT_L(0); PG8_BAR; PG8_MMA(0, 0, At, B0); PG8_MMA(0, 1, At, B1); PG8_BAR; PG8_SCHED;
	s_waitcnt lgkmcnt(0)
	v_mfma_f32_16x16x32_bf16 v[60:63], v[120:123], v[160:163], v[60:63]
	v_mfma_f32_16x16x32_bf16 v[56:59], v[132:135], v[160:163], v[56:59]
	v_mfma_f32_16x16x32_bf16 v[44:47], v[120:123], v[168:171], v[44:47]
	v_mfma_f32_16x16x32_bf16 v[40:43], v[132:135], v[168:171], v[40:43]
	v_mfma_f32_16x16x32_bf16 v[28:31], v[120:123], v[188:191], v[28:31]
	v_mfma_f32_16x16x32_bf16 v[24:27], v[132:135], v[188:191], v[24:27]
	v_mfma_f32_16x16x32_bf16 v[12:15], v[120:123], v[196:199], v[12:15]
	v_mfma_f32_16x16x32_bf16 v[8:11], v[132:135], v[196:199], v[8:11]
	v_mfma_f32_16x16x32_bf16 v[60:63], v[124:127], v[164:167], v[60:63]
	v_mfma_f32_16x16x32_bf16 v[56:59], v[136:139], v[164:167], v[56:59]
	v_mfma_f32_16x16x32_bf16 v[44:47], v[124:127], v[172:175], v[44:47]
	v_mfma_f32_16x16x32_bf16 v[40:43], v[136:139], v[172:175], v[40:43]
	v_mfma_f32_16x16x32_bf16 v[28:31], v[124:127], v[192:195], v[28:31]
	v_mfma_f32_16x16x32_bf16 v[24:27], v[136:139], v[192:195], v[24:27]
	v_mfma_f32_16x16x32_bf16 v[12:15], v[124:127], v[214:217], v[12:15]
	v_mfma_f32_16x16x32_bf16 v[8:11], v[136:139], v[214:217], v[8:11]
	v_mfma_f32_16x16x32_bf16 v[52:55], v[144:147], v[160:163], v[52:55]
	v_mfma_f32_16x16x32_bf16 v[48:51], v[152:155], v[160:163], v[48:51]
	v_mfma_f32_16x16x32_bf16 v[36:39], v[144:147], v[168:171], v[36:39]
	v_mfma_f32_16x16x32_bf16 v[32:35], v[152:155], v[168:171], v[32:35]
	v_mfma_f32_16x16x32_bf16 v[20:23], v[144:147], v[188:191], v[20:23]
	v_mfma_f32_16x16x32_bf16 v[16:19], v[152:155], v[188:191], v[16:19]
	v_mfma_f32_16x16x32_bf16 v[4:7], v[144:147], v[196:199], v[4:7]
	v_mfma_f32_16x16x32_bf16 v[0:3], v[152:155], v[196:199], v[0:3]
	v_mfma_f32_16x16x32_bf16 v[52:55], v[148:151], v[164:167], v[52:55]
	v_mfma_f32_16x16x32_bf16 v[48:51], v[156:159], v[164:167], v[48:51]
	v_mfma_f32_16x16x32_bf16 v[36:39], v[148:151], v[172:175], v[36:39]
	v_mfma_f32_16x16x32_bf16 v[32:35], v[156:159], v[172:175], v[32:35]
	v_mfma_f32_16x16x32_bf16 v[20:23], v[148:151], v[192:195], v[20:23]
	v_mfma_f32_16x16x32_bf16 v[16:19], v[156:159], v[192:195], v[16:19]
	v_mfma_f32_16x16x32_bf16 v[4:7], v[148:151], v[214:217], v[4:7]
	v_mfma_f32_16x16x32_bf16 v[0:3], v[156:159], v[214:217], v[0:3]
	s_barrier
	s_add_i32 s46, 0, 0x18000
	s_add_i32 s47, 0, 0x1c000
	v_add_u32_e32 v136, s46, v206
	v_add_u32_e32 v156, s47, v206
	ds_read_b128 v[120:123], v136
	ds_read_b128 v[124:127], v136 offset:1024
	ds_read_b128 v[132:135], v136 offset:2048
	ds_read_b128 v[136:139], v136 offset:3072
	ds_read_b128 v[144:147], v156
	ds_read_b128 v[148:151], v156 offset:1024
	ds_read_b128 v[152:155], v156 offset:2048
	ds_read_b128 v[156:159], v156 offset:3072
	s_add_u32 s38, s38, 0x80000
	s_addc_u32 s39, s39, 0
	s_mov_b32 m0, s44
	v_lshl_add_u64 v[224:225], s[38:39], 0, v[176:177]
	ds_read_b128 v[160:163], v210 offset:32768
	ds_read_b128 v[164:167], v210 offset:33792
	ds_read_b128 v[168:171], v210 offset:34816
	ds_read_b128 v[172:175], v210 offset:35840
	ds_read_b128 v[188:191], v210 offset:36864
	ds_read_b128 v[192:195], v210 offset:37888
	ds_read_b128 v[196:199], v210 offset:38912
	ds_read_b128 v[214:217], v210 offset:39936
	global_load_lds_dwordx4 v[224:225], off
	v_lshl_add_u64 v[224:225], s[38:39], 0, v[180:181]
	s_mov_b32 m0, s45
	s_nop 0
	global_load_lds_dwordx4 v[224:225], off
	s_waitcnt vmcnt(8)
	s_waitcnt lgkmcnt(0)
	s_barrier
	s_waitcnt lgkmcnt(0)
	v_mfma_f32_16x16x32_bf16 v[140:143], v[120:123], v[160:163], v[140:143]
	v_mfma_f32_16x16x32_bf16 v[128:131], v[132:135], v[160:163], v[128:131]
	v_mfma_f32_16x16x32_bf16 v[108:111], v[120:123], v[168:171], v[108:111]
	v_mfma_f32_16x16x32_bf16 v[104:107], v[132:135], v[168:171], v[104:107]
	v_mfma_f32_16x16x32_bf16 v[92:95], v[120:123], v[188:191], v[92:95]
	v_mfma_f32_16x16x32_bf16 v[88:91], v[132:135], v[188:191], v[88:91]
	v_mfma_f32_16x16x32_bf16 v[76:79], v[120:123], v[196:199], v[76:79]
	v_mfma_f32_16x16x32_bf16 v[72:75], v[132:135], v[196:199], v[72:75]
	v_mfma_f32_16x16x32_bf16 v[140:143], v[124:127], v[164:167], v[140:143]
	v_mfma_f32_16x16x32_bf16 v[128:131], v[136:139], v[164:167], v[128:131]
	v_mfma_f32_16x16x32_bf16 v[108:111], v[124:127], v[172:175], v[108:111]
	v_mfma_f32_16x16x32_bf16 v[104:107], v[136:139], v[172:175], v[104:107]
	v_mfma_f32_16x16x32_bf16 v[92:95], v[124:127], v[192:195], v[92:95]
	v_mfma_f32_16x16x32_bf16 v[88:91], v[136:139], v[192:195], v[88:91]
	v_mfma_f32_16x16x32_bf16 v[76:79], v[124:127], v[214:217], v[76:79]
	v_mfma_f32_16x16x32_bf16 v[72:75], v[136:139], v[214:217], v[72:75]
	v_mfma_f32_16x16x32_bf16 v[116:119], v[144:147], v[160:163], v[116:119]
	v_mfma_f32_16x16x32_bf16 v[112:115], v[152:155], v[160:163], v[112:115]
	v_mfma_f32_16x16x32_bf16 v[100:103], v[144:147], v[168:171], v[100:103]
	v_mfma_f32_16x16x32_bf16 v[96:99], v[152:155], v[168:171], v[96:99]
	v_mfma_f32_16x16x32_bf16 v[84:87], v[144:147], v[188:191], v[84:87]
	v_mfma_f32_16x16x32_bf16 v[80:83], v[152:155], v[188:191], v[80:83]
	v_mfma_f32_16x16x32_bf16 v[68:71], v[144:147], v[196:199], v[68:71]
	v_mfma_f32_16x16x32_bf16 v[64:67], v[152:155], v[196:199], v[64:67]
	v_mfma_f32_16x16x32_bf16 v[116:119], v[148:151], v[164:167], v[116:119]
	v_mfma_f32_16x16x32_bf16 v[112:115], v[156:159], v[164:167], v[112:115]
	v_mfma_f32_16x16x32_bf16 v[100:103], v[148:151], v[172:175], v[100:103]
	v_mfma_f32_16x16x32_bf16 v[96:99], v[156:159], v[172:175], v[96:99]
	v_mfma_f32_16x16x32_bf16 v[84:87], v[148:151], v[192:195], v[84:87]
	v_mfma_f32_16x16x32_bf16 v[80:83], v[156:159], v[192:195], v[80:83]
	v_mfma_f32_16x16x32_bf16 v[68:71], v[148:151], v[214:217], v[68:71]
	v_mfma_f32_16x16x32_bf16 v[64:67], v[156:159], v[214:217], v[64:67]
	s_barrier
; #define PG8_STAGE(bufoff, gbase, voff) do { _Pragma("unroll") for (int _i = 0; _i < 2; ++_i) \
;         __builtin_amdgcn_global_load_lds((const unsigned*)((const char*)(gbase) + (voff)[_i]), (LAS unsigned*)(lds + (bufoff) + ldsw + _i * 8192), 16, 0, 0); } while (0)
; #define PG8_LDA(dst, b, h) do { _Pragma("unroll") for (int m = 0; m < 4; ++m) _Pragma("unroll") for (int k = 0; k < 2; ++k) dst[m][k] = *(const LAS bf16x8*)(lds + PG8_SA(b, h) + aoff + m * 2048 + k * 1024); } while (0)
; #define PG8_MMA(ai, bj, At, Bt) do { __builtin_amdgcn_s_setprio(1); _Pragma("unroll") for (int m = 0; m < 4; ++m) _Pragma("unroll") for (int n = 0; n < 2; ++n) _Pragma("unroll") for (int k = 0; k < 2; ++k) \
;         acc[ai][bj][m][n] = __builtin_amdgcn_mfma_f32_16x16x32_bf16(Bt[n][k], At[m][k], acc[ai][bj][m][n], 0, 0, 0); __builtin_amdgcn_s_setprio(0); } while (0)
; #define PG8_WAIT_V(n) asm volatile("s_waitcnt vmcnt(" #n ")" ::: "memory")
; #define PG8_WAIT_L(n) asm volatile("s_waitcnt lgkmcnt(" #n ")" ::: "memory")
; #define PG8_BAR __builtin_amdgcn_s_barrier()
; #define PG8_SCHED __builtin_amdgcn_sched_barrier(0)
; template <class Epi, class Sched, bool ALIGN_EPI = true>
; __device__ __forceinline__ void gemm_phase(LAS unsigned char* lds, const Gemm g, const Sched& S, const Epi& E) {
;     ...
;             PG8_LDA(At, 1, 1); PG8_STAGE(PG8_SB(1, 0), b3, voffB); PG8_STAGE(PG8_SB(1, 1), b3 + hstep, voffB); PG8_STAGE(PG8_SA(1, 0), a3, voffA);
;             PG8_WAIT_V(8); PG8_WAIT_L(0); PG8_BAR; PG8_MMA(1, 0, At, B0); PG8_MMA(1, 1, At, B1); PG8_BAR; PG8_SCHED;
;         }
;         if constexpr (ALIGN_EPI) { if (wr == 0) PG8_BAR; }
	s_add_i32 s38, s46, s41
	v_lshl_add_u64 v[200:201], v[200:201], 0, s[26:27]
	s_mov_b32 m0, s38
	ds_read_b128 v[160:163], v210 offset:49152
	ds_read_b128 v[164:167], v210 offset:50176
	ds_read_b128 v[168:171], v210 offset:51200
	ds_read_b128 v[172:175], v210 offset:52224
	ds_read_b128 v[188:191], v210 offset:53248
	ds_read_b128 v[192:195], v210 offset:54272
	ds_read_b128 v[196:199], v210 offset:55296
	ds_read_b128 v[214:217], v210 offset:56320
	global_load_lds_dwordx4 v[200:201], off
	s_add_i32 m0, s38, 0x2000
	s_add_u32 s36, s36, 0x80080
	v_lshl_add_u64 v[200:201], v[218:219], 0, s[26:27]
	s_addc_u32 s37, s37, 0
	s_add_i32 s38, s47, s41
	global_load_lds_dwordx4 v[200:201], off
	v_lshl_add_u64 v[200:201], s[36:37], 0, v[178:179]
	s_mov_b32 m0, s38
	s_nop 0
	global_load_lds_dwordx4 v[200:201], off
	v_lshl_add_u64 v[200:201], s[36:37], 0, v[182:183]
	s_add_i32 m0, s38, 0x2000
	s_nop 0
	global_load_lds_dwordx4 v[200:201], off
	v_lshl_add_u64 v[200:201], v[220:221], 0, s[26:27]
	s_mov_b32 m0, s48
	s_nop 0
	global_load_lds_dwordx4 v[200:201], off
	v_lshl_add_u64 v[200:201], v[222:223], 0, s[26:27]
	s_mov_b32 m0, s49
	s_nop 0
	global_load_lds_dwordx4 v[200:201], off
	s_waitcnt vmcnt(8)
	s_waitcnt lgkmcnt(0)
	s_barrier
	s_waitcnt lgkmcnt(0)
	v_mfma_f32_16x16x32_bf16 v[60:63], v[120:123], v[160:163], v[60:63]
	v_mfma_f32_16x16x32_bf16 v[56:59], v[132:135], v[160:163], v[56:59]
	v_mfma_f32_16x16x32_bf16 v[44:47], v[120:123], v[168:171], v[44:47]
	v_mfma_f32_16x16x32_bf16 v[40:43], v[132:135], v[168:171], v[40:43]
	v_mfma_f32_16x16x32_bf16 v[28:31], v[120:123], v[188:191], v[28:31]
	v_mfma_f32_16x16x32_bf16 v[24:27], v[132:135], v[188:191], v[24:27]
	v_mfma_f32_16x16x32_bf16 v[12:15], v[120:123], v[196:199], v[12:15]
	v_mfma_f32_16x16x32_bf16 v[8:11], v[132:135], v[196:199], v[8:11]
	v_mfma_f32_16x16x32_bf16 v[60:63], v[124:127], v[164:167], v[60:63]
	v_mfma_f32_16x16x32_bf16 v[56:59], v[136:139], v[164:167], v[56:59]
	v_mfma_f32_16x16x32_bf16 v[44:47], v[124:127], v[172:175], v[44:47]
	v_mfma_f32_16x16x32_bf16 v[40:43], v[136:139], v[172:175], v[40:43]
	v_mfma_f32_16x16x32_bf16 v[28:31], v[124:127], v[192:195], v[28:31]
	v_mfma_f32_16x16x32_bf16 v[24:27], v[136:139], v[192:195], v[24:27]
	v_mfma_f32_16x16x32_bf16 v[12:15], v[124:127], v[214:217], v[12:15]
	v_mfma_f32_16x16x32_bf16 v[8:11], v[136:139], v[214:217], v[8:11]
	v_mfma_f32_16x16x32_bf16 v[52:55], v[144:147], v[160:163], v[52:55]
	v_mfma_f32_16x16x32_bf16 v[48:51], v[152:155], v[160:163], v[48:51]
	v_mfma_f32_16x16x32_bf16 v[36:39], v[144:147], v[168:171], v[36:39]
	v_mfma_f32_16x16x32_bf16 v[32:35], v[152:155], v[168:171], v[32:35]
	v_mfma_f32_16x16x32_bf16 v[20:23], v[144:147], v[188:191], v[20:23]
	v_mfma_f32_16x16x32_bf16 v[16:19], v[152:155], v[188:191], v[16:19]
	v_mfma_f32_16x16x32_bf16 v[4:7], v[144:147], v[196:199], v[4:7]
	v_mfma_f32_16x16x32_bf16 v[0:3], v[152:155], v[196:199], v[0:3]
	v_mfma_f32_16x16x32_bf16 v[52:55], v[148:151], v[164:167], v[52:55]
	v_mfma_f32_16x16x32_bf16 v[48:51], v[156:159], v[164:167], v[48:51]
	v_mfma_f32_16x16x32_bf16 v[36:39], v[148:151], v[172:175], v[36:39]
	v_mfma_f32_16x16x32_bf16 v[32:35], v[156:159], v[172:175], v[32:35]
	v_mfma_f32_16x16x32_bf16 v[20:23], v[148:151], v[192:195], v[20:23]
	v_mfma_f32_16x16x32_bf16 v[16:19], v[156:159], v[192:195], v[16:19]
	v_mfma_f32_16x16x32_bf16 v[4:7], v[148:151], v[214:217], v[4:7]
	v_mfma_f32_16x16x32_bf16 v[0:3], v[156:159], v[214:217], v[0:3]
	s_barrier
	s_add_i32 s60, s60, 2
	s_add_u32 s34, s34, 0x100
	s_addc_u32 s35, s35, 0
	s_add_u32 s58, s58, 0x100
	s_addc_u32 s59, s59, 0
	s_cmp_gt_u32 s60, 29
	s_cbranch_scc0 .LBB0_837
	s_and_b64 vcc, exec, s[28:29]
	s_cbranch_vccz .LBB0_840
	s_barrier
